# GEMM K-loops: wave priority raised to 2 only while issuing the 12 LDS-DMA loads of a K-step, back to 0 before the wait
# speedup vs baseline: 1.0128x; 1.0053x over previous
; template <int MI, bool SWAP, bool F8 = false>
; __device__ __forceinline__ void gemm_core(const bf16_t* __restrict__ A, int lda, const bf16_t* __restrict__ B, int ldb,
;                                           int K, char* smem, f32x4 (&acc)[MI][4]) {
;     ...
;   for (int kt = 0; kt < nk; ++kt) {
;     __syncthreads();
; #pragma unroll
;     for (int i = 0; i < MI; ++i) *(u32x4*)(smem + woff + i * 4096) = ra[i];
; #pragma unroll
;     for (int i = 0; i < 4; ++i) *(u32x4*)(smem + 32768 + woff + i * 4096) = rb[i];
;     __syncthreads();
;     if (kt + 1 < nk) {
; #pragma unroll
;       for (int i = 0; i < MI; ++i) ra[i] = *(const u32x4*)(ap + (size_t)(32 * i) * lda + (kt + 1) * 64);
; #pragma unroll
;       for (int i = 0; i < 4; ++i) rb[i] = *(const u32x4*)(bp + (size_t)(32 * i) * ldb + (kt + 1) * 64);
;     }
;     if (F8) {
;       const int c0 = (g ^ (li & 7)) << 4, c1 = ((4 + g) ^ (li & 7)) << 4;
;       i32x8 wf8[4];
; #pragma unroll
;       for (int j = 0; j < 4; ++j) {
;         const char* rp = smem + wrow + ((j & 1) * 16 + (j >> 1) * 64) * 128;
;         const u32x4 lo = *(const u32x4*)(rp + c0), hi = *(const u32x4*)(rp + c1);
;         wf8[j] = (i32x8){(int)lo.x, (int)lo.y, (int)lo.z, (int)lo.w, (int)hi.x, (int)hi.y, (int)hi.z, (int)hi.w};
;       }
; #pragma unroll
;       for (int i = 0; i < MI; ++i) {
;         const char* rp = smem + xrow + i * 2048;
;         const u32x4 lo = *(const u32x4*)(rp + c0), hi = *(const u32x4*)(rp + c1);
;         const i32x8 xf8 = {(int)lo.x, (int)lo.y, (int)lo.z, (int)lo.w, (int)hi.x, (int)hi.y, (int)hi.z, (int)hi.w};
; #pragma unroll
;         for (int j = 0; j < 4; ++j)
;           acc[i][j] = __builtin_amdgcn_mfma_scale_f32_16x16x128_f8f6f4(wf8[j], xf8, acc[i][j], 0, 0, 0, 0x77777777, 0, 0x7f7f7f7f);
;       }
;     } else {
; #pragma unroll
;     for (int kk = 0; kk < 2; ++kk) {
;       const int ch = ((kk * 4 + g) ^ (li & 7)) << 4;
;       bf16x8 xf[MI], wf[4];
; #pragma unroll
;       for (int j = 0; j < 4; ++j) wf[j] = *(const bf16x8*)(smem + wrow + ((j & 1) * 16 + (j >> 1) * 64) * 128 + ch);
; #pragma unroll
;       for (int i = 0; i < MI; ++i) xf[i] = *(const bf16x8*)(smem + xrow + i * 2048 + ch);
; #pragma unroll
;       for (int i = 0; i < MI; ++i)
; #pragma unroll
;         for (int j = 0; j < 4; ++j) {
.LBB0_120:
	s_barrier
	s_setprio 2
	s_mov_b32 m0, s62
	s_nop 0
	global_load_lds_dwordx4 v252, s[56:57]
	s_add_u32 m0, s62, 0x1000
	s_nop 0
	global_load_lds_dwordx4 v253, s[56:57]
	s_add_u32 s56, s56, 0x20000
	s_addc_u32 s57, s57, 0
	s_add_u32 m0, s62, 0x2000
	s_nop 0
	global_load_lds_dwordx4 v252, s[56:57]
	s_add_u32 m0, s62, 0x3000
	s_nop 0
	global_load_lds_dwordx4 v253, s[56:57]
	s_add_u32 s56, s56, 0x20000
	s_addc_u32 s57, s57, 0
	s_add_u32 m0, s62, 0x4000
	s_nop 0
	global_load_lds_dwordx4 v252, s[56:57]
	s_add_u32 m0, s62, 0x5000
	s_nop 0
	global_load_lds_dwordx4 v253, s[56:57]
	s_add_u32 s56, s56, 0x20000
	s_addc_u32 s57, s57, 0
	s_add_u32 m0, s62, 0x6000
	s_nop 0
	global_load_lds_dwordx4 v252, s[56:57]
	s_add_u32 m0, s62, 0x7000
	s_nop 0
	global_load_lds_dwordx4 v253, s[56:57]
	s_sub_u32 s56, s56, 0x60000
	s_subb_u32 s57, s57, 0
	s_add_u32 m0, s62, 0x8000
	s_nop 0
	global_load_lds_dwordx4 v252, s[58:59]
	s_add_u32 m0, s62, 0x9000
	s_nop 0
	global_load_lds_dwordx4 v253, s[58:59]
	s_add_u32 s58, s58, 0x20000
	s_addc_u32 s59, s59, 0
	s_add_u32 m0, s62, 0xa000
	s_nop 0
	global_load_lds_dwordx4 v252, s[58:59]
	s_add_u32 m0, s62, 0xb000
	s_nop 0
	global_load_lds_dwordx4 v253, s[58:59]
	s_sub_u32 s58, s58, 0x20000
	s_subb_u32 s59, s59, 0
	s_setprio 0
	v_add_u32_e32 v252, 0x80, v252
	v_add_u32_e32 v253, 0x80, v253
	s_waitcnt vmcnt(0)
	s_barrier
	ds_read_b128 v[148:151], v215 offset:32768
	ds_read_b128 v[152:155], v215 offset:34816
	ds_read_b128 v[156:159], v213
	ds_read_b128 v[160:163], v213 offset:2048
	ds_read_b128 v[164:167], v215 offset:40960
	ds_read_b128 v[168:171], v215 offset:43008
	s_waitcnt lgkmcnt(3)
	v_mfma_f32_16x16x32_bf16 v[140:143], v[148:151], v[156:159], v[140:143]
	v_mfma_f32_16x16x32_bf16 v[136:139], v[152:155], v[156:159], v[136:139]
	s_waitcnt lgkmcnt(1)
	v_mfma_f32_16x16x32_bf16 v[132:135], v[164:167], v[156:159], v[132:135]
	s_waitcnt lgkmcnt(0)
	v_mfma_f32_16x16x32_bf16 v[128:131], v[168:171], v[156:159], v[128:131]
	v_mfma_f32_16x16x32_bf16 v[124:127], v[148:151], v[160:163], v[124:127]
	v_mfma_f32_16x16x32_bf16 v[120:123], v[152:155], v[160:163], v[120:123]
	v_mfma_f32_16x16x32_bf16 v[116:119], v[164:167], v[160:163], v[116:119]
	v_mfma_f32_16x16x32_bf16 v[104:107], v[168:171], v[160:163], v[104:107]
	ds_read_b128 v[156:159], v213 offset:4096
	ds_read_b128 v[160:163], v213 offset:6144
	s_waitcnt lgkmcnt(1)
	v_mfma_f32_16x16x32_bf16 v[88:91], v[148:151], v[156:159], v[88:91]
	v_mfma_f32_16x16x32_bf16 v[84:87], v[152:155], v[156:159], v[84:87]
	v_mfma_f32_16x16x32_bf16 v[80:83], v[164:167], v[156:159], v[80:83]
	v_mfma_f32_16x16x32_bf16 v[76:79], v[168:171], v[156:159], v[76:79]
	s_waitcnt lgkmcnt(0)
	v_mfma_f32_16x16x32_bf16 v[72:75], v[148:151], v[160:163], v[72:75]
	v_mfma_f32_16x16x32_bf16 v[68:71], v[152:155], v[160:163], v[68:71]
	v_mfma_f32_16x16x32_bf16 v[64:67], v[164:167], v[160:163], v[64:67]
	v_mfma_f32_16x16x32_bf16 v[60:63], v[168:171], v[160:163], v[60:63]
	ds_read_b128 v[156:159], v213 offset:8192
	ds_read_b128 v[160:163], v213 offset:10240
	s_waitcnt lgkmcnt(1)
	v_mfma_f32_16x16x32_bf16 v[44:47], v[148:151], v[156:159], v[44:47]
	v_mfma_f32_16x16x32_bf16 v[40:43], v[152:155], v[156:159], v[40:43]
	v_mfma_f32_16x16x32_bf16 v[36:39], v[164:167], v[156:159], v[36:39]
	v_mfma_f32_16x16x32_bf16 v[32:35], v[168:171], v[156:159], v[32:35]
	s_waitcnt lgkmcnt(0)
	v_mfma_f32_16x16x32_bf16 v[28:31], v[148:151], v[160:163], v[28:31]
	v_mfma_f32_16x16x32_bf16 v[24:27], v[152:155], v[160:163], v[24:27]
	v_mfma_f32_16x16x32_bf16 v[20:23], v[164:167], v[160:163], v[20:23]
	v_mfma_f32_16x16x32_bf16 v[52:55], v[168:171], v[160:163], v[52:55]
	ds_read_b128 v[156:159], v213 offset:12288
	ds_read_b128 v[160:163], v213 offset:14336
	ds_read_b128 v[172:175], v206 offset:32768
	ds_read_b128 v[180:183], v206 offset:34816
	s_waitcnt lgkmcnt(3)
	v_mfma_f32_16x16x32_bf16 v[48:51], v[148:151], v[156:159], v[48:51]
	v_mfma_f32_16x16x32_bf16 v[56:59], v[152:155], v[156:159], v[56:59]
	s_waitcnt lgkmcnt(2)
	v_mfma_f32_16x16x32_bf16 v[100:103], v[148:151], v[160:163], v[100:103]
	v_mfma_f32_16x16x32_bf16 v[96:99], v[152:155], v[160:163], v[96:99]
	ds_read_b128 v[148:151], v0
	ds_read_b128 v[152:155], v0 offset:2048
	ds_read_b128 v[192:195], v206 offset:40960
	ds_read_b128 v[196:199], v206 offset:43008
	s_waitcnt lgkmcnt(3)
	v_mfma_f32_16x16x32_bf16 v[140:143], v[172:175], v[148:151], v[140:143]
	v_mfma_f32_16x16x32_bf16 v[136:139], v[180:183], v[148:151], v[136:139]
	s_waitcnt lgkmcnt(1)
	v_mfma_f32_16x16x32_bf16 v[132:135], v[192:195], v[148:151], v[132:135]
	s_waitcnt lgkmcnt(0)
	v_mfma_f32_16x16x32_bf16 v[128:131], v[196:199], v[148:151], v[128:131]
	v_mfma_f32_16x16x32_bf16 v[124:127], v[172:175], v[152:155], v[124:127]
	v_mfma_f32_16x16x32_bf16 v[120:123], v[180:183], v[152:155], v[120:123]
	v_mfma_f32_16x16x32_bf16 v[116:119], v[192:195], v[152:155], v[116:119]
	v_mfma_f32_16x16x32_bf16 v[104:107], v[196:199], v[152:155], v[104:107]
	ds_read_b128 v[148:151], v0 offset:4096
	ds_read_b128 v[152:155], v0 offset:6144
	v_mfma_f32_16x16x32_bf16 v[112:115], v[164:167], v[156:159], v[112:115]
	v_mfma_f32_16x16x32_bf16 v[92:95], v[164:167], v[160:163], v[92:95]
	v_mfma_f32_16x16x32_bf16 v[108:111], v[168:171], v[156:159], v[108:111]
	v_mfma_f32_16x16x32_bf16 v[144:147], v[168:171], v[160:163], v[144:147]
	s_waitcnt lgkmcnt(0)
; template <int MI, bool SWAP, bool F8 = false>
; __device__ __forceinline__ void gemm_core(const bf16_t* __restrict__ A, int lda, const bf16_t* __restrict__ B, int ldb,
;                                           int K, char* smem, f32x4 (&acc)[MI][4]) {
;     ...
;   for (int kt = 0; kt < nk; ++kt) {
;     __syncthreads();
; #pragma unroll
;     for (int i = 0; i < MI; ++i) *(u32x4*)(smem + woff + i * 4096) = ra[i];
; #pragma unroll
;     for (int i = 0; i < 4; ++i) *(u32x4*)(smem + 32768 + woff + i * 4096) = rb[i];
;     __syncthreads();
;     if (kt + 1 < nk) {
; #pragma unroll
;       for (int i = 0; i < MI; ++i) ra[i] = *(const u32x4*)(ap + (size_t)(32 * i) * lda + (kt + 1) * 64);
; #pragma unroll
;       for (int i = 0; i < 4; ++i) rb[i] = *(const u32x4*)(bp + (size_t)(32 * i) * ldb + (kt + 1) * 64);
;     }
;     if (F8) {
;       const int c0 = (g ^ (li & 7)) << 4, c1 = ((4 + g) ^ (li & 7)) << 4;
;       i32x8 wf8[4];
; #pragma unroll
;       for (int j = 0; j < 4; ++j) {
;         const char* rp = smem + wrow + ((j & 1) * 16 + (j >> 1) * 64) * 128;
;         const u32x4 lo = *(const u32x4*)(rp + c0), hi = *(const u32x4*)(rp + c1);
;         wf8[j] = (i32x8){(int)lo.x, (int)lo.y, (int)lo.z, (int)lo.w, (int)hi.x, (int)hi.y, (int)hi.z, (int)hi.w};
;       }
; #pragma unroll
;       for (int i = 0; i < MI; ++i) {
;         const char* rp = smem + xrow + i * 2048;
;         const u32x4 lo = *(const u32x4*)(rp + c0), hi = *(const u32x4*)(rp + c1);
;         const i32x8 xf8 = {(int)lo.x, (int)lo.y, (int)lo.z, (int)lo.w, (int)hi.x, (int)hi.y, (int)hi.z, (int)hi.w};
; #pragma unroll
;         for (int j = 0; j < 4; ++j)
;           acc[i][j] = __builtin_amdgcn_mfma_scale_f32_16x16x128_f8f6f4(wf8[j], xf8, acc[i][j], 0, 0, 0, 0x77777777, 0, 0x7f7f7f7f);
;       }
;     } else {
; #pragma unroll
;     for (int kk = 0; kk < 2; ++kk) {
;       const int ch = ((kk * 4 + g) ^ (li & 7)) << 4;
;       bf16x8 xf[MI], wf[4];
; #pragma unroll
;       for (int j = 0; j < 4; ++j) wf[j] = *(const bf16x8*)(smem + wrow + ((j & 1) * 16 + (j >> 1) * 64) * 128 + ch);
; #pragma unroll
;       for (int i = 0; i < MI; ++i) xf[i] = *(const bf16x8*)(smem + xrow + i * 2048 + ch);
; #pragma unroll
;       for (int i = 0; i < MI; ++i)
; #pragma unroll
;         for (int j = 0; j < 4; ++j) {
	v_mfma_f32_16x16x32_bf16 v[72:75], v[172:175], v[152:155], v[72:75]
	v_mfma_f32_16x16x32_bf16 v[68:71], v[180:183], v[152:155], v[68:71]
	v_mfma_f32_16x16x32_bf16 v[64:67], v[192:195], v[152:155], v[64:67]
	v_mfma_f32_16x16x32_bf16 v[60:63], v[196:199], v[152:155], v[60:63]
	v_mfma_f32_16x16x32_bf16 v[88:91], v[172:175], v[148:151], v[88:91]
	v_mfma_f32_16x16x32_bf16 v[84:87], v[180:183], v[148:151], v[84:87]
	v_mfma_f32_16x16x32_bf16 v[80:83], v[192:195], v[148:151], v[80:83]
	v_mfma_f32_16x16x32_bf16 v[76:79], v[196:199], v[148:151], v[76:79]
	ds_read_b128 v[148:151], v0 offset:8192
	ds_read_b128 v[156:159], v0 offset:10240
	ds_read_b128 v[160:163], v0 offset:12288
	ds_read_b128 v[200:203], v0 offset:14336
	s_waitcnt lgkmcnt(3)
	v_mfma_f32_16x16x32_bf16 v[44:47], v[172:175], v[148:151], v[44:47]
	v_mfma_f32_16x16x32_bf16 v[40:43], v[180:183], v[148:151], v[40:43]
	v_mfma_f32_16x16x32_bf16 v[36:39], v[192:195], v[148:151], v[36:39]
	v_mfma_f32_16x16x32_bf16 v[32:35], v[196:199], v[148:151], v[32:35]
	s_waitcnt lgkmcnt(2)
	v_mfma_f32_16x16x32_bf16 v[28:31], v[172:175], v[156:159], v[28:31]
	v_mfma_f32_16x16x32_bf16 v[24:27], v[180:183], v[156:159], v[24:27]
	v_mfma_f32_16x16x32_bf16 v[20:23], v[192:195], v[156:159], v[20:23]
	v_mfma_f32_16x16x32_bf16 v[52:55], v[196:199], v[156:159], v[52:55]
	s_waitcnt lgkmcnt(1)
	v_mfma_f32_16x16x32_bf16 v[48:51], v[172:175], v[160:163], v[48:51]
	v_mfma_f32_16x16x32_bf16 v[56:59], v[180:183], v[160:163], v[56:59]
	v_mfma_f32_16x16x32_bf16 v[112:115], v[192:195], v[160:163], v[112:115]
	v_mfma_f32_16x16x32_bf16 v[108:111], v[196:199], v[160:163], v[108:111]
	s_waitcnt lgkmcnt(0)
	v_mfma_f32_16x16x32_bf16 v[100:103], v[172:175], v[200:203], v[100:103]
	v_mfma_f32_16x16x32_bf16 v[96:99], v[180:183], v[200:203], v[96:99]
	v_mfma_f32_16x16x32_bf16 v[92:95], v[192:195], v[200:203], v[92:95]
	v_mfma_f32_16x16x32_bf16 v[144:147], v[196:199], v[200:203], v[144:147]
	s_add_u32 s22, s22, 0x80
	s_addc_u32 s23, s23, 0
	s_cmpk_lg_i32 s22, 0x780
	s_cbranch_scc1 .LBB0_120
	s_barrier
	s_setprio 2
	s_mov_b32 m0, s62
	s_nop 0
	global_load_lds_dwordx4 v252, s[56:57]
	s_add_u32 m0, s62, 0x1000
	s_nop 0
	global_load_lds_dwordx4 v253, s[56:57]
	s_add_u32 s56, s56, 0x20000
	s_addc_u32 s57, s57, 0
	s_add_u32 m0, s62, 0x2000
	s_nop 0
	global_load_lds_dwordx4 v252, s[56:57]
	s_add_u32 m0, s62, 0x3000
	s_nop 0
	global_load_lds_dwordx4 v253, s[56:57]
	s_add_u32 s56, s56, 0x20000
	s_addc_u32 s57, s57, 0
	s_add_u32 m0, s62, 0x4000
	s_nop 0
	global_load_lds_dwordx4 v252, s[56:57]
	s_add_u32 m0, s62, 0x5000
	s_nop 0
	global_load_lds_dwordx4 v253, s[56:57]
	s_add_u32 s56, s56, 0x20000
	s_addc_u32 s57, s57, 0
	s_add_u32 m0, s62, 0x6000
	s_nop 0
	global_load_lds_dwordx4 v252, s[56:57]
	s_add_u32 m0, s62, 0x7000
	s_nop 0
	global_load_lds_dwordx4 v253, s[56:57]
	s_sub_u32 s56, s56, 0x60000
	s_subb_u32 s57, s57, 0
	s_add_u32 m0, s62, 0x8000
	s_nop 0
	global_load_lds_dwordx4 v252, s[58:59]
	s_add_u32 m0, s62, 0x9000
	s_nop 0
	global_load_lds_dwordx4 v253, s[58:59]
	s_add_u32 s58, s58, 0x20000
	s_addc_u32 s59, s59, 0
	s_add_u32 m0, s62, 0xa000
	s_nop 0
	global_load_lds_dwordx4 v252, s[58:59]
	s_add_u32 m0, s62, 0xb000
	s_nop 0
	global_load_lds_dwordx4 v253, s[58:59]
	s_sub_u32 s58, s58, 0x20000
	s_subb_u32 s59, s59, 0
	s_setprio 0
	s_waitcnt vmcnt(0)
	s_barrier
	v_bfe_u32 v12, v208, 4, 1
	v_mul_u32_u24_e32 v12, 24, v12
	v_mov_b32_e32 v13, 0
	ds_read_b128 v[148:151], v215 offset:32768
	ds_read_b128 v[152:155], v215 offset:34816
	ds_read_b128 v[156:159], v215 offset:40960
	ds_read_b128 v[160:163], v215 offset:43008
	ds_read_b128 v[164:167], v213
	ds_read_b128 v[168:171], v213 offset:2048
	ds_read_b128 v[172:175], v213 offset:4096
	ds_read_b128 v[176:179], v213 offset:6144
	ds_read_b128 v[180:183], v213 offset:8192
	ds_read_b128 v[184:187], v213 offset:10240
	ds_read_b128 v[188:191], v213 offset:12288
	ds_read_b128 v[192:195], v213 offset:14336
	s_waitcnt lgkmcnt(7)
	v_mfma_f32_16x16x32_bf16 v[140:143], v[148:151], v[164:167], v[140:143]
	s_mul_hi_i32 s11, s10, 0x180000
	s_mul_i32 s10, s10, 0x180000
	s_add_u32 s22, s8, s10
	v_mfma_f32_16x16x32_bf16 v[136:139], v[152:155], v[164:167], v[136:139]
	s_addc_u32 s23, s9, s11
	s_lshl_b64 s[10:11], s[20:21], 1
	s_add_u32 s10, s22, s10
	v_mfma_f32_16x16x32_bf16 v[132:135], v[156:159], v[164:167], v[132:135]
	s_addc_u32 s11, s23, s11
	s_movk_i32 s20, 0x1800
	s_add_i32 s28, s28, s78
	v_mfma_f32_16x16x32_bf16 v[128:131], v[160:163], v[164:167], v[128:131]
	s_add_i32 s27, s27, s71
	s_cmpk_gt_i32 s28, 0x5ff
	s_waitcnt lgkmcnt(6)
	v_mfma_f32_16x16x32_bf16 v[124:127], v[148:151], v[168:171], v[124:127]
	v_mfma_f32_16x16x32_bf16 v[120:123], v[152:155], v[168:171], v[120:123]
	v_mfma_f32_16x16x32_bf16 v[116:119], v[156:159], v[168:171], v[116:119]
	v_mfma_f32_16x16x32_bf16 v[104:107], v[160:163], v[168:171], v[104:107]
	s_waitcnt lgkmcnt(5)
	v_mfma_f32_16x16x32_bf16 v[88:91], v[148:151], v[172:175], v[88:91]
	v_mfma_f32_16x16x32_bf16 v[84:87], v[152:155], v[172:175], v[84:87]
	v_mfma_f32_16x16x32_bf16 v[80:83], v[156:159], v[172:175], v[80:83]
	v_mfma_f32_16x16x32_bf16 v[76:79], v[160:163], v[172:175], v[76:79]
	s_waitcnt lgkmcnt(4)
	v_mfma_f32_16x16x32_bf16 v[72:75], v[148:151], v[176:179], v[72:75]
	v_mfma_f32_16x16x32_bf16 v[68:71], v[152:155], v[176:179], v[68:71]
	v_mfma_f32_16x16x32_bf16 v[64:67], v[156:159], v[176:179], v[64:67]
	v_mfma_f32_16x16x32_bf16 v[60:63], v[160:163], v[176:179], v[60:63]
	s_waitcnt lgkmcnt(3)
	v_mfma_f32_16x16x32_bf16 v[44:47], v[148:151], v[180:183], v[44:47]
	v_mfma_f32_16x16x32_bf16 v[40:43], v[152:155], v[180:183], v[40:43]
	v_mfma_f32_16x16x32_bf16 v[36:39], v[156:159], v[180:183], v[36:39]
	v_mfma_f32_16x16x32_bf16 v[32:35], v[160:163], v[180:183], v[32:35]
	s_waitcnt lgkmcnt(2)
; template <int MI, bool SWAP, bool F8 = false>
; __device__ __forceinline__ void gemm_core(const bf16_t* __restrict__ A, int lda, const bf16_t* __restrict__ B, int ldb,
;                                           int K, char* smem, f32x4 (&acc)[MI][4]) {
;     ...
;       for (int j = 0; j < 4; ++j) wf[j] = *(const bf16x8*)(smem + wrow + ((j & 1) * 16 + (j >> 1) * 64) * 128 + ch);
; #pragma unroll
;       for (int i = 0; i < MI; ++i) xf[i] = *(const bf16x8*)(smem + xrow + i * 2048 + ch);
; #pragma unroll
;       for (int i = 0; i < MI; ++i)
; #pragma unroll
;         for (int j = 0; j < 4; ++j) {
;           if (SWAP) acc[i][j] = __builtin_amdgcn_mfma_f32_16x16x32_bf16(xf[i], wf[j], acc[i][j], 0, 0, 0);
;           else acc[i][j] = __builtin_amdgcn_mfma_f32_16x16x32_bf16(wf[j], xf[i], acc[i][j], 0, 0, 0);
; template <int MI, bool F8 = false>
; __device__ void gemm_tile_bf16(const bf16_t* A, int lda, const bf16_t* B, int ldb, int K, bf16_t* C, int ldc, char* smem) {
;     ...
;   for (int i = 0; i < MI; ++i)
; #pragma unroll
;     for (int j = 0; j < 4; ++j) {
;       u32x2 v;
;       v.x = pk_bf16(acc[i][j][0], acc[i][j][1]);
;       v.y = pk_bf16(acc[i][j][2], acc[i][j][3]);
;       *(u32x2*)(C + (size_t)MROW(i) * ldc + NCOL(j)) = v;
;     }
	v_mfma_f32_16x16x32_bf16 v[28:31], v[148:151], v[184:187], v[28:31]
	v_mfma_f32_16x16x32_bf16 v[24:27], v[152:155], v[184:187], v[24:27]
	v_mfma_f32_16x16x32_bf16 v[20:23], v[156:159], v[184:187], v[20:23]
	v_mfma_f32_16x16x32_bf16 v[52:55], v[160:163], v[184:187], v[52:55]
	s_waitcnt lgkmcnt(1)
	v_mfma_f32_16x16x32_bf16 v[48:51], v[148:151], v[188:191], v[48:51]
	v_mfma_f32_16x16x32_bf16 v[164:167], v[152:155], v[188:191], v[56:59]
	v_mfma_f32_16x16x32_bf16 v[168:171], v[156:159], v[188:191], v[112:115]
	v_mfma_f32_16x16x32_bf16 v[172:175], v[160:163], v[188:191], v[108:111]
	s_waitcnt lgkmcnt(0)
	v_mfma_f32_16x16x32_bf16 v[148:151], v[148:151], v[192:195], v[100:103]
	v_mfma_f32_16x16x32_bf16 v[152:155], v[152:155], v[192:195], v[96:99]
	v_mfma_f32_16x16x32_bf16 v[156:159], v[156:159], v[192:195], v[92:95]
	v_mfma_f32_16x16x32_bf16 v[144:147], v[160:163], v[192:195], v[144:147]
	ds_read_b128 v[160:163], v206 offset:32768
	ds_read_b128 v[176:179], v206 offset:34816
	ds_read_b128 v[180:183], v206 offset:40960
	ds_read_b128 v[184:187], v206 offset:43008
	ds_read_b128 v[56:59], v0
	ds_read_b128 v[92:95], v0 offset:2048
	ds_read_b128 v[96:99], v0 offset:4096
	ds_read_b128 v[188:191], v0 offset:6144
	ds_read_b128 v[192:195], v0 offset:8192
	ds_read_b128 v[196:199], v0 offset:10240
	ds_read_b128 v[200:203], v0 offset:12288
	ds_read_b128 v[204:207], v0 offset:14336
	s_waitcnt lgkmcnt(7)
	v_mfma_f32_16x16x32_bf16 v[140:143], v[160:163], v[56:59], v[140:143]
	v_mfma_f32_16x16x32_bf16 v[136:139], v[176:179], v[56:59], v[136:139]
	v_mfma_f32_16x16x32_bf16 v[132:135], v[180:183], v[56:59], v[132:135]
	s_nop 5
	v_cvt_pk_bf16_f32 v140, v140, v141
	v_cvt_pk_bf16_f32 v141, v142, v143
	v_cvt_pk_bf16_f32 v136, v136, v137
	v_mfma_f32_16x16x32_bf16 v[128:131], v[184:187], v[56:59], v[128:131]
	v_cvt_pk_bf16_f32 v137, v138, v139
	v_cvt_pk_bf16_f32 v132, v132, v133
	v_cvt_pk_bf16_f32 v133, v134, v135
	s_waitcnt lgkmcnt(2)
	v_mfma_f32_16x16x32_bf16 v[56:59], v[180:183], v[196:199], v[20:23]
	s_waitcnt lgkmcnt(0)
	v_mfma_f32_16x16x32_bf16 v[20:23], v[184:187], v[204:207], v[144:147]
	s_nop 0
	v_cvt_pk_bf16_f32 v128, v128, v129
	v_cvt_pk_bf16_f32 v129, v130, v131
	s_nop 2
	v_cvt_pk_bf16_f32 v56, v56, v57
	v_mov_b32_e32 v146, v208
	v_mfma_f32_16x16x32_bf16 v[124:127], v[160:163], v[92:95], v[124:127]
	v_lshrrev_b32_e32 v0, 1, v146
	v_and_b32_e32 v0, 32, v0
	v_lshrrev_b32_e32 v2, 2, v146
	v_and_b32_e32 v147, 0xffffff8f, v146
	v_and_or_b32 v0, v2, 12, v0
	v_mov_b64_e32 v[2:3], s[10:11]
	v_mfma_f32_16x16x32_bf16 v[216:219], v[180:183], v[92:95], v[116:119]
	v_mad_i64_i32 v[144:145], s[10:11], v147, s20, v[2:3]
	v_lshlrev_b32_e32 v0, 1, v0
	v_mfma_f32_16x16x32_bf16 v[116:119], v[184:187], v[92:95], v[104:107]
	v_lshl_add_u64 v[142:143], v[144:145], 0, v[0:1]
	global_store_dwordx2 v[142:143], v[128:129], off offset:160
	v_or_b32_e32 v128, 16, v147
	v_mfma_f32_16x16x32_bf16 v[112:115], v[160:163], v[96:99], v[88:91]
	v_mad_i64_i32 v[128:129], s[10:11], v128, s20, v[2:3]
	v_cvt_pk_bf16_f32 v124, v124, v125
	v_mfma_f32_16x16x32_bf16 v[100:103], v[184:187], v[96:99], v[76:79]
	v_cvt_pk_bf16_f32 v125, v126, v127
	v_lshl_add_u64 v[126:127], v[128:129], 0, v[0:1]
	v_cvt_pk_bf16_f32 v116, v116, v117
	v_cvt_pk_bf16_f32 v117, v118, v119
	global_store_dwordx2 v[126:127], v[116:117], off offset:160
	v_or_b32_e32 v116, 32, v147
	v_mfma_f32_16x16x32_bf16 v[108:111], v[176:179], v[96:99], v[84:87]
	v_mad_i64_i32 v[116:117], s[10:11], v116, s20, v[2:3]
	v_cvt_pk_bf16_f32 v112, v112, v113
	v_mfma_f32_16x16x32_bf16 v[104:107], v[180:183], v[96:99], v[80:83]
	v_cvt_pk_bf16_f32 v113, v114, v115
	v_lshl_add_u64 v[114:115], v[116:117], 0, v[0:1]
	v_cvt_pk_bf16_f32 v100, v100, v101
	v_mfma_f32_16x16x32_bf16 v[96:99], v[160:163], v[188:191], v[72:75]
	v_cvt_pk_bf16_f32 v101, v102, v103
	global_store_dwordx2 v[114:115], v[100:101], off offset:160
	v_or_b32_e32 v100, 48, v147
	v_mfma_f32_16x16x32_bf16 v[84:87], v[184:187], v[188:191], v[60:63]
	v_mad_i64_i32 v[100:101], s[10:11], v100, s20, v[2:3]
	s_nop 2
	v_cvt_pk_bf16_f32 v96, v96, v97
	v_mfma_f32_16x16x32_bf16 v[120:123], v[176:179], v[92:95], v[120:123]
	v_cvt_pk_bf16_f32 v97, v98, v99
	v_lshl_add_u64 v[98:99], v[100:101], 0, v[0:1]
	v_cvt_pk_bf16_f32 v84, v84, v85
	v_mfma_f32_16x16x32_bf16 v[92:95], v[176:179], v[188:191], v[68:71]
	v_cvt_pk_bf16_f32 v85, v86, v87
	global_store_dwordx2 v[98:99], v[84:85], off offset:160
	v_or_b32_e32 v84, 64, v147
	v_mfma_f32_16x16x32_bf16 v[80:83], v[160:163], v[192:195], v[44:47]
	v_mad_i64_i32 v[84:85], s[10:11], v84, s20, v[2:3]
	v_cvt_pk_bf16_f32 v120, v120, v121
	v_mfma_f32_16x16x32_bf16 v[68:71], v[184:187], v[192:195], v[32:35]
	v_cvt_pk_bf16_f32 v121, v122, v123
	s_nop 3
	v_cvt_pk_bf16_f32 v80, v80, v81
	v_cvt_pk_bf16_f32 v81, v82, v83
	v_mfma_f32_16x16x32_bf16 v[88:91], v[180:183], v[188:191], v[64:67]
	v_lshl_add_u64 v[82:83], v[84:85], 0, v[0:1]
	v_cvt_pk_bf16_f32 v68, v68, v69
	v_cvt_pk_bf16_f32 v69, v70, v71
	v_mfma_f32_16x16x32_bf16 v[64:67], v[160:163], v[196:199], v[28:31]
; template <int MI, bool F8 = false>
; __device__ void gemm_tile_bf16(const bf16_t* A, int lda, const bf16_t* B, int ldb, int K, bf16_t* C, int ldc, char* smem) {
;     ...
;   for (int i = 0; i < MI; ++i)
; #pragma unroll
;     for (int j = 0; j < 4; ++j) {
;       u32x2 v;
;       v.x = pk_bf16(acc[i][j][0], acc[i][j][1]);
;       v.y = pk_bf16(acc[i][j][2], acc[i][j][3]);
;       *(u32x2*)(C + (size_t)MROW(i) * ldc + NCOL(j)) = v;
;     }
; __global__ void __launch_bounds__(256, 2) fwd_kernel(P p) {
;     ...
;       for (int it = blockIdx.x; it < 64 * 24; it += G) {
	global_store_dwordx2 v[82:83], v[68:69], off offset:160
	v_or_b32_e32 v68, 0x50, v147
	v_mad_i64_i32 v[68:69], s[10:11], v68, s20, v[2:3]
	v_mfma_f32_16x16x32_bf16 v[52:55], v[184:187], v[196:199], v[52:55]
	s_nop 3
	v_cvt_pk_bf16_f32 v64, v64, v65
	v_cvt_pk_bf16_f32 v65, v66, v67
	v_lshl_add_u64 v[66:67], v[68:69], 0, v[0:1]
	v_mfma_f32_16x16x32_bf16 v[72:75], v[180:183], v[192:195], v[36:39]
	global_store_dwordx2 v[126:127], v[120:121], off offset:32
	v_cvt_pk_bf16_f32 v52, v52, v53
	v_cvt_pk_bf16_f32 v53, v54, v55
	v_mfma_f32_16x16x32_bf16 v[48:51], v[160:163], v[200:203], v[48:51]
	global_store_dwordx2 v[66:67], v[52:53], off offset:160
	v_or_b32_e32 v52, 0x60, v147
	v_mad_i64_i32 v[52:53], s[10:11], v52, s20, v[2:3]
	v_mfma_f32_16x16x32_bf16 v[36:39], v[184:187], v[200:203], v[172:175]
	s_nop 3
	v_cvt_pk_bf16_f32 v48, v48, v49
	v_cvt_pk_bf16_f32 v49, v50, v51
	v_lshl_add_u64 v[50:51], v[52:53], 0, v[0:1]
	v_mfma_f32_16x16x32_bf16 v[76:79], v[176:179], v[192:195], v[40:43]
	v_cvt_pk_bf16_f32 v120, v216, v217
	v_cvt_pk_bf16_f32 v36, v36, v37
	v_cvt_pk_bf16_f32 v37, v38, v39
	v_mfma_f32_16x16x32_bf16 v[60:63], v[176:179], v[196:199], v[24:27]
	global_store_dwordx2 v[50:51], v[36:37], off offset:160
	v_or_b32_e32 v36, 0x70, v146
	v_mad_i64_i32 v[2:3], s[10:11], v36, s20, v[2:3]
	v_mfma_f32_16x16x32_bf16 v[44:47], v[176:179], v[200:203], v[164:167]
	v_cvt_pk_bf16_f32 v121, v218, v219
	v_cvt_pk_bf16_f32 v108, v108, v109
	v_cvt_pk_bf16_f32 v109, v110, v111
	v_mfma_f32_16x16x32_bf16 v[40:43], v[180:183], v[200:203], v[168:171]
	v_cvt_pk_bf16_f32 v104, v104, v105
	v_cvt_pk_bf16_f32 v105, v106, v107
	v_cvt_pk_bf16_f32 v92, v92, v93
	v_mfma_f32_16x16x32_bf16 v[32:35], v[160:163], v[204:207], v[148:151]
	v_cvt_pk_bf16_f32 v93, v94, v95
	v_cvt_pk_bf16_f32 v88, v88, v89
	v_cvt_pk_bf16_f32 v89, v90, v91
	v_mfma_f32_16x16x32_bf16 v[28:31], v[176:179], v[204:207], v[152:155]
	v_cvt_pk_bf16_f32 v76, v76, v77
	v_cvt_pk_bf16_f32 v77, v78, v79
	v_cvt_pk_bf16_f32 v72, v72, v73
	v_mfma_f32_16x16x32_bf16 v[24:27], v[180:183], v[204:207], v[156:159]
	v_cvt_pk_bf16_f32 v73, v74, v75
	v_cvt_pk_bf16_f32 v60, v60, v61
	v_cvt_pk_bf16_f32 v61, v62, v63
	v_cvt_pk_bf16_f32 v57, v58, v59
	v_cvt_pk_bf16_f32 v44, v44, v45
	v_cvt_pk_bf16_f32 v45, v46, v47
	v_cvt_pk_bf16_f32 v40, v40, v41
	v_cvt_pk_bf16_f32 v41, v42, v43
	v_cvt_pk_bf16_f32 v32, v32, v33
	v_cvt_pk_bf16_f32 v33, v34, v35
	v_lshl_add_u64 v[2:3], v[2:3], 0, v[0:1]
	v_cvt_pk_bf16_f32 v28, v28, v29
	v_cvt_pk_bf16_f32 v29, v30, v31
	v_cvt_pk_bf16_f32 v24, v24, v25
	v_cvt_pk_bf16_f32 v25, v26, v27
	v_cvt_pk_bf16_f32 v20, v20, v21
	v_cvt_pk_bf16_f32 v21, v22, v23
	v_mov_b64_e32 v[4:5], v[140:141]
	v_mov_b64_e32 v[6:7], v[136:137]
	s_nop 1
	v_permlane16_swap_b32_e32 v4, v6
	v_permlane16_swap_b32_e32 v5, v7
	v_lshl_add_u64 v[14:15], v[142:143], 0, v[12:13]
	global_store_dwordx4 v[14:15], v[4:7], off
	global_store_dwordx2 v[142:143], v[132:133], off offset:128
	global_store_dwordx2 v[126:127], v[124:125], off
	global_store_dwordx2 v[126:127], v[120:121], off offset:128
	v_mov_b64_e32 v[8:9], v[112:113]
	v_mov_b64_e32 v[10:11], v[108:109]
	s_nop 1
	v_permlane16_swap_b32_e32 v8, v10
	v_permlane16_swap_b32_e32 v9, v11
	v_lshl_add_u64 v[14:15], v[114:115], 0, v[12:13]
	global_store_dwordx4 v[14:15], v[8:11], off
	global_store_dwordx2 v[114:115], v[104:105], off offset:128
	v_mov_b64_e32 v[4:5], v[96:97]
	v_mov_b64_e32 v[6:7], v[92:93]
	s_nop 1
	v_permlane16_swap_b32_e32 v4, v6
	v_permlane16_swap_b32_e32 v5, v7
	v_lshl_add_u64 v[14:15], v[98:99], 0, v[12:13]
	global_store_dwordx4 v[14:15], v[4:7], off
	global_store_dwordx2 v[98:99], v[88:89], off offset:128
	v_mov_b64_e32 v[8:9], v[80:81]
	v_mov_b64_e32 v[10:11], v[76:77]
	s_nop 1
	v_permlane16_swap_b32_e32 v8, v10
	v_permlane16_swap_b32_e32 v9, v11
	v_lshl_add_u64 v[14:15], v[82:83], 0, v[12:13]
	global_store_dwordx4 v[14:15], v[8:11], off
	global_store_dwordx2 v[82:83], v[72:73], off offset:128
	v_mov_b64_e32 v[4:5], v[64:65]
	v_mov_b64_e32 v[6:7], v[60:61]
	s_nop 1
	v_permlane16_swap_b32_e32 v4, v6
	v_permlane16_swap_b32_e32 v5, v7
	v_lshl_add_u64 v[14:15], v[66:67], 0, v[12:13]
	global_store_dwordx4 v[14:15], v[4:7], off
	global_store_dwordx2 v[66:67], v[56:57], off offset:128
	v_mov_b64_e32 v[8:9], v[48:49]
	v_mov_b64_e32 v[10:11], v[44:45]
	s_nop 1
	v_permlane16_swap_b32_e32 v8, v10
	v_permlane16_swap_b32_e32 v9, v11
	v_lshl_add_u64 v[14:15], v[50:51], 0, v[12:13]
	global_store_dwordx4 v[14:15], v[8:11], off
	global_store_dwordx2 v[50:51], v[40:41], off offset:128
	v_mov_b64_e32 v[4:5], v[32:33]
	v_mov_b64_e32 v[6:7], v[28:29]
	s_nop 1
	v_permlane16_swap_b32_e32 v4, v6
	v_permlane16_swap_b32_e32 v5, v7
	v_lshl_add_u64 v[14:15], v[2:3], 0, v[12:13]
	global_store_dwordx4 v[14:15], v[4:7], off
	v_mov_b64_e32 v[8:9], v[24:25]
	v_mov_b64_e32 v[10:11], v[20:21]
	s_nop 1
	v_permlane16_swap_b32_e32 v8, v10
	v_permlane16_swap_b32_e32 v9, v11
	v_lshl_add_u64 v[14:15], v[2:3], 0, v[12:13]
	global_store_dwordx4 v[14:15], v[8:11], off offset:128
	s_cbranch_scc0 .LBB0_119

; template <int MI, bool SWAP, bool F8 = false>
; __device__ __forceinline__ void gemm_core(const bf16_t* __restrict__ A, int lda, const bf16_t* __restrict__ B, int ldb,
;                                           int K, char* smem, f32x4 (&acc)[MI][4]) {
;     ...
;   for (int kt = 0; kt < nk; ++kt) {
;     __syncthreads();
; #pragma unroll
;     for (int i = 0; i < MI; ++i) *(u32x4*)(smem + woff + i * 4096) = ra[i];
; #pragma unroll
;     for (int i = 0; i < 4; ++i) *(u32x4*)(smem + 32768 + woff + i * 4096) = rb[i];
;     __syncthreads();
;     if (kt + 1 < nk) {
; #pragma unroll
;       for (int i = 0; i < MI; ++i) ra[i] = *(const u32x4*)(ap + (size_t)(32 * i) * lda + (kt + 1) * 64);
; #pragma unroll
;       for (int i = 0; i < 4; ++i) rb[i] = *(const u32x4*)(bp + (size_t)(32 * i) * ldb + (kt + 1) * 64);
.LBB0_236:
	v_add_u32_e32 v215, v203, v204
	s_barrier
	s_setprio 2
	s_mov_b32 m0, s62
	s_nop 0
	global_load_lds_dwordx4 v252, s[56:57]
	s_add_u32 m0, s62, 0x1000
	s_nop 0
	global_load_lds_dwordx4 v253, s[56:57]
	s_add_u32 s56, s56, 0x20000
	s_addc_u32 s57, s57, 0
	s_add_u32 m0, s62, 0x2000
	s_nop 0
	global_load_lds_dwordx4 v252, s[56:57]
	s_add_u32 m0, s62, 0x3000
	s_nop 0
	global_load_lds_dwordx4 v253, s[56:57]
	s_add_u32 s56, s56, 0x20000
	s_addc_u32 s57, s57, 0
	s_add_u32 m0, s62, 0x4000
	s_nop 0
	global_load_lds_dwordx4 v252, s[56:57]
	s_add_u32 m0, s62, 0x5000
	s_nop 0
	global_load_lds_dwordx4 v253, s[56:57]
	s_add_u32 s56, s56, 0x20000
	s_addc_u32 s57, s57, 0
	s_add_u32 m0, s62, 0x6000
	s_nop 0
	global_load_lds_dwordx4 v252, s[56:57]
	s_add_u32 m0, s62, 0x7000
	s_nop 0
	global_load_lds_dwordx4 v253, s[56:57]
	s_sub_u32 s56, s56, 0x60000
	s_subb_u32 s57, s57, 0
	s_add_u32 m0, s62, 0x8000
	s_nop 0
	global_load_lds_dwordx4 v252, s[58:59]
	s_add_u32 m0, s62, 0x9000
	s_nop 0
	global_load_lds_dwordx4 v253, s[58:59]
	s_add_u32 s58, s58, 0x20000
	s_addc_u32 s59, s59, 0
	s_add_u32 m0, s62, 0xa000
	s_nop 0
	global_load_lds_dwordx4 v252, s[58:59]
	s_add_u32 m0, s62, 0xb000
	s_nop 0
	global_load_lds_dwordx4 v253, s[58:59]
	s_sub_u32 s58, s58, 0x20000
	s_subb_u32 s59, s59, 0
	s_setprio 0
	v_add_u32_e32 v252, 0x80, v252
	v_add_u32_e32 v253, 0x80, v253
	s_waitcnt vmcnt(0)
	s_cmp_gt_u32 s63, 12
	s_cbranch_scc1 .Lcch236_ret
	s_cmp_eq_u32 s63, 0
	s_cbranch_scc1 .Lcch236_h0
	s_cmp_eq_u32 s63, 3
	s_cbranch_scc1 .Lcch236_h1
	s_cmp_eq_u32 s63, 6
	s_cbranch_scc1 .Lcch236_h2
	s_cmp_eq_u32 s63, 9
	s_cbranch_scc1 .Lcch236_h3
	s_cmp_eq_u32 s63, 12
	s_cbranch_scc1 .Lcch236_h4
	s_branch .Lcch236_ret

; template <int MI, bool SWAP, bool F8 = false>
; __device__ __forceinline__ void gemm_core(const bf16_t* __restrict__ A, int lda, const bf16_t* __restrict__ B, int ldb,
;                                           int K, char* smem, f32x4 (&acc)[MI][4]) {
;     ...
; #pragma unroll
;     for (int kk = 0; kk < 2; ++kk) {
;       const int ch = ((kk * 4 + g) ^ (li & 7)) << 4;
;       bf16x8 xf[MI], wf[4];
; #pragma unroll
;       for (int j = 0; j < 4; ++j) wf[j] = *(const bf16x8*)(smem + wrow + ((j & 1) * 16 + (j >> 1) * 64) * 128 + ch);
; #pragma unroll
;       for (int i = 0; i < MI; ++i) xf[i] = *(const bf16x8*)(smem + xrow + i * 2048 + ch);
; #pragma unroll
;       for (int i = 0; i < MI; ++i)
; #pragma unroll
;         for (int j = 0; j < 4; ++j) {
;           if (SWAP) acc[i][j] = __builtin_amdgcn_mfma_f32_16x16x32_bf16(xf[i], wf[j], acc[i][j], 0, 0, 0);
;           else acc[i][j] = __builtin_amdgcn_mfma_f32_16x16x32_bf16(wf[j], xf[i], acc[i][j], 0, 0, 0);
;         }
;     }
.Lcch236_ret:
	s_add_u32 s63, s63, 1
	s_barrier
	v_add_u32_e32 v213, v202, v204
	ds_read_b128 v[148:151], v215 offset:32768
	ds_read_b128 v[152:155], v215 offset:34816
	ds_read_b128 v[156:159], v213
	ds_read_b128 v[160:163], v213 offset:2048
	ds_read_b128 v[164:167], v215 offset:40960
	ds_read_b128 v[168:171], v215 offset:43008
	s_waitcnt lgkmcnt(3)
	v_mfma_f32_16x16x32_bf16 v[140:143], v[148:151], v[156:159], v[140:143]
	v_add_u32_e32 v207, v203, v205
	v_add_u32_e32 v206, v202, v205
	v_mfma_f32_16x16x32_bf16 v[136:139], v[152:155], v[156:159], v[136:139]
	s_waitcnt lgkmcnt(1)
	v_mfma_f32_16x16x32_bf16 v[132:135], v[164:167], v[156:159], v[132:135]
	s_waitcnt lgkmcnt(0)
	v_mfma_f32_16x16x32_bf16 v[124:127], v[168:171], v[156:159], v[124:127]
	v_mfma_f32_16x16x32_bf16 v[108:111], v[148:151], v[160:163], v[108:111]
	v_mfma_f32_16x16x32_bf16 v[104:107], v[152:155], v[160:163], v[104:107]
	v_mfma_f32_16x16x32_bf16 v[96:99], v[164:167], v[160:163], v[96:99]
	v_mfma_f32_16x16x32_bf16 v[92:95], v[168:171], v[160:163], v[92:95]
	ds_read_b128 v[156:159], v213 offset:4096
	ds_read_b128 v[160:163], v213 offset:6144
	s_waitcnt lgkmcnt(1)
	v_mfma_f32_16x16x32_bf16 v[88:91], v[148:151], v[156:159], v[88:91]
	v_mfma_f32_16x16x32_bf16 v[84:87], v[152:155], v[156:159], v[84:87]
	v_mfma_f32_16x16x32_bf16 v[80:83], v[164:167], v[156:159], v[80:83]
	v_mfma_f32_16x16x32_bf16 v[60:63], v[168:171], v[156:159], v[60:63]
	s_waitcnt lgkmcnt(0)
	v_mfma_f32_16x16x32_bf16 v[56:59], v[148:151], v[160:163], v[56:59]
	v_mfma_f32_16x16x32_bf16 v[52:55], v[152:155], v[160:163], v[52:55]
	v_mfma_f32_16x16x32_bf16 v[48:51], v[164:167], v[160:163], v[48:51]
	v_mfma_f32_16x16x32_bf16 v[44:47], v[168:171], v[160:163], v[44:47]
	ds_read_b128 v[156:159], v213 offset:8192
	ds_read_b128 v[160:163], v213 offset:10240
	s_waitcnt lgkmcnt(1)
	v_mfma_f32_16x16x32_bf16 v[40:43], v[148:151], v[156:159], v[40:43]
	v_mfma_f32_16x16x32_bf16 v[36:39], v[152:155], v[156:159], v[36:39]
	v_mfma_f32_16x16x32_bf16 v[32:35], v[164:167], v[156:159], v[32:35]
	v_mfma_f32_16x16x32_bf16 v[28:31], v[168:171], v[156:159], v[28:31]
	s_waitcnt lgkmcnt(0)
	v_mfma_f32_16x16x32_bf16 v[24:27], v[148:151], v[160:163], v[24:27]
	v_mfma_f32_16x16x32_bf16 v[20:23], v[152:155], v[160:163], v[20:23]
	v_mfma_f32_16x16x32_bf16 v[68:71], v[164:167], v[160:163], v[68:71]
	v_mfma_f32_16x16x32_bf16 v[64:67], v[168:171], v[160:163], v[64:67]
	ds_read_b128 v[156:159], v213 offset:12288
	ds_read_b128 v[160:163], v213 offset:14336
	ds_read_b128 v[172:175], v207 offset:32768
	ds_read_b128 v[180:183], v207 offset:34816
	s_waitcnt lgkmcnt(3)
	v_mfma_f32_16x16x32_bf16 v[72:75], v[148:151], v[156:159], v[72:75]
	v_mfma_f32_16x16x32_bf16 v[76:79], v[152:155], v[156:159], v[76:79]
	v_mfma_f32_16x16x32_bf16 v[128:131], v[164:167], v[156:159], v[128:131]
	v_mfma_f32_16x16x32_bf16 v[120:123], v[168:171], v[156:159], v[120:123]
	s_waitcnt lgkmcnt(2)
	v_mfma_f32_16x16x32_bf16 v[116:119], v[148:151], v[160:163], v[116:119]
	v_mfma_f32_16x16x32_bf16 v[112:115], v[152:155], v[160:163], v[112:115]
	ds_read_b128 v[148:151], v206
	ds_read_b128 v[152:155], v206 offset:2048
	ds_read_b128 v[192:195], v207 offset:40960
	ds_read_b128 v[196:199], v207 offset:43008
	v_mfma_f32_16x16x32_bf16 v[100:103], v[164:167], v[160:163], v[100:103]
	v_mfma_f32_16x16x32_bf16 v[144:147], v[168:171], v[160:163], v[144:147]
	s_waitcnt lgkmcnt(3)
	v_mfma_f32_16x16x32_bf16 v[140:143], v[172:175], v[148:151], v[140:143]
	v_mfma_f32_16x16x32_bf16 v[136:139], v[180:183], v[148:151], v[136:139]
	s_waitcnt lgkmcnt(1)
	v_mfma_f32_16x16x32_bf16 v[132:135], v[192:195], v[148:151], v[132:135]
	s_waitcnt lgkmcnt(0)
	v_mfma_f32_16x16x32_bf16 v[124:127], v[196:199], v[148:151], v[124:127]
	v_mfma_f32_16x16x32_bf16 v[108:111], v[172:175], v[152:155], v[108:111]
	v_mfma_f32_16x16x32_bf16 v[104:107], v[180:183], v[152:155], v[104:107]
	v_mfma_f32_16x16x32_bf16 v[96:99], v[192:195], v[152:155], v[96:99]
	v_mfma_f32_16x16x32_bf16 v[92:95], v[196:199], v[152:155], v[92:95]
	ds_read_b128 v[148:151], v206 offset:4096
	ds_read_b128 v[152:155], v206 offset:6144
	s_waitcnt lgkmcnt(1)
	v_mfma_f32_16x16x32_bf16 v[88:91], v[172:175], v[148:151], v[88:91]
	ds_read_b128 v[156:159], v206 offset:12288
	ds_read_b128 v[216:219], v206 offset:14336
	v_mfma_f32_16x16x32_bf16 v[84:87], v[180:183], v[148:151], v[84:87]
	v_mfma_f32_16x16x32_bf16 v[80:83], v[192:195], v[148:151], v[80:83]
	v_mfma_f32_16x16x32_bf16 v[60:63], v[196:199], v[148:151], v[60:63]
	ds_read_b128 v[148:151], v206 offset:8192
	s_waitcnt lgkmcnt(3)
	v_mfma_f32_16x16x32_bf16 v[56:59], v[172:175], v[152:155], v[56:59]
	v_mfma_f32_16x16x32_bf16 v[52:55], v[180:183], v[152:155], v[52:55]
	v_mfma_f32_16x16x32_bf16 v[48:51], v[192:195], v[152:155], v[48:51]
	v_mfma_f32_16x16x32_bf16 v[44:47], v[196:199], v[152:155], v[44:47]
	ds_read_b128 v[152:155], v206 offset:10240
	s_waitcnt lgkmcnt(1)
	v_mfma_f32_16x16x32_bf16 v[40:43], v[172:175], v[148:151], v[40:43]
	v_mfma_f32_16x16x32_bf16 v[36:39], v[180:183], v[148:151], v[36:39]
	v_mfma_f32_16x16x32_bf16 v[32:35], v[192:195], v[148:151], v[32:35]
	v_mfma_f32_16x16x32_bf16 v[28:31], v[196:199], v[148:151], v[28:31]
	s_waitcnt lgkmcnt(0)
	v_mfma_f32_16x16x32_bf16 v[24:27], v[172:175], v[152:155], v[24:27]
	v_mfma_f32_16x16x32_bf16 v[20:23], v[180:183], v[152:155], v[20:23]
	v_mfma_f32_16x16x32_bf16 v[68:71], v[192:195], v[152:155], v[68:71]
	v_mfma_f32_16x16x32_bf16 v[64:67], v[196:199], v[152:155], v[64:67]
	v_mfma_f32_16x16x32_bf16 v[72:75], v[172:175], v[156:159], v[72:75]
	v_mfma_f32_16x16x32_bf16 v[76:79], v[180:183], v[156:159], v[76:79]
	v_mfma_f32_16x16x32_bf16 v[128:131], v[192:195], v[156:159], v[128:131]
	v_mfma_f32_16x16x32_bf16 v[120:123], v[196:199], v[156:159], v[120:123]
	v_mfma_f32_16x16x32_bf16 v[116:119], v[172:175], v[216:219], v[116:119]
	v_mfma_f32_16x16x32_bf16 v[112:115], v[180:183], v[216:219], v[112:115]
	v_mfma_f32_16x16x32_bf16 v[100:103], v[192:195], v[216:219], v[100:103]
	v_mfma_f32_16x16x32_bf16 v[144:147], v[196:199], v[216:219], v[144:147]
	s_add_u32 s20, s20, 0x80
	s_addc_u32 s21, s21, 0
	s_cmpk_lg_i32 s20, 0x780
	s_cbranch_scc1 .LBB0_236
; template <int MI, bool SWAP, bool F8 = false>
; __device__ __forceinline__ void gemm_core(const bf16_t* __restrict__ A, int lda, const bf16_t* __restrict__ B, int ldb,
;                                           int K, char* smem, f32x4 (&acc)[MI][4]) {
;     ...
;   for (int kt = 0; kt < nk; ++kt) {
;     __syncthreads();
; #pragma unroll
;     for (int i = 0; i < MI; ++i) *(u32x4*)(smem + woff + i * 4096) = ra[i];
; #pragma unroll
;     for (int i = 0; i < 4; ++i) *(u32x4*)(smem + 32768 + woff + i * 4096) = rb[i];
;     __syncthreads();
;     if (kt + 1 < nk) {
; #pragma unroll
;       for (int i = 0; i < MI; ++i) ra[i] = *(const u32x4*)(ap + (size_t)(32 * i) * lda + (kt + 1) * 64);
; #pragma unroll
;       for (int i = 0; i < 4; ++i) rb[i] = *(const u32x4*)(bp + (size_t)(32 * i) * ldb + (kt + 1) * 64);
;     }
;     if (F8) {
;       const int c0 = (g ^ (li & 7)) << 4, c1 = ((4 + g) ^ (li & 7)) << 4;
;       i32x8 wf8[4];
; #pragma unroll
;       for (int j = 0; j < 4; ++j) {
;         const char* rp = smem + wrow + ((j & 1) * 16 + (j >> 1) * 64) * 128;
;         const u32x4 lo = *(const u32x4*)(rp + c0), hi = *(const u32x4*)(rp + c1);
;         wf8[j] = (i32x8){(int)lo.x, (int)lo.y, (int)lo.z, (int)lo.w, (int)hi.x, (int)hi.y, (int)hi.z, (int)hi.w};
;       }
; #pragma unroll
;       for (int i = 0; i < MI; ++i) {
;         const char* rp = smem + xrow + i * 2048;
;         const u32x4 lo = *(const u32x4*)(rp + c0), hi = *(const u32x4*)(rp + c1);
;         const i32x8 xf8 = {(int)lo.x, (int)lo.y, (int)lo.z, (int)lo.w, (int)hi.x, (int)hi.y, (int)hi.z, (int)hi.w};
; #pragma unroll
;         for (int j = 0; j < 4; ++j)
;           acc[i][j] = __builtin_amdgcn_mfma_scale_f32_16x16x128_f8f6f4(wf8[j], xf8, acc[i][j], 0, 0, 0, 0x77777777, 0, 0x7f7f7f7f);
;       }
;     } else {
; #pragma unroll
;     for (int kk = 0; kk < 2; ++kk) {
;       const int ch = ((kk * 4 + g) ^ (li & 7)) << 4;
;       bf16x8 xf[MI], wf[4];
; #pragma unroll
;       for (int j = 0; j < 4; ++j) wf[j] = *(const bf16x8*)(smem + wrow + ((j & 1) * 16 + (j >> 1) * 64) * 128 + ch);
; #pragma unroll
;       for (int i = 0; i < MI; ++i) xf[i] = *(const bf16x8*)(smem + xrow + i * 2048 + ch);
; #pragma unroll
;       for (int i = 0; i < MI; ++i)
; #pragma unroll
;         for (int j = 0; j < 4; ++j) {
	s_barrier
	s_setprio 2
	s_mov_b32 m0, s62
	s_nop 0
	global_load_lds_dwordx4 v252, s[56:57]
	s_add_u32 m0, s62, 0x1000
	s_nop 0
	global_load_lds_dwordx4 v253, s[56:57]
	s_add_u32 s56, s56, 0x20000
	s_addc_u32 s57, s57, 0
	s_add_u32 m0, s62, 0x2000
	s_nop 0
	global_load_lds_dwordx4 v252, s[56:57]
	s_add_u32 m0, s62, 0x3000
	s_nop 0
	global_load_lds_dwordx4 v253, s[56:57]
	s_add_u32 s56, s56, 0x20000
	s_addc_u32 s57, s57, 0
	s_add_u32 m0, s62, 0x4000
	s_nop 0
	global_load_lds_dwordx4 v252, s[56:57]
	s_add_u32 m0, s62, 0x5000
	s_nop 0
	global_load_lds_dwordx4 v253, s[56:57]
	s_add_u32 s56, s56, 0x20000
	s_addc_u32 s57, s57, 0
	s_add_u32 m0, s62, 0x6000
	s_nop 0
	global_load_lds_dwordx4 v252, s[56:57]
	s_add_u32 m0, s62, 0x7000
	s_nop 0
	global_load_lds_dwordx4 v253, s[56:57]
	s_sub_u32 s56, s56, 0x60000
	s_subb_u32 s57, s57, 0
	s_add_u32 m0, s62, 0x8000
	s_nop 0
	global_load_lds_dwordx4 v252, s[58:59]
	s_add_u32 m0, s62, 0x9000
	s_nop 0
	global_load_lds_dwordx4 v253, s[58:59]
	s_add_u32 s58, s58, 0x20000
	s_addc_u32 s59, s59, 0
	s_add_u32 m0, s62, 0xa000
	s_nop 0
	global_load_lds_dwordx4 v252, s[58:59]
	s_add_u32 m0, s62, 0xb000
	s_nop 0
	global_load_lds_dwordx4 v253, s[58:59]
	s_sub_u32 s58, s58, 0x20000
	s_subb_u32 s59, s59, 0
	s_setprio 0
	s_waitcnt vmcnt(0)
	s_barrier
	ds_read_b128 v[148:151], v215 offset:32768
	ds_read_b128 v[152:155], v215 offset:34816
	ds_read_b128 v[156:159], v215 offset:40960
	ds_read_b128 v[160:163], v215 offset:43008
	ds_read_b128 v[164:167], v213
	ds_read_b128 v[168:171], v213 offset:2048
	ds_read_b128 v[172:175], v213 offset:4096
	ds_read_b128 v[176:179], v213 offset:6144
	ds_read_b128 v[180:183], v213 offset:8192
	ds_read_b128 v[184:187], v213 offset:10240
	ds_read_b128 v[188:191], v213 offset:12288
	ds_read_b128 v[192:195], v213 offset:14336
	s_waitcnt lgkmcnt(7)
	v_mfma_f32_16x16x32_bf16 v[132:135], v[156:159], v[164:167], v[132:135]
	s_lshl_b64 s[10:11], s[10:11], 2
	s_add_u32 s10, s16, s10
	s_addc_u32 s11, s17, s11
	v_mfma_f32_16x16x32_bf16 v[140:143], v[148:151], v[164:167], v[140:143]
	s_lshl_b32 s20, s26, 2
	s_add_u32 s10, s10, s20
	s_addc_u32 s11, s11, 0
	v_mfma_f32_16x16x32_bf16 v[136:139], v[152:155], v[164:167], v[136:139]
	s_add_i32 s25, s25, s78
	s_add_i32 s24, s24, s71
	s_add_i32 s23, s23, s76
	v_mfma_f32_16x16x32_bf16 v[124:127], v[160:163], v[164:167], v[124:127]
	s_cmpk_gt_i32 s25, 0x1ff
	s_waitcnt lgkmcnt(6)
	v_mfma_f32_16x16x32_bf16 v[108:111], v[148:151], v[168:171], v[108:111]
	v_mfma_f32_16x16x32_bf16 v[104:107], v[152:155], v[168:171], v[104:107]
	v_mfma_f32_16x16x32_bf16 v[96:99], v[156:159], v[168:171], v[96:99]
	v_mfma_f32_16x16x32_bf16 v[92:95], v[160:163], v[168:171], v[92:95]
	s_waitcnt lgkmcnt(5)
	v_mfma_f32_16x16x32_bf16 v[88:91], v[148:151], v[172:175], v[88:91]
	v_mfma_f32_16x16x32_bf16 v[84:87], v[152:155], v[172:175], v[84:87]
	v_mfma_f32_16x16x32_bf16 v[80:83], v[156:159], v[172:175], v[80:83]
	v_mfma_f32_16x16x32_bf16 v[60:63], v[160:163], v[172:175], v[60:63]
	s_waitcnt lgkmcnt(4)
	v_mfma_f32_16x16x32_bf16 v[56:59], v[148:151], v[176:179], v[56:59]
	v_mfma_f32_16x16x32_bf16 v[52:55], v[152:155], v[176:179], v[52:55]
	v_mfma_f32_16x16x32_bf16 v[48:51], v[156:159], v[176:179], v[48:51]
	v_mfma_f32_16x16x32_bf16 v[44:47], v[160:163], v[176:179], v[44:47]
	s_waitcnt lgkmcnt(3)
	v_mfma_f32_16x16x32_bf16 v[40:43], v[148:151], v[180:183], v[40:43]
	v_mfma_f32_16x16x32_bf16 v[36:39], v[152:155], v[180:183], v[36:39]
	v_mfma_f32_16x16x32_bf16 v[32:35], v[156:159], v[180:183], v[32:35]
	v_mfma_f32_16x16x32_bf16 v[28:31], v[160:163], v[180:183], v[28:31]
	s_waitcnt lgkmcnt(2)
	v_mfma_f32_16x16x32_bf16 v[24:27], v[148:151], v[184:187], v[24:27]
	v_mfma_f32_16x16x32_bf16 v[20:23], v[152:155], v[184:187], v[20:23]
	v_mfma_f32_16x16x32_bf16 v[164:167], v[156:159], v[184:187], v[68:71]
	v_mfma_f32_16x16x32_bf16 v[168:171], v[160:163], v[184:187], v[64:67]
	s_waitcnt lgkmcnt(1)
	v_mfma_f32_16x16x32_bf16 v[172:175], v[148:151], v[188:191], v[72:75]
	v_mfma_f32_16x16x32_bf16 v[176:179], v[152:155], v[188:191], v[76:79]
	v_mfma_f32_16x16x32_bf16 v[180:183], v[156:159], v[188:191], v[128:131]
	v_mfma_f32_16x16x32_bf16 v[184:187], v[160:163], v[188:191], v[120:123]
	s_waitcnt lgkmcnt(0)
	v_mfma_f32_16x16x32_bf16 v[148:151], v[148:151], v[192:195], v[116:119]
	v_mfma_f32_16x16x32_bf16 v[152:155], v[152:155], v[192:195], v[112:115]
	v_mfma_f32_16x16x32_bf16 v[156:159], v[156:159], v[192:195], v[100:103]
	v_mfma_f32_16x16x32_bf16 v[144:147], v[160:163], v[192:195], v[144:147]
	ds_read_b128 v[160:163], v207 offset:32768
	ds_read_b128 v[188:191], v207 offset:34816
	ds_read_b128 v[192:195], v207 offset:40960
	ds_read_b128 v[196:199], v207 offset:43008
	ds_read_b128 v[64:67], v206
	ds_read_b128 v[68:71], v206 offset:2048
	ds_read_b128 v[72:75], v206 offset:4096
	ds_read_b128 v[76:79], v206 offset:6144
	ds_read_b128 v[200:203], v206 offset:8192
	ds_read_b128 v[216:219], v206 offset:10240
	ds_read_b128 v[220:223], v206 offset:12288
	ds_read_b128 v[204:207], v206 offset:14336
	s_waitcnt lgkmcnt(7)
; template <bool ACCUM, int MI>
; __device__ void gemm_tile_f32(const bf16_t* A, int lda, const bf16_t* B, int ldb, int K, float* C, int ldc, char* smem) {
;     ...
;   gemm_core<MI, false>(A, lda, B, ldb, K, smem, acc);
;   EPI_COORDS
; #pragma unroll
;   for (int i = 0; i < MI; ++i)
; #pragma unroll
;     for (int j = 0; j < 4; ++j) {
;       f32x4* cp = (f32x4*)(C + (size_t)MROW(i) * ldc + NCOL(j));
;       f32x4 v = acc[i][j];
;       if (ACCUM) v += *cp;
;       *cp = v;
;     }
	v_mfma_f32_16x16x32_bf16 v[224:227], v[192:195], v[64:67], v[132:135]
	v_mfma_f32_16x16x32_bf16 v[228:231], v[196:199], v[64:67], v[124:127]
	s_waitcnt lgkmcnt(6)
	v_mfma_f32_16x16x32_bf16 v[128:131], v[160:163], v[68:71], v[108:111]
	v_mfma_f32_16x16x32_bf16 v[124:127], v[188:191], v[68:71], v[104:107]
	s_waitcnt lgkmcnt(5)
	v_mfma_f32_16x16x32_bf16 v[112:115], v[160:163], v[72:75], v[88:91]
	v_mfma_f32_16x16x32_bf16 v[108:111], v[188:191], v[72:75], v[84:87]
	v_mfma_f32_16x16x32_bf16 v[104:107], v[192:195], v[72:75], v[80:83]
	v_mfma_f32_16x16x32_bf16 v[100:103], v[196:199], v[72:75], v[60:63]
	s_waitcnt lgkmcnt(3)
	v_mfma_f32_16x16x32_bf16 v[72:75], v[192:195], v[200:203], v[32:35]
	s_waitcnt lgkmcnt(0)
	v_mfma_f32_16x16x32_bf16 v[32:35], v[160:163], v[204:207], v[148:151]
	v_mfma_f32_16x16x32_bf16 v[60:63], v[188:191], v[216:219], v[20:23]
	v_mfma_f32_16x16x32_bf16 v[20:23], v[196:199], v[204:207], v[144:147]
	v_mfma_f32_16x16x32_bf16 v[140:143], v[160:163], v[64:67], v[140:143]
	v_mfma_f32_16x16x32_bf16 v[136:139], v[188:191], v[64:67], v[136:139]
	v_mfma_f32_16x16x32_bf16 v[120:123], v[192:195], v[68:71], v[96:99]
	v_mfma_f32_16x16x32_bf16 v[116:119], v[196:199], v[68:71], v[92:95]
	v_mfma_f32_16x16x32_bf16 v[96:99], v[160:163], v[76:79], v[56:59]
	v_mfma_f32_16x16x32_bf16 v[92:95], v[188:191], v[76:79], v[52:55]
	v_mfma_f32_16x16x32_bf16 v[88:91], v[192:195], v[76:79], v[48:51]
	v_mfma_f32_16x16x32_bf16 v[84:87], v[196:199], v[76:79], v[44:47]
	v_mfma_f32_16x16x32_bf16 v[80:83], v[160:163], v[200:203], v[40:43]
	v_mfma_f32_16x16x32_bf16 v[76:79], v[188:191], v[200:203], v[36:39]
	v_mfma_f32_16x16x32_bf16 v[68:71], v[196:199], v[200:203], v[28:31]
	v_mfma_f32_16x16x32_bf16 v[64:67], v[160:163], v[216:219], v[24:27]
	v_mfma_f32_16x16x32_bf16 v[56:59], v[192:195], v[216:219], v[164:167]
	v_mfma_f32_16x16x32_bf16 v[52:55], v[196:199], v[216:219], v[168:171]
	v_mfma_f32_16x16x32_bf16 v[48:51], v[160:163], v[220:223], v[172:175]
	v_mfma_f32_16x16x32_bf16 v[44:47], v[188:191], v[220:223], v[176:179]
	v_mfma_f32_16x16x32_bf16 v[40:43], v[192:195], v[220:223], v[180:183]
	v_mfma_f32_16x16x32_bf16 v[36:39], v[196:199], v[220:223], v[184:187]
	v_mfma_f32_16x16x32_bf16 v[28:31], v[188:191], v[204:207], v[152:155]
	v_mfma_f32_16x16x32_bf16 v[24:27], v[192:195], v[204:207], v[156:159]
	s_nop 7
	s_nop 7
	s_nop 7
	global_store_dwordx4 v237, v[140:143], s[98:99]
	global_store_dwordx4 v237, v[136:139], s[98:99] offset:64
	global_store_dwordx4 v237, v[224:227], s[98:99] offset:256
	global_store_dwordx4 v237, v[228:231], s[98:99] offset:320
	v_add_u32_e32 v237, 0x10000, v237
	global_store_dwordx4 v237, v[128:131], s[98:99]
	global_store_dwordx4 v237, v[124:127], s[98:99] offset:64
	global_store_dwordx4 v237, v[120:123], s[98:99] offset:256
	global_store_dwordx4 v237, v[116:119], s[98:99] offset:320
	v_add_u32_e32 v237, 0x10000, v237
	global_store_dwordx4 v237, v[112:115], s[98:99]
	global_store_dwordx4 v237, v[108:111], s[98:99] offset:64
	global_store_dwordx4 v237, v[104:107], s[98:99] offset:256
	global_store_dwordx4 v237, v[100:103], s[98:99] offset:320
	v_add_u32_e32 v237, 0x10000, v237
	global_store_dwordx4 v237, v[96:99], s[98:99]
	global_store_dwordx4 v237, v[92:95], s[98:99] offset:64
	global_store_dwordx4 v237, v[88:91], s[98:99] offset:256
	global_store_dwordx4 v237, v[84:87], s[98:99] offset:320
	v_add_u32_e32 v237, 0x10000, v237
	global_store_dwordx4 v237, v[80:83], s[98:99]
	global_store_dwordx4 v237, v[76:79], s[98:99] offset:64
	global_store_dwordx4 v237, v[72:75], s[98:99] offset:256
	global_store_dwordx4 v237, v[68:71], s[98:99] offset:320
	v_add_u32_e32 v237, 0x10000, v237
	global_store_dwordx4 v237, v[64:67], s[98:99]
	global_store_dwordx4 v237, v[60:63], s[98:99] offset:64
	global_store_dwordx4 v237, v[56:59], s[98:99] offset:256
	global_store_dwordx4 v237, v[52:55], s[98:99] offset:320
	v_add_u32_e32 v237, 0x10000, v237
	global_store_dwordx4 v237, v[48:51], s[98:99]
	global_store_dwordx4 v237, v[44:47], s[98:99] offset:64
	global_store_dwordx4 v237, v[40:43], s[98:99] offset:256
	global_store_dwordx4 v237, v[36:39], s[98:99] offset:320
	v_add_u32_e32 v237, 0x10000, v237
	global_store_dwordx4 v237, v[32:35], s[98:99]
	global_store_dwordx4 v237, v[28:31], s[98:99] offset:64
	global_store_dwordx4 v237, v[24:27], s[98:99] offset:256
	global_store_dwordx4 v237, v[20:23], s[98:99] offset:320
	s_cbranch_scc0 .LBB0_235

; template <int MI, bool SWAP, bool F8 = false>
; __device__ __forceinline__ void gemm_core(const bf16_t* __restrict__ A, int lda, const bf16_t* __restrict__ B, int ldb,
;                                           int K, char* smem, f32x4 (&acc)[MI][4]) {
;     ...
;   for (int kt = 0; kt < nk; ++kt) {
;     __syncthreads();
; #pragma unroll
;     for (int i = 0; i < MI; ++i) *(u32x4*)(smem + woff + i * 4096) = ra[i];
; #pragma unroll
;     for (int i = 0; i < 4; ++i) *(u32x4*)(smem + 32768 + woff + i * 4096) = rb[i];
;     __syncthreads();
;     if (kt + 1 < nk) {
; #pragma unroll
;       for (int i = 0; i < MI; ++i) ra[i] = *(const u32x4*)(ap + (size_t)(32 * i) * lda + (kt + 1) * 64);
; #pragma unroll
;       for (int i = 0; i < 4; ++i) rb[i] = *(const u32x4*)(bp + (size_t)(32 * i) * ldb + (kt + 1) * 64);
;     }
;     if (F8) {
;       const int c0 = (g ^ (li & 7)) << 4, c1 = ((4 + g) ^ (li & 7)) << 4;
;       i32x8 wf8[4];
; #pragma unroll
;       for (int j = 0; j < 4; ++j) {
;         const char* rp = smem + wrow + ((j & 1) * 16 + (j >> 1) * 64) * 128;
;         const u32x4 lo = *(const u32x4*)(rp + c0), hi = *(const u32x4*)(rp + c1);
;         wf8[j] = (i32x8){(int)lo.x, (int)lo.y, (int)lo.z, (int)lo.w, (int)hi.x, (int)hi.y, (int)hi.z, (int)hi.w};
;       }
; #pragma unroll
;       for (int i = 0; i < MI; ++i) {
;         const char* rp = smem + xrow + i * 2048;
;         const u32x4 lo = *(const u32x4*)(rp + c0), hi = *(const u32x4*)(rp + c1);
;         const i32x8 xf8 = {(int)lo.x, (int)lo.y, (int)lo.z, (int)lo.w, (int)hi.x, (int)hi.y, (int)hi.z, (int)hi.w};
; #pragma unroll
;         for (int j = 0; j < 4; ++j)
;           acc[i][j] = __builtin_amdgcn_mfma_scale_f32_16x16x128_f8f6f4(wf8[j], xf8, acc[i][j], 0, 0, 0, 0x77777777, 0, 0x7f7f7f7f);
;       }
;     } else {
; #pragma unroll
;     for (int kk = 0; kk < 2; ++kk) {
;       const int ch = ((kk * 4 + g) ^ (li & 7)) << 4;
;       bf16x8 xf[MI], wf[4];
; #pragma unroll
;       for (int j = 0; j < 4; ++j) wf[j] = *(const bf16x8*)(smem + wrow + ((j & 1) * 16 + (j >> 1) * 64) * 128 + ch);
; #pragma unroll
;       for (int i = 0; i < MI; ++i) xf[i] = *(const bf16x8*)(smem + xrow + i * 2048 + ch);
; #pragma unroll
;       for (int i = 0; i < MI; ++i)
; #pragma unroll
;         for (int j = 0; j < 4; ++j) {
.LBB0_301:
	v_add_u32_e32 v213, v204, v205
	s_barrier
	s_setprio 2
	s_mov_b32 m0, s62
	s_nop 0
	global_load_lds_dwordx4 v252, s[56:57]
	s_add_u32 m0, s62, 0x1000
	s_nop 0
	global_load_lds_dwordx4 v253, s[56:57]
	s_add_u32 s56, s56, 0x20000
	s_addc_u32 s57, s57, 0
	s_add_u32 m0, s62, 0x2000
	s_nop 0
	global_load_lds_dwordx4 v252, s[56:57]
	s_add_u32 m0, s62, 0x3000
	s_nop 0
	global_load_lds_dwordx4 v253, s[56:57]
	s_add_u32 s56, s56, 0x20000
	s_addc_u32 s57, s57, 0
	s_add_u32 m0, s62, 0x4000
	s_nop 0
	global_load_lds_dwordx4 v252, s[56:57]
	s_add_u32 m0, s62, 0x5000
	s_nop 0
	global_load_lds_dwordx4 v253, s[56:57]
	s_add_u32 s56, s56, 0x20000
	s_addc_u32 s57, s57, 0
	s_add_u32 m0, s62, 0x6000
	s_nop 0
	global_load_lds_dwordx4 v252, s[56:57]
	s_add_u32 m0, s62, 0x7000
	s_nop 0
	global_load_lds_dwordx4 v253, s[56:57]
	s_sub_u32 s56, s56, 0x60000
	s_subb_u32 s57, s57, 0
	s_add_u32 m0, s62, 0x8000
	s_nop 0
	global_load_lds_dwordx4 v252, s[58:59]
	s_add_u32 m0, s62, 0x9000
	s_nop 0
	global_load_lds_dwordx4 v253, s[58:59]
	s_add_u32 s58, s58, 0x20000
	s_addc_u32 s59, s59, 0
	s_add_u32 m0, s62, 0xa000
	s_nop 0
	global_load_lds_dwordx4 v252, s[58:59]
	s_add_u32 m0, s62, 0xb000
	s_nop 0
	global_load_lds_dwordx4 v253, s[58:59]
	s_sub_u32 s58, s58, 0x20000
	s_subb_u32 s59, s59, 0
	s_setprio 0
	v_add_u32_e32 v252, 0x80, v252
	v_add_u32_e32 v253, 0x80, v253
	s_waitcnt vmcnt(0)
	s_barrier
	v_add_u32_e32 v0, v203, v205
	ds_read_b128 v[136:139], v213 offset:32768
	ds_read_b128 v[144:147], v213 offset:34816
	ds_read_b128 v[152:155], v0
	ds_read_b128 v[156:159], v0 offset:2048
	ds_read_b128 v[164:167], v213 offset:40960
	ds_read_b128 v[168:171], v213 offset:43008
	s_waitcnt lgkmcnt(3)
	v_mfma_f32_16x16x32_bf16 v[148:151], v[136:139], v[152:155], v[148:151]
	v_add_u32_e32 v215, v204, v206
	v_add_u32_e32 v207, v203, v206
	v_mfma_f32_16x16x32_bf16 v[140:143], v[144:147], v[152:155], v[140:143]
	s_waitcnt lgkmcnt(1)
	v_mfma_f32_16x16x32_bf16 v[132:135], v[164:167], v[152:155], v[132:135]
	s_waitcnt lgkmcnt(0)
	v_mfma_f32_16x16x32_bf16 v[128:131], v[168:171], v[152:155], v[128:131]
	v_mfma_f32_16x16x32_bf16 v[124:127], v[136:139], v[156:159], v[124:127]
	v_mfma_f32_16x16x32_bf16 v[120:123], v[144:147], v[156:159], v[120:123]
	v_mfma_f32_16x16x32_bf16 v[116:119], v[164:167], v[156:159], v[116:119]
	v_mfma_f32_16x16x32_bf16 v[112:115], v[168:171], v[156:159], v[112:115]
	ds_read_b128 v[152:155], v0 offset:4096
	ds_read_b128 v[156:159], v0 offset:6144
	s_waitcnt lgkmcnt(1)
	v_mfma_f32_16x16x32_bf16 v[108:111], v[136:139], v[152:155], v[108:111]
	v_mfma_f32_16x16x32_bf16 v[104:107], v[144:147], v[152:155], v[104:107]
	v_mfma_f32_16x16x32_bf16 v[100:103], v[164:167], v[152:155], v[100:103]
	v_mfma_f32_16x16x32_bf16 v[96:99], v[168:171], v[152:155], v[96:99]
	s_waitcnt lgkmcnt(0)
	v_mfma_f32_16x16x32_bf16 v[92:95], v[136:139], v[156:159], v[92:95]
	v_mfma_f32_16x16x32_bf16 v[88:91], v[144:147], v[156:159], v[88:91]
	v_mfma_f32_16x16x32_bf16 v[84:87], v[164:167], v[156:159], v[84:87]
	v_mfma_f32_16x16x32_bf16 v[80:83], v[168:171], v[156:159], v[80:83]
	ds_read_b128 v[152:155], v0 offset:8192
	ds_read_b128 v[156:159], v0 offset:10240
	s_waitcnt lgkmcnt(1)
	v_mfma_f32_16x16x32_bf16 v[68:71], v[136:139], v[152:155], v[68:71]
	v_mfma_f32_16x16x32_bf16 v[64:67], v[144:147], v[152:155], v[64:67]
	v_mfma_f32_16x16x32_bf16 v[60:63], v[164:167], v[152:155], v[60:63]
	v_mfma_f32_16x16x32_bf16 v[56:59], v[168:171], v[152:155], v[56:59]
	s_waitcnt lgkmcnt(0)
	v_mfma_f32_16x16x32_bf16 v[48:51], v[136:139], v[156:159], v[48:51]
	v_mfma_f32_16x16x32_bf16 v[44:47], v[144:147], v[156:159], v[44:47]
	v_mfma_f32_16x16x32_bf16 v[40:43], v[164:167], v[156:159], v[40:43]
	v_mfma_f32_16x16x32_bf16 v[36:39], v[168:171], v[156:159], v[36:39]
	ds_read_b128 v[152:155], v0 offset:12288
	ds_read_b128 v[156:159], v0 offset:14336
	ds_read_b128 v[172:175], v215 offset:32768
	ds_read_b128 v[180:183], v215 offset:34816
	s_waitcnt lgkmcnt(3)
	v_mfma_f32_16x16x32_bf16 v[28:31], v[136:139], v[152:155], v[28:31]
	v_mfma_f32_16x16x32_bf16 v[24:27], v[144:147], v[152:155], v[24:27]
	v_mfma_f32_16x16x32_bf16 v[76:79], v[164:167], v[152:155], v[76:79]
	v_mfma_f32_16x16x32_bf16 v[72:75], v[168:171], v[152:155], v[72:75]
	s_waitcnt lgkmcnt(2)
	v_mfma_f32_16x16x32_bf16 v[52:55], v[136:139], v[156:159], v[52:55]
	v_mfma_f32_16x16x32_bf16 v[32:35], v[144:147], v[156:159], v[32:35]
	ds_read_b128 v[136:139], v207
	ds_read_b128 v[144:147], v207 offset:2048
	ds_read_b128 v[192:195], v215 offset:40960
	ds_read_b128 v[196:199], v215 offset:43008
	v_mfma_f32_16x16x32_bf16 v[20:23], v[164:167], v[156:159], v[20:23]
	v_mfma_f32_16x16x32_bf16 v[160:163], v[168:171], v[156:159], v[160:163]
	s_waitcnt lgkmcnt(3)
	v_mfma_f32_16x16x32_bf16 v[148:151], v[172:175], v[136:139], v[148:151]
	v_mfma_f32_16x16x32_bf16 v[140:143], v[180:183], v[136:139], v[140:143]
	s_waitcnt lgkmcnt(1)
	v_mfma_f32_16x16x32_bf16 v[132:135], v[192:195], v[136:139], v[132:135]
	s_waitcnt lgkmcnt(0)
	v_mfma_f32_16x16x32_bf16 v[128:131], v[196:199], v[136:139], v[128:131]
	v_mfma_f32_16x16x32_bf16 v[124:127], v[172:175], v[144:147], v[124:127]
	v_mfma_f32_16x16x32_bf16 v[120:123], v[180:183], v[144:147], v[120:123]
	v_mfma_f32_16x16x32_bf16 v[116:119], v[192:195], v[144:147], v[116:119]
	v_mfma_f32_16x16x32_bf16 v[112:115], v[196:199], v[144:147], v[112:115]
	ds_read_b128 v[136:139], v207 offset:4096
	ds_read_b128 v[144:147], v207 offset:6144
	s_waitcnt lgkmcnt(1)
; template <int MI, bool SWAP, bool F8 = false>
; __device__ __forceinline__ void gemm_core(const bf16_t* __restrict__ A, int lda, const bf16_t* __restrict__ B, int ldb,
;                                           int K, char* smem, f32x4 (&acc)[MI][4]) {
;     ...
;   for (int kt = 0; kt < nk; ++kt) {
;     __syncthreads();
; #pragma unroll
;     for (int i = 0; i < MI; ++i) *(u32x4*)(smem + woff + i * 4096) = ra[i];
; #pragma unroll
;     for (int i = 0; i < 4; ++i) *(u32x4*)(smem + 32768 + woff + i * 4096) = rb[i];
;     __syncthreads();
;     if (kt + 1 < nk) {
; #pragma unroll
;       for (int i = 0; i < MI; ++i) ra[i] = *(const u32x4*)(ap + (size_t)(32 * i) * lda + (kt + 1) * 64);
; #pragma unroll
;       for (int i = 0; i < 4; ++i) rb[i] = *(const u32x4*)(bp + (size_t)(32 * i) * ldb + (kt + 1) * 64);
;     }
;     if (F8) {
;       const int c0 = (g ^ (li & 7)) << 4, c1 = ((4 + g) ^ (li & 7)) << 4;
;       i32x8 wf8[4];
; #pragma unroll
;       for (int j = 0; j < 4; ++j) {
;         const char* rp = smem + wrow + ((j & 1) * 16 + (j >> 1) * 64) * 128;
;         const u32x4 lo = *(const u32x4*)(rp + c0), hi = *(const u32x4*)(rp + c1);
;         wf8[j] = (i32x8){(int)lo.x, (int)lo.y, (int)lo.z, (int)lo.w, (int)hi.x, (int)hi.y, (int)hi.z, (int)hi.w};
;       }
; #pragma unroll
;       for (int i = 0; i < MI; ++i) {
;         const char* rp = smem + xrow + i * 2048;
;         const u32x4 lo = *(const u32x4*)(rp + c0), hi = *(const u32x4*)(rp + c1);
;         const i32x8 xf8 = {(int)lo.x, (int)lo.y, (int)lo.z, (int)lo.w, (int)hi.x, (int)hi.y, (int)hi.z, (int)hi.w};
; #pragma unroll
;         for (int j = 0; j < 4; ++j)
;           acc[i][j] = __builtin_amdgcn_mfma_scale_f32_16x16x128_f8f6f4(wf8[j], xf8, acc[i][j], 0, 0, 0, 0x77777777, 0, 0x7f7f7f7f);
;       }
;     } else {
; #pragma unroll
;     for (int kk = 0; kk < 2; ++kk) {
;       const int ch = ((kk * 4 + g) ^ (li & 7)) << 4;
;       bf16x8 xf[MI], wf[4];
; #pragma unroll
;       for (int j = 0; j < 4; ++j) wf[j] = *(const bf16x8*)(smem + wrow + ((j & 1) * 16 + (j >> 1) * 64) * 128 + ch);
; #pragma unroll
;       for (int i = 0; i < MI; ++i) xf[i] = *(const bf16x8*)(smem + xrow + i * 2048 + ch);
; #pragma unroll
;       for (int i = 0; i < MI; ++i)
; #pragma unroll
;         for (int j = 0; j < 4; ++j) {
	v_mfma_f32_16x16x32_bf16 v[108:111], v[172:175], v[136:139], v[108:111]
	ds_read_b128 v[152:155], v207 offset:12288
	ds_read_b128 v[216:219], v207 offset:14336
	v_mfma_f32_16x16x32_bf16 v[104:107], v[180:183], v[136:139], v[104:107]
	v_mfma_f32_16x16x32_bf16 v[100:103], v[192:195], v[136:139], v[100:103]
	v_mfma_f32_16x16x32_bf16 v[96:99], v[196:199], v[136:139], v[96:99]
	ds_read_b128 v[136:139], v207 offset:8192
	s_waitcnt lgkmcnt(3)
	v_mfma_f32_16x16x32_bf16 v[92:95], v[172:175], v[144:147], v[92:95]
	v_mfma_f32_16x16x32_bf16 v[88:91], v[180:183], v[144:147], v[88:91]
	v_mfma_f32_16x16x32_bf16 v[84:87], v[192:195], v[144:147], v[84:87]
	v_mfma_f32_16x16x32_bf16 v[80:83], v[196:199], v[144:147], v[80:83]
	ds_read_b128 v[144:147], v207 offset:10240
	s_waitcnt lgkmcnt(1)
	v_mfma_f32_16x16x32_bf16 v[68:71], v[172:175], v[136:139], v[68:71]
	v_mfma_f32_16x16x32_bf16 v[64:67], v[180:183], v[136:139], v[64:67]
	v_mfma_f32_16x16x32_bf16 v[60:63], v[192:195], v[136:139], v[60:63]
	v_mfma_f32_16x16x32_bf16 v[56:59], v[196:199], v[136:139], v[56:59]
	s_waitcnt lgkmcnt(0)
	v_mfma_f32_16x16x32_bf16 v[48:51], v[172:175], v[144:147], v[48:51]
	v_mfma_f32_16x16x32_bf16 v[44:47], v[180:183], v[144:147], v[44:47]
	v_mfma_f32_16x16x32_bf16 v[40:43], v[192:195], v[144:147], v[40:43]
	v_mfma_f32_16x16x32_bf16 v[36:39], v[196:199], v[144:147], v[36:39]
	v_mfma_f32_16x16x32_bf16 v[28:31], v[172:175], v[152:155], v[28:31]
	v_mfma_f32_16x16x32_bf16 v[24:27], v[180:183], v[152:155], v[24:27]
	v_mfma_f32_16x16x32_bf16 v[76:79], v[192:195], v[152:155], v[76:79]
	v_mfma_f32_16x16x32_bf16 v[72:75], v[196:199], v[152:155], v[72:75]
	v_mfma_f32_16x16x32_bf16 v[52:55], v[172:175], v[216:219], v[52:55]
	v_mfma_f32_16x16x32_bf16 v[32:35], v[180:183], v[216:219], v[32:35]
	v_mfma_f32_16x16x32_bf16 v[20:23], v[192:195], v[216:219], v[20:23]
	v_mfma_f32_16x16x32_bf16 v[160:163], v[196:199], v[216:219], v[160:163]
	s_add_u32 s26, s26, 0x80
	s_addc_u32 s27, s27, 0
	s_cmpk_lg_i32 s26, 0x780
	s_cbranch_scc1 .LBB0_301
	s_barrier
	s_setprio 2
	s_mov_b32 m0, s62
	s_nop 0
	global_load_lds_dwordx4 v252, s[56:57]
	s_add_u32 m0, s62, 0x1000
	s_nop 0
	global_load_lds_dwordx4 v253, s[56:57]
	s_add_u32 s56, s56, 0x20000
	s_addc_u32 s57, s57, 0
	s_add_u32 m0, s62, 0x2000
	s_nop 0
	global_load_lds_dwordx4 v252, s[56:57]
	s_add_u32 m0, s62, 0x3000
	s_nop 0
	global_load_lds_dwordx4 v253, s[56:57]
	s_add_u32 s56, s56, 0x20000
	s_addc_u32 s57, s57, 0
	s_add_u32 m0, s62, 0x4000
	s_nop 0
	global_load_lds_dwordx4 v252, s[56:57]
	s_add_u32 m0, s62, 0x5000
	s_nop 0
	global_load_lds_dwordx4 v253, s[56:57]
	s_add_u32 s56, s56, 0x20000
	s_addc_u32 s57, s57, 0
	s_add_u32 m0, s62, 0x6000
	s_nop 0
	global_load_lds_dwordx4 v252, s[56:57]
	s_add_u32 m0, s62, 0x7000
	s_nop 0
	global_load_lds_dwordx4 v253, s[56:57]
	s_sub_u32 s56, s56, 0x60000
	s_subb_u32 s57, s57, 0
	s_add_u32 m0, s62, 0x8000
	s_nop 0
	global_load_lds_dwordx4 v252, s[58:59]
	s_add_u32 m0, s62, 0x9000
	s_nop 0
	global_load_lds_dwordx4 v253, s[58:59]
	s_add_u32 s58, s58, 0x20000
	s_addc_u32 s59, s59, 0
	s_add_u32 m0, s62, 0xa000
	s_nop 0
	global_load_lds_dwordx4 v252, s[58:59]
	s_add_u32 m0, s62, 0xb000
	s_nop 0
	global_load_lds_dwordx4 v253, s[58:59]
	s_sub_u32 s58, s58, 0x20000
	s_subb_u32 s59, s59, 0
	s_setprio 0
	s_waitcnt vmcnt(0)
	s_barrier
	v_bfe_u32 v12, v208, 4, 1
	v_mul_u32_u24_e32 v12, 24, v12
	v_mov_b32_e32 v13, 0
	ds_read_b128 v[136:139], v213 offset:32768
	ds_read_b128 v[144:147], v213 offset:34816
	ds_read_b128 v[152:155], v0
	ds_read_b128 v[156:159], v0 offset:2048
	ds_read_b128 v[164:167], v213 offset:40960
	ds_read_b128 v[168:171], v213 offset:43008
	s_waitcnt lgkmcnt(3)
	v_mfma_f32_16x16x32_bf16 v[148:151], v[136:139], v[152:155], v[148:151]
	s_cmp_eq_u32 s42, 6
	s_cselect_b64 s[26:27], -1, 0
	s_cmp_lg_u32 s42, 6
	v_mfma_f32_16x16x32_bf16 v[140:143], v[144:147], v[152:155], v[140:143]
	s_cselect_b64 s[30:31], -1, 0
	s_and_b64 vcc, exec, s[26:27]
	s_waitcnt lgkmcnt(1)
	v_mfma_f32_16x16x32_bf16 v[132:135], v[164:167], v[152:155], v[132:135]
	s_waitcnt lgkmcnt(0)
	v_mfma_f32_16x16x32_bf16 v[128:131], v[168:171], v[152:155], v[128:131]
	v_mfma_f32_16x16x32_bf16 v[172:175], v[136:139], v[156:159], v[124:127]
	s_nop 2
	ds_read_b128 v[124:127], v0 offset:4096
	ds_read_b128 v[152:155], v0 offset:6144
	s_waitcnt lgkmcnt(0)
	v_mfma_f32_16x16x32_bf16 v[176:179], v[164:167], v[152:155], v[84:87]
	v_mfma_f32_16x16x32_bf16 v[180:183], v[168:171], v[152:155], v[80:83]
	s_nop 2
	ds_read_b128 v[80:83], v0 offset:8192
	ds_read_b128 v[84:87], v0 offset:10240
	s_waitcnt lgkmcnt(1)
	v_mfma_f32_16x16x32_bf16 v[196:199], v[168:171], v[80:83], v[56:59]
	s_waitcnt lgkmcnt(0)
	v_mfma_f32_16x16x32_bf16 v[200:203], v[136:139], v[84:87], v[48:51]
	s_nop 2
	ds_read_b128 v[48:51], v0 offset:12288
	ds_read_b128 v[56:59], v0 offset:14336
	v_mfma_f32_16x16x32_bf16 v[116:119], v[164:167], v[156:159], v[116:119]
	v_mfma_f32_16x16x32_bf16 v[112:115], v[168:171], v[156:159], v[112:115]
	v_mfma_f32_16x16x32_bf16 v[100:103], v[164:167], v[124:127], v[100:103]
	v_mfma_f32_16x16x32_bf16 v[96:99], v[168:171], v[124:127], v[96:99]
	v_mfma_f32_16x16x32_bf16 v[192:195], v[164:167], v[80:83], v[60:63]
	v_mfma_f32_16x16x32_bf16 v[40:43], v[164:167], v[84:87], v[40:43]
	v_mfma_f32_16x16x32_bf16 v[36:39], v[168:171], v[84:87], v[36:39]
	s_waitcnt lgkmcnt(1)
	v_mfma_f32_16x16x32_bf16 v[28:31], v[136:139], v[48:51], v[28:31]
	v_mfma_f32_16x16x32_bf16 v[24:27], v[144:147], v[48:51], v[24:27]
	v_mfma_f32_16x16x32_bf16 v[76:79], v[164:167], v[48:51], v[76:79]
	v_mfma_f32_16x16x32_bf16 v[216:219], v[168:171], v[48:51], v[72:75]
	s_waitcnt lgkmcnt(0)
; template <int MI, bool SWAP, bool F8 = false>
; __device__ __forceinline__ void gemm_core(const bf16_t* __restrict__ A, int lda, const bf16_t* __restrict__ B, int ldb,
;                                           int K, char* smem, f32x4 (&acc)[MI][4]) {
;     ...
;           if (SWAP) acc[i][j] = __builtin_amdgcn_mfma_f32_16x16x32_bf16(xf[i], wf[j], acc[i][j], 0, 0, 0);
;           else acc[i][j] = __builtin_amdgcn_mfma_f32_16x16x32_bf16(wf[j], xf[i], acc[i][j], 0, 0, 0);
;         }
;     }
; __device__ void even_in_tile(const P& p, int li_even, int tm, int tn, char* smem) {
;     ...
;   if (seg != 6) {
;     const float* ctab = (const float*)(ws + OFF_COS);
;     const float* stab = (const float*)(ws + OFF_SIN);
; #pragma unroll
;     for (int i = 0; i < MI; ++i) {
;       const int s = s0 + MROW(i);
; #pragma unroll
;       for (int jj = 0; jj < 2; ++jj) {
;         const int d = wn * 32 + jj * 16 + g * 4;
;         const f32x4 c = *(const f32x4*)(ctab + s * 64 + d);
;         const f32x4 sn = *(const f32x4*)(stab + s * 64 + d);
	v_mfma_f32_16x16x32_bf16 v[224:227], v[144:147], v[56:59], v[32:35]
	v_mfma_f32_16x16x32_bf16 v[20:23], v[164:167], v[56:59], v[20:23]
	ds_read_b128 v[164:167], v215 offset:32768
	v_mfma_f32_16x16x32_bf16 v[160:163], v[168:171], v[56:59], v[160:163]
	ds_read_b128 v[168:171], v215 offset:34816
	ds_read_b128 v[32:35], v207
	ds_read_b128 v[48:51], v207 offset:2048
	ds_read_b128 v[228:231], v215 offset:40960
	ds_read_b128 v[232:235], v215 offset:43008
	v_mfma_f32_16x16x32_bf16 v[120:123], v[144:147], v[156:159], v[120:123]
	v_mov_b32_e32 v215, v208
	v_mfma_f32_16x16x32_bf16 v[108:111], v[136:139], v[124:127], v[108:111]
	v_mfma_f32_16x16x32_bf16 v[104:107], v[144:147], v[124:127], v[104:107]
	v_mfma_f32_16x16x32_bf16 v[92:95], v[136:139], v[152:155], v[92:95]
	v_mfma_f32_16x16x32_bf16 v[156:159], v[144:147], v[152:155], v[88:91]
	v_mfma_f32_16x16x32_bf16 v[184:187], v[136:139], v[80:83], v[68:71]
	v_mfma_f32_16x16x32_bf16 v[188:191], v[144:147], v[80:83], v[64:67]
	v_mfma_f32_16x16x32_bf16 v[44:47], v[144:147], v[84:87], v[44:47]
	v_mfma_f32_16x16x32_bf16 v[220:223], v[136:139], v[56:59], v[52:55]
	s_waitcnt lgkmcnt(3)
	v_mfma_f32_16x16x32_bf16 v[124:127], v[164:167], v[32:35], v[148:151]
	v_mfma_f32_16x16x32_bf16 v[150:153], v[168:171], v[32:35], v[140:143]
	s_waitcnt lgkmcnt(1)
	v_mfma_f32_16x16x32_bf16 v[88:91], v[228:231], v[32:35], v[132:135]
	s_waitcnt lgkmcnt(0)
	v_mfma_f32_16x16x32_bf16 v[84:87], v[232:235], v[32:35], v[128:131]
	v_mfma_f32_16x16x32_bf16 v[134:137], v[164:167], v[48:51], v[172:175]
	v_mfma_f32_16x16x32_bf16 v[138:141], v[168:171], v[48:51], v[120:123]
	v_mfma_f32_16x16x32_bf16 v[80:83], v[228:231], v[48:51], v[116:119]
	v_mfma_f32_16x16x32_bf16 v[72:75], v[232:235], v[48:51], v[112:115]
	ds_read_b128 v[32:35], v207 offset:4096
	ds_read_b128 v[48:51], v207 offset:6144
	s_waitcnt lgkmcnt(1)
	v_mfma_f32_16x16x32_bf16 v[142:145], v[164:167], v[32:35], v[108:111]
	v_mfma_f32_16x16x32_bf16 v[146:149], v[168:171], v[32:35], v[104:107]
	v_mfma_f32_16x16x32_bf16 v[68:71], v[228:231], v[32:35], v[100:103]
	v_mfma_f32_16x16x32_bf16 v[64:67], v[232:235], v[32:35], v[96:99]
	s_waitcnt lgkmcnt(0)
	v_mfma_f32_16x16x32_bf16 v[128:131], v[164:167], v[48:51], v[92:95]
	ds_read_b128 v[32:35], v207 offset:8192
	s_nop 1
	ds_read_b128 v[92:95], v207 offset:10240
	v_mfma_f32_16x16x32_bf16 v[120:123], v[168:171], v[48:51], v[156:159]
	v_mfma_f32_16x16x32_bf16 v[60:63], v[228:231], v[48:51], v[176:179]
	v_mfma_f32_16x16x32_bf16 v[56:59], v[232:235], v[48:51], v[180:183]
	s_waitcnt lgkmcnt(1)
	v_mfma_f32_16x16x32_bf16 v[112:115], v[164:167], v[32:35], v[184:187]
	v_mfma_f32_16x16x32_bf16 v[108:111], v[168:171], v[32:35], v[188:191]
	v_mfma_f32_16x16x32_bf16 v[52:55], v[228:231], v[32:35], v[192:195]
	v_mfma_f32_16x16x32_bf16 v[48:51], v[232:235], v[32:35], v[196:199]
	ds_read_b128 v[32:35], v207 offset:12288
	ds_read_b128 v[116:119], v207 offset:14336
	s_waitcnt lgkmcnt(2)
	v_mfma_f32_16x16x32_bf16 v[104:107], v[164:167], v[92:95], v[200:203]
	v_and_b32_e32 v213, 15, v215
	v_mfma_f32_16x16x32_bf16 v[100:103], v[168:171], v[92:95], v[44:47]
	v_mfma_f32_16x16x32_bf16 v[44:47], v[228:231], v[92:95], v[40:43]
	v_mfma_f32_16x16x32_bf16 v[40:43], v[232:235], v[92:95], v[36:39]
	s_waitcnt lgkmcnt(1)
	v_mfma_f32_16x16x32_bf16 v[96:99], v[164:167], v[32:35], v[28:31]
	v_mfma_f32_16x16x32_bf16 v[92:95], v[168:171], v[32:35], v[24:27]
	v_mfma_f32_16x16x32_bf16 v[36:39], v[228:231], v[32:35], v[76:79]
	v_mfma_f32_16x16x32_bf16 v[32:35], v[232:235], v[32:35], v[216:219]
	s_waitcnt lgkmcnt(0)
	v_mfma_f32_16x16x32_bf16 v[76:79], v[164:167], v[116:119], v[220:223]
	s_nop 0
	v_bfe_u32 v218, v215, 6, 1
	v_bfe_u32 v219, v215, 4, 2
	v_mfma_f32_16x16x32_bf16 v[28:31], v[168:171], v[116:119], v[224:227]
	v_mfma_f32_16x16x32_bf16 v[24:27], v[228:231], v[116:119], v[20:23]
	v_mfma_f32_16x16x32_bf16 v[20:23], v[232:235], v[116:119], v[160:163]
	s_cbranch_vccnz .LBB0_315
	v_and_b32_e32 v0, 0x3ffff80, v215
	v_add_u32_e32 v0, s41, v0
	s_add_u32 s34, s45, 0x4000
	v_or_b32_e32 v0, v0, v213
	s_addc_u32 s35, s48, 0
	v_lshlrev_b32_e32 v2, 6, v0
	s_add_u32 s36, s45, 0x104000
	v_ashrrev_i32_e32 v3, 31, v2
	s_addc_u32 s37, s48, 0
	v_lshlrev_b64 v[116:117], 2, v[2:3]
	v_lshlrev_b32_e32 v0, 4, v219
	v_lshl_add_u64 v[118:119], s[34:35], 0, v[116:117]
	v_lshl_add_u64 v[116:117], s[36:37], 0, v[116:117]
	v_lshl_or_b32 v0, v218, 7, v0
	v_lshl_add_u64 v[132:133], v[118:119], 0, v[0:1]
	v_lshl_add_u64 v[162:163], v[116:117], 0, v[0:1]
	v_lshl_add_u32 v236, v2, 2, v0
	global_load_dwordx4 v[164:167], v236, s[34:35]
	global_load_dwordx4 v[168:171], v236, s[36:37]
	global_load_dwordx4 v[172:175], v236, s[34:35] offset:64
	global_load_dwordx4 v[176:179], v236, s[36:37] offset:64
	v_add_u32_e32 v236, 0x1000, v236
	global_load_dwordx4 v[180:183], v236, s[34:35]
	global_load_dwordx4 v[184:187], v236, s[36:37]
	global_load_dwordx4 v[188:191], v236, s[34:35] offset:64
	global_load_dwordx4 v[192:195], v236, s[36:37] offset:64
	v_add_u32_e32 v236, 0x1000, v236
	global_load_dwordx4 v[196:199], v236, s[34:35]
	global_load_dwordx4 v[200:203], v236, s[36:37]
	global_load_dwordx4 v[204:207], v236, s[34:35] offset:64
	global_load_dwordx4 v[220:223], v236, s[36:37] offset:64
	v_add_u32_e32 v236, 0x1000, v236
	global_load_dwordx4 v[224:227], v236, s[34:35]
	global_load_dwordx4 v[228:231], v236, s[36:37]
	global_load_dwordx4 v[232:235], v236, s[34:35] offset:64
	global_load_dwordx4 v[4:7], v236, s[36:37] offset:64
	v_add_u32_e32 v236, 0x1000, v236
	s_waitcnt vmcnt(14)
; __device__ void even_in_tile(const P& p, int li_even, int tm, int tn, char* smem) {
;     ...
; #pragma unroll
;     for (int i = 0; i < MI; ++i) {
;       const int s = s0 + MROW(i);
; #pragma unroll
;       for (int jj = 0; jj < 2; ++jj) {
;         const int d = wn * 32 + jj * 16 + g * 4;
;         const f32x4 c = *(const f32x4*)(ctab + s * 64 + d);
;         const f32x4 sn = *(const f32x4*)(stab + s * 64 + d);
; #pragma unroll
;         for (int r = 0; r < 4; ++r) {
;           const float a = acc[i][jj][r], bb = acc[i][jj + 2][r];
;           acc[i][jj][r] = a * c[r] - bb * sn[r];
;           acc[i][jj + 2][r] = bb * c[r] + a * sn[r];
;         }
;       }
;     }
;   }
	v_mov_b32_e32 v154, v164
	v_mov_b32_e32 v155, v165
	v_mov_b32_e32 v156, v166
	v_mov_b32_e32 v157, v167
	v_mov_b32_e32 v158, v168
	v_mov_b32_e32 v159, v169
	v_mov_b32_e32 v160, v170
	v_mov_b32_e32 v161, v171
	global_load_dwordx4 v[164:167], v236, s[34:35]
	global_load_dwordx4 v[168:171], v236, s[36:37]
	v_pk_mul_f32 v[116:117], v[88:89], v[158:159]
	v_pk_mul_f32 v[118:119], v[124:125], v[158:159]
	v_pk_fma_f32 v[116:117], v[124:125], v[154:155], v[116:117] neg_lo:[0,0,1] neg_hi:[0,0,1]
	v_pk_fma_f32 v[88:89], v[88:89], v[154:155], v[118:119]
	v_mul_f32_e32 v118, v126, v156
	v_mul_f32_e32 v124, v90, v160
	v_mul_f32_e32 v154, v90, v156
	v_mul_f32_e32 v156, v126, v160
	v_mov_b32_e32 v90, v127
	v_mov_b32_e32 v160, v157
	v_mov_b32_e32 v126, v91
	v_pk_mul_f32 v[158:159], v[90:91], v[160:161]
	v_pk_mul_f32 v[90:91], v[126:127], v[160:161]
	v_mov_b32_e32 v119, v158
	v_mov_b32_e32 v155, v90
	v_mov_b32_e32 v157, v91
	v_mov_b32_e32 v125, v159
	v_pk_add_f32 v[90:91], v[154:155], v[156:157]
	v_pk_add_f32 v[118:119], v[118:119], v[124:125] neg_lo:[0,1] neg_hi:[0,1]
	s_waitcnt vmcnt(14)
	v_mov_b32_e32 v154, v172
	v_mov_b32_e32 v155, v173
	v_mov_b32_e32 v156, v174
	v_mov_b32_e32 v157, v175
	v_mov_b32_e32 v158, v176
	v_mov_b32_e32 v159, v177
	v_mov_b32_e32 v160, v178
	v_mov_b32_e32 v161, v179
	global_load_dwordx4 v[172:175], v236, s[34:35] offset:64
	global_load_dwordx4 v[176:179], v236, s[36:37] offset:64
	v_add_u32_e32 v236, 0x1000, v236
	v_pk_mul_f32 v[124:125], v[84:85], v[158:159]
	v_pk_mul_f32 v[126:127], v[150:151], v[158:159]
	v_pk_fma_f32 v[124:125], v[150:151], v[154:155], v[124:125] neg_lo:[0,0,1] neg_hi:[0,0,1]
	v_pk_fma_f32 v[84:85], v[84:85], v[154:155], v[126:127]
	v_mul_f32_e32 v132, v86, v160
	v_mul_f32_e32 v150, v86, v156
	v_mul_f32_e32 v154, v152, v160
	v_mov_b32_e32 v86, v153
	v_mov_b32_e32 v160, v157
	v_mul_f32_e32 v126, v152, v156
	v_pk_mul_f32 v[156:157], v[86:87], v[160:161]
	v_mov_b32_e32 v152, v87
	v_mov_b32_e32 v127, v156
	v_mov_b32_e32 v133, v157
	v_pk_add_f32 v[126:127], v[126:127], v[132:133] neg_lo:[0,1] neg_hi:[0,1]
	v_or_b32_e32 v132, 0x400, v2
	v_pk_mul_f32 v[86:87], v[152:153], v[160:161]
	v_ashrrev_i32_e32 v133, 31, v132
	v_mov_b32_e32 v151, v86
	v_mov_b32_e32 v155, v87
	v_lshlrev_b64 v[132:133], 2, v[132:133]
	v_pk_add_f32 v[86:87], v[150:151], v[154:155]
	v_lshl_add_u64 v[150:151], s[34:35], 0, v[132:133]
	v_lshl_add_u64 v[132:133], s[36:37], 0, v[132:133]
	v_lshl_add_u64 v[158:159], v[150:151], 0, v[0:1]
	v_lshl_add_u64 v[160:161], v[132:133], 0, v[0:1]
	s_waitcnt vmcnt(14)
	v_mov_b32_e32 v150, v180
	v_mov_b32_e32 v151, v181
	v_mov_b32_e32 v152, v182
	v_mov_b32_e32 v153, v183
	v_mov_b32_e32 v154, v184
	v_mov_b32_e32 v155, v185
	v_mov_b32_e32 v156, v186
	v_mov_b32_e32 v157, v187
	global_load_dwordx4 v[180:183], v236, s[34:35]
	global_load_dwordx4 v[184:187], v236, s[36:37]
	v_pk_mul_f32 v[132:133], v[80:81], v[154:155]
	s_nop 0
	v_pk_fma_f32 v[132:133], v[134:135], v[150:151], v[132:133] neg_lo:[0,0,1] neg_hi:[0,0,1]
	v_pk_mul_f32 v[134:135], v[134:135], v[154:155]
	v_mul_f32_e32 v154, v136, v156
	v_pk_fma_f32 v[80:81], v[80:81], v[150:151], v[134:135]
	v_mul_f32_e32 v134, v136, v152
	v_mul_f32_e32 v150, v82, v156
	v_mul_f32_e32 v152, v82, v152
	v_mov_b32_e32 v82, v137
	v_mov_b32_e32 v156, v153
	v_mov_b32_e32 v136, v83
	v_pk_mul_f32 v[162:163], v[82:83], v[156:157]
	v_pk_mul_f32 v[82:83], v[136:137], v[156:157]
	v_mov_b32_e32 v135, v162
	v_mov_b32_e32 v151, v163
	v_mov_b32_e32 v153, v82
	v_mov_b32_e32 v155, v83
	v_pk_add_f32 v[134:135], v[134:135], v[150:151] neg_lo:[0,1] neg_hi:[0,1]
	v_pk_add_f32 v[82:83], v[152:153], v[154:155]
	s_waitcnt vmcnt(14)
	v_mov_b32_e32 v150, v188
	v_mov_b32_e32 v151, v189
	v_mov_b32_e32 v152, v190
	v_mov_b32_e32 v153, v191
	v_mov_b32_e32 v154, v192
	v_mov_b32_e32 v155, v193
	v_mov_b32_e32 v156, v194
	v_mov_b32_e32 v157, v195
	global_load_dwordx4 v[188:191], v236, s[34:35] offset:64
	global_load_dwordx4 v[192:195], v236, s[36:37] offset:64
	v_add_u32_e32 v236, 0x1000, v236
	v_pk_mul_f32 v[136:137], v[72:73], v[154:155]
	s_nop 0
	v_pk_fma_f32 v[136:137], v[138:139], v[150:151], v[136:137] neg_lo:[0,0,1] neg_hi:[0,0,1]
	v_pk_mul_f32 v[138:139], v[138:139], v[154:155]
	v_mul_f32_e32 v154, v140, v156
	v_pk_fma_f32 v[72:73], v[72:73], v[150:151], v[138:139]
	v_mul_f32_e32 v138, v140, v152
	v_mul_f32_e32 v150, v74, v156
	v_mul_f32_e32 v152, v74, v152
	v_mov_b32_e32 v74, v141
	v_mov_b32_e32 v156, v153
	v_mov_b32_e32 v140, v75
	v_pk_mul_f32 v[158:159], v[74:75], v[156:157]
	v_pk_mul_f32 v[74:75], v[140:141], v[156:157]
	v_or_b32_e32 v140, 0x800, v2
	v_ashrrev_i32_e32 v141, 31, v140
	v_mov_b32_e32 v139, v158
	v_mov_b32_e32 v151, v159
	v_lshlrev_b64 v[140:141], 2, v[140:141]
	v_pk_add_f32 v[138:139], v[138:139], v[150:151] neg_lo:[0,1] neg_hi:[0,1]
	v_lshl_add_u64 v[150:151], s[34:35], 0, v[140:141]
	v_lshl_add_u64 v[140:141], s[36:37], 0, v[140:141]
	v_mov_b32_e32 v153, v74
	v_mov_b32_e32 v155, v75
	v_lshl_add_u64 v[158:159], v[150:151], 0, v[0:1]
	v_lshl_add_u64 v[160:161], v[140:141], 0, v[0:1]
	v_pk_add_f32 v[74:75], v[152:153], v[154:155]
	s_waitcnt vmcnt(14)
; __device__ void even_in_tile(const P& p, int li_even, int tm, int tn, char* smem) {
;     ...
; #pragma unroll
;     for (int i = 0; i < MI; ++i) {
;       const int s = s0 + MROW(i);
; #pragma unroll
;       for (int jj = 0; jj < 2; ++jj) {
;         const int d = wn * 32 + jj * 16 + g * 4;
;         const f32x4 c = *(const f32x4*)(ctab + s * 64 + d);
;         const f32x4 sn = *(const f32x4*)(stab + s * 64 + d);
; #pragma unroll
;         for (int r = 0; r < 4; ++r) {
;           const float a = acc[i][jj][r], bb = acc[i][jj + 2][r];
;           acc[i][jj][r] = a * c[r] - bb * sn[r];
;           acc[i][jj + 2][r] = bb * c[r] + a * sn[r];
;         }
;       }
;     }
;   }
	v_mov_b32_e32 v150, v196
	v_mov_b32_e32 v151, v197
	v_mov_b32_e32 v152, v198
	v_mov_b32_e32 v153, v199
	v_mov_b32_e32 v154, v200
	v_mov_b32_e32 v155, v201
	v_mov_b32_e32 v156, v202
	v_mov_b32_e32 v157, v203
	global_load_dwordx4 v[196:199], v236, s[34:35]
	global_load_dwordx4 v[200:203], v236, s[36:37]
	v_pk_mul_f32 v[140:141], v[68:69], v[154:155]
	s_nop 0
	v_pk_fma_f32 v[140:141], v[142:143], v[150:151], v[140:141] neg_lo:[0,0,1] neg_hi:[0,0,1]
	v_pk_mul_f32 v[142:143], v[142:143], v[154:155]
	v_mul_f32_e32 v154, v144, v156
	v_pk_fma_f32 v[68:69], v[68:69], v[150:151], v[142:143]
	v_mul_f32_e32 v142, v144, v152
	v_mul_f32_e32 v150, v70, v156
	v_mul_f32_e32 v152, v70, v152
	v_mov_b32_e32 v70, v145
	v_mov_b32_e32 v156, v153
	v_mov_b32_e32 v144, v71
	v_pk_mul_f32 v[162:163], v[70:71], v[156:157]
	v_pk_mul_f32 v[70:71], v[144:145], v[156:157]
	v_mov_b32_e32 v143, v162
	v_mov_b32_e32 v151, v163
	v_mov_b32_e32 v153, v70
	v_mov_b32_e32 v155, v71
	v_pk_add_f32 v[142:143], v[142:143], v[150:151] neg_lo:[0,1] neg_hi:[0,1]
	v_pk_add_f32 v[70:71], v[152:153], v[154:155]
	s_waitcnt vmcnt(14)
	v_mov_b32_e32 v150, v204
	v_mov_b32_e32 v151, v205
	v_mov_b32_e32 v152, v206
	v_mov_b32_e32 v153, v207
	v_mov_b32_e32 v154, v220
	v_mov_b32_e32 v155, v221
	v_mov_b32_e32 v156, v222
	v_mov_b32_e32 v157, v223
	global_load_dwordx4 v[204:207], v236, s[34:35] offset:64
	global_load_dwordx4 v[220:223], v236, s[36:37] offset:64
	v_add_u32_e32 v236, 0x1000, v236
	v_pk_mul_f32 v[144:145], v[64:65], v[154:155]
	s_nop 0
	v_pk_fma_f32 v[144:145], v[146:147], v[150:151], v[144:145] neg_lo:[0,0,1] neg_hi:[0,0,1]
	v_pk_mul_f32 v[146:147], v[146:147], v[154:155]
	v_mul_f32_e32 v154, v148, v156
	v_pk_fma_f32 v[64:65], v[64:65], v[150:151], v[146:147]
	v_mul_f32_e32 v146, v148, v152
	v_mul_f32_e32 v150, v66, v156
	v_mul_f32_e32 v152, v66, v152
	v_mov_b32_e32 v66, v149
	v_mov_b32_e32 v156, v153
	v_mov_b32_e32 v148, v67
	v_pk_mul_f32 v[158:159], v[66:67], v[156:157]
	v_pk_mul_f32 v[66:67], v[148:149], v[156:157]
	v_or_b32_e32 v148, 0xc00, v2
	v_ashrrev_i32_e32 v149, 31, v148
	v_mov_b32_e32 v147, v158
	v_mov_b32_e32 v151, v159
	v_lshlrev_b64 v[148:149], 2, v[148:149]
	v_pk_add_f32 v[146:147], v[146:147], v[150:151] neg_lo:[0,1] neg_hi:[0,1]
	v_lshl_add_u64 v[150:151], s[34:35], 0, v[148:149]
	v_lshl_add_u64 v[148:149], s[36:37], 0, v[148:149]
	v_mov_b32_e32 v153, v66
	v_mov_b32_e32 v155, v67
	v_lshl_add_u64 v[158:159], v[150:151], 0, v[0:1]
	v_lshl_add_u64 v[160:161], v[148:149], 0, v[0:1]
	v_pk_add_f32 v[66:67], v[152:153], v[154:155]
	s_waitcnt vmcnt(14)
	v_mov_b32_e32 v150, v224
	v_mov_b32_e32 v151, v225
	v_mov_b32_e32 v152, v226
	v_mov_b32_e32 v153, v227
	v_mov_b32_e32 v154, v228
	v_mov_b32_e32 v155, v229
	v_mov_b32_e32 v156, v230
	v_mov_b32_e32 v157, v231
	global_load_dwordx4 v[224:227], v236, s[34:35]
	global_load_dwordx4 v[228:231], v236, s[36:37]
	v_pk_mul_f32 v[148:149], v[60:61], v[154:155]
	s_nop 0
	v_pk_fma_f32 v[148:149], v[128:129], v[150:151], v[148:149] neg_lo:[0,0,1] neg_hi:[0,0,1]
	v_pk_mul_f32 v[128:129], v[128:129], v[154:155]
	v_mul_f32_e32 v154, v130, v156
	v_pk_fma_f32 v[60:61], v[60:61], v[150:151], v[128:129]
	v_mul_f32_e32 v128, v130, v152
	v_mul_f32_e32 v150, v62, v156
	v_mul_f32_e32 v152, v62, v152
	v_mov_b32_e32 v62, v131
	v_mov_b32_e32 v156, v153
	v_mov_b32_e32 v130, v63
	v_pk_mul_f32 v[162:163], v[62:63], v[156:157]
	v_pk_mul_f32 v[62:63], v[130:131], v[156:157]
	v_mov_b32_e32 v129, v162
	v_mov_b32_e32 v153, v62
	v_mov_b32_e32 v155, v63
	v_pk_add_f32 v[62:63], v[152:153], v[154:155]
	s_nop 0
	v_mov_b32_e32 v151, v163
	v_pk_add_f32 v[150:151], v[128:129], v[150:151] neg_lo:[0,1] neg_hi:[0,1]
	s_waitcnt vmcnt(14)
	v_mov_b32_e32 v152, v232
	v_mov_b32_e32 v153, v233
	v_mov_b32_e32 v154, v234
	v_mov_b32_e32 v155, v235
	v_mov_b32_e32 v156, v4
	v_mov_b32_e32 v157, v5
	v_mov_b32_e32 v158, v6
	v_mov_b32_e32 v159, v7
	global_load_dwordx4 v[232:235], v236, s[34:35] offset:64
	global_load_dwordx4 v[4:7], v236, s[36:37] offset:64
	v_pk_mul_f32 v[128:129], v[56:57], v[156:157]
	s_nop 0
	v_pk_fma_f32 v[128:129], v[120:121], v[152:153], v[128:129] neg_lo:[0,0,1] neg_hi:[0,0,1]
	v_pk_mul_f32 v[120:121], v[120:121], v[156:157]
	v_mul_f32_e32 v130, v58, v158
	v_pk_fma_f32 v[56:57], v[56:57], v[152:153], v[120:121]
	v_mul_f32_e32 v120, v122, v154
	v_mul_f32_e32 v152, v58, v154
	v_mul_f32_e32 v154, v122, v158
	v_mov_b32_e32 v58, v123
	v_mov_b32_e32 v158, v155
	v_pk_mul_f32 v[156:157], v[58:59], v[158:159]
	v_mov_b32_e32 v122, v59
	v_mov_b32_e32 v121, v156
	v_mov_b32_e32 v131, v157
	v_pk_add_f32 v[130:131], v[120:121], v[130:131] neg_lo:[0,1] neg_hi:[0,1]
	v_or_b32_e32 v120, 0x1000, v2
	v_ashrrev_i32_e32 v121, 31, v120
	v_lshlrev_b64 v[120:121], 2, v[120:121]
	v_pk_mul_f32 v[58:59], v[122:123], v[158:159]
	v_lshl_add_u64 v[122:123], s[34:35], 0, v[120:121]
	v_lshl_add_u64 v[120:121], s[36:37], 0, v[120:121]
	v_mov_b32_e32 v153, v58
	v_mov_b32_e32 v155, v59
	v_lshl_add_u64 v[160:161], v[122:123], 0, v[0:1]
	v_lshl_add_u64 v[162:163], v[120:121], 0, v[0:1]
	v_pk_add_f32 v[58:59], v[152:153], v[154:155]
	s_waitcnt vmcnt(14)
	v_mov_b32_e32 v152, v164
	v_mov_b32_e32 v153, v165
	v_mov_b32_e32 v154, v166
	v_mov_b32_e32 v155, v167
	v_mov_b32_e32 v156, v168
	v_mov_b32_e32 v157, v169
	v_mov_b32_e32 v158, v170
	v_mov_b32_e32 v159, v171
	v_pk_mul_f32 v[120:121], v[52:53], v[156:157]
	s_nop 0
	v_pk_fma_f32 v[120:121], v[112:113], v[152:153], v[120:121] neg_lo:[0,0,1] neg_hi:[0,0,1]
	v_pk_mul_f32 v[112:113], v[112:113], v[156:157]
	v_mul_f32_e32 v122, v54, v158
	v_pk_fma_f32 v[52:53], v[52:53], v[152:153], v[112:113]
	v_mul_f32_e32 v112, v114, v154
	v_mul_f32_e32 v152, v54, v154
	v_mul_f32_e32 v154, v114, v158
	v_mov_b32_e32 v54, v115
	v_mov_b32_e32 v158, v155
	v_mov_b32_e32 v114, v55
	v_pk_mul_f32 v[156:157], v[54:55], v[158:159]
	v_pk_mul_f32 v[54:55], v[114:115], v[158:159]
	v_mov_b32_e32 v113, v156
	v_mov_b32_e32 v153, v54
	v_mov_b32_e32 v155, v55
	v_mov_b32_e32 v123, v157
	v_pk_add_f32 v[54:55], v[152:153], v[154:155]
	v_pk_add_f32 v[122:123], v[112:113], v[122:123] neg_lo:[0,1] neg_hi:[0,1]
	s_waitcnt vmcnt(12)
; __device__ void even_in_tile(const P& p, int li_even, int tm, int tn, char* smem) {
;     ...
; #pragma unroll
;     for (int i = 0; i < MI; ++i) {
;       const int s = s0 + MROW(i);
; #pragma unroll
;       for (int jj = 0; jj < 2; ++jj) {
;         const int d = wn * 32 + jj * 16 + g * 4;
;         const f32x4 c = *(const f32x4*)(ctab + s * 64 + d);
;         const f32x4 sn = *(const f32x4*)(stab + s * 64 + d);
; #pragma unroll
;         for (int r = 0; r < 4; ++r) {
;           const float a = acc[i][jj][r], bb = acc[i][jj + 2][r];
;           acc[i][jj][r] = a * c[r] - bb * sn[r];
;           acc[i][jj + 2][r] = bb * c[r] + a * sn[r];
;         }
;       }
;     }
;   }
	v_mov_b32_e32 v152, v172
	v_mov_b32_e32 v153, v173
	v_mov_b32_e32 v154, v174
	v_mov_b32_e32 v155, v175
	v_mov_b32_e32 v156, v176
	v_mov_b32_e32 v157, v177
	v_mov_b32_e32 v158, v178
	v_mov_b32_e32 v159, v179
	v_pk_mul_f32 v[112:113], v[48:49], v[156:157]
	s_nop 0
	v_pk_fma_f32 v[112:113], v[108:109], v[152:153], v[112:113] neg_lo:[0,0,1] neg_hi:[0,0,1]
	v_pk_mul_f32 v[108:109], v[108:109], v[156:157]
	v_mul_f32_e32 v114, v50, v158
	v_pk_fma_f32 v[48:49], v[48:49], v[152:153], v[108:109]
	v_mul_f32_e32 v108, v110, v154
	v_mul_f32_e32 v152, v50, v154
	v_mul_f32_e32 v154, v110, v158
	v_mov_b32_e32 v50, v111
	v_mov_b32_e32 v158, v155
	v_pk_mul_f32 v[156:157], v[50:51], v[158:159]
	v_mov_b32_e32 v110, v51
	v_mov_b32_e32 v109, v156
	v_mov_b32_e32 v115, v157
	v_pk_add_f32 v[114:115], v[108:109], v[114:115] neg_lo:[0,1] neg_hi:[0,1]
	v_or_b32_e32 v108, 0x1400, v2
	v_ashrrev_i32_e32 v109, 31, v108
	v_lshlrev_b64 v[108:109], 2, v[108:109]
	v_pk_mul_f32 v[50:51], v[110:111], v[158:159]
	v_lshl_add_u64 v[110:111], s[34:35], 0, v[108:109]
	v_lshl_add_u64 v[108:109], s[36:37], 0, v[108:109]
	v_mov_b32_e32 v153, v50
	v_mov_b32_e32 v155, v51
	v_lshl_add_u64 v[160:161], v[110:111], 0, v[0:1]
	v_lshl_add_u64 v[162:163], v[108:109], 0, v[0:1]
	v_pk_add_f32 v[50:51], v[152:153], v[154:155]
	s_waitcnt vmcnt(10)
	v_mov_b32_e32 v152, v180
	v_mov_b32_e32 v153, v181
	v_mov_b32_e32 v154, v182
	v_mov_b32_e32 v155, v183
	v_mov_b32_e32 v156, v184
	v_mov_b32_e32 v157, v185
	v_mov_b32_e32 v158, v186
	v_mov_b32_e32 v159, v187
	v_pk_mul_f32 v[108:109], v[44:45], v[156:157]
	s_nop 0
	v_pk_fma_f32 v[108:109], v[104:105], v[152:153], v[108:109] neg_lo:[0,0,1] neg_hi:[0,0,1]
	v_pk_mul_f32 v[104:105], v[104:105], v[156:157]
	v_mul_f32_e32 v110, v46, v158
	v_pk_fma_f32 v[44:45], v[44:45], v[152:153], v[104:105]
	v_mul_f32_e32 v104, v106, v154
	v_mul_f32_e32 v152, v46, v154
	v_mul_f32_e32 v154, v106, v158
	v_mov_b32_e32 v46, v107
	v_mov_b32_e32 v158, v155
	v_mov_b32_e32 v106, v47
	v_pk_mul_f32 v[156:157], v[46:47], v[158:159]
	v_pk_mul_f32 v[46:47], v[106:107], v[158:159]
	v_mov_b32_e32 v105, v156
	v_mov_b32_e32 v153, v46
	v_mov_b32_e32 v155, v47
	v_mov_b32_e32 v111, v157
	v_pk_add_f32 v[46:47], v[152:153], v[154:155]
	v_pk_add_f32 v[110:111], v[104:105], v[110:111] neg_lo:[0,1] neg_hi:[0,1]
	s_waitcnt vmcnt(8)
	v_mov_b32_e32 v152, v188
	v_mov_b32_e32 v153, v189
	v_mov_b32_e32 v154, v190
	v_mov_b32_e32 v155, v191
	v_mov_b32_e32 v156, v192
	v_mov_b32_e32 v157, v193
	v_mov_b32_e32 v158, v194
	v_mov_b32_e32 v159, v195
	v_pk_mul_f32 v[104:105], v[40:41], v[156:157]
	s_nop 0
	v_pk_fma_f32 v[104:105], v[100:101], v[152:153], v[104:105] neg_lo:[0,0,1] neg_hi:[0,0,1]
	v_pk_mul_f32 v[100:101], v[100:101], v[156:157]
	v_mul_f32_e32 v106, v42, v158
	v_pk_fma_f32 v[40:41], v[40:41], v[152:153], v[100:101]
	v_mul_f32_e32 v100, v102, v154
	v_mul_f32_e32 v152, v42, v154
	v_mul_f32_e32 v154, v102, v158
	v_mov_b32_e32 v42, v103
	v_mov_b32_e32 v158, v155
	v_pk_mul_f32 v[156:157], v[42:43], v[158:159]
	v_mov_b32_e32 v102, v43
	v_mov_b32_e32 v101, v156
	v_mov_b32_e32 v107, v157
	v_pk_add_f32 v[106:107], v[100:101], v[106:107] neg_lo:[0,1] neg_hi:[0,1]
	v_or_b32_e32 v100, 0x1800, v2
	v_ashrrev_i32_e32 v101, 31, v100
	v_lshlrev_b64 v[100:101], 2, v[100:101]
	v_pk_mul_f32 v[42:43], v[102:103], v[158:159]
	v_lshl_add_u64 v[102:103], s[34:35], 0, v[100:101]
	v_lshl_add_u64 v[100:101], s[36:37], 0, v[100:101]
	v_mov_b32_e32 v153, v42
	v_mov_b32_e32 v155, v43
	v_lshl_add_u64 v[160:161], v[102:103], 0, v[0:1]
	v_lshl_add_u64 v[162:163], v[100:101], 0, v[0:1]
	v_pk_add_f32 v[42:43], v[152:153], v[154:155]
	v_or_b32_e32 v2, 0x1c00, v2
	v_ashrrev_i32_e32 v3, 31, v2
	v_lshlrev_b64 v[2:3], 2, v[2:3]
	s_waitcnt vmcnt(6)
	v_mov_b32_e32 v152, v196
	v_mov_b32_e32 v153, v197
	v_mov_b32_e32 v154, v198
	v_mov_b32_e32 v155, v199
	v_mov_b32_e32 v156, v200
	v_mov_b32_e32 v157, v201
	v_mov_b32_e32 v158, v202
	v_mov_b32_e32 v159, v203
	v_pk_mul_f32 v[100:101], v[36:37], v[156:157]
	s_nop 0
	v_pk_fma_f32 v[100:101], v[96:97], v[152:153], v[100:101] neg_lo:[0,0,1] neg_hi:[0,0,1]
	v_pk_mul_f32 v[96:97], v[96:97], v[156:157]
	v_mul_f32_e32 v102, v38, v158
	v_pk_fma_f32 v[36:37], v[36:37], v[152:153], v[96:97]
	v_mul_f32_e32 v96, v98, v154
	v_mul_f32_e32 v152, v38, v154
	v_mul_f32_e32 v154, v98, v158
	v_mov_b32_e32 v38, v99
	v_mov_b32_e32 v158, v155
	v_mov_b32_e32 v98, v39
	v_pk_mul_f32 v[156:157], v[38:39], v[158:159]
	v_pk_mul_f32 v[38:39], v[98:99], v[158:159]
	v_mov_b32_e32 v97, v156
	v_mov_b32_e32 v153, v38
	v_mov_b32_e32 v155, v39
	v_mov_b32_e32 v103, v157
	v_pk_add_f32 v[38:39], v[152:153], v[154:155]
	v_pk_add_f32 v[102:103], v[96:97], v[102:103] neg_lo:[0,1] neg_hi:[0,1]
	s_waitcnt vmcnt(4)
; __device__ void even_in_tile(const P& p, int li_even, int tm, int tn, char* smem) {
;     ...
; #pragma unroll
;     for (int i = 0; i < MI; ++i) {
;       const int s = s0 + MROW(i);
; #pragma unroll
;       for (int jj = 0; jj < 2; ++jj) {
;         const int d = wn * 32 + jj * 16 + g * 4;
;         const f32x4 c = *(const f32x4*)(ctab + s * 64 + d);
;         const f32x4 sn = *(const f32x4*)(stab + s * 64 + d);
; #pragma unroll
;         for (int r = 0; r < 4; ++r) {
;           const float a = acc[i][jj][r], bb = acc[i][jj + 2][r];
;           acc[i][jj][r] = a * c[r] - bb * sn[r];
;           acc[i][jj + 2][r] = bb * c[r] + a * sn[r];
;         }
;       }
;     }
;   }
;   if (seg == 1) {
	v_mov_b32_e32 v152, v204
	v_mov_b32_e32 v153, v205
	v_mov_b32_e32 v154, v206
	v_mov_b32_e32 v155, v207
	v_mov_b32_e32 v156, v220
	v_mov_b32_e32 v157, v221
	v_mov_b32_e32 v158, v222
	v_mov_b32_e32 v159, v223
	v_pk_mul_f32 v[96:97], v[32:33], v[156:157]
	s_nop 0
	v_pk_fma_f32 v[96:97], v[92:93], v[152:153], v[96:97] neg_lo:[0,0,1] neg_hi:[0,0,1]
	v_pk_mul_f32 v[92:93], v[92:93], v[156:157]
	v_mul_f32_e32 v98, v34, v158
	v_pk_fma_f32 v[32:33], v[32:33], v[152:153], v[92:93]
	v_mul_f32_e32 v92, v94, v154
	v_mul_f32_e32 v152, v34, v154
	v_mul_f32_e32 v154, v94, v158
	v_mov_b32_e32 v34, v95
	v_mov_b32_e32 v158, v155
	v_pk_mul_f32 v[156:157], v[34:35], v[158:159]
	v_mov_b32_e32 v94, v35
	v_mov_b32_e32 v93, v156
	v_mov_b32_e32 v99, v157
	v_pk_add_f32 v[98:99], v[92:93], v[98:99] neg_lo:[0,1] neg_hi:[0,1]
	v_pk_mul_f32 v[34:35], v[94:95], v[158:159]
	v_lshl_add_u64 v[92:93], s[34:35], 0, v[2:3]
	v_lshl_add_u64 v[2:3], s[36:37], 0, v[2:3]
	v_mov_b32_e32 v153, v34
	v_mov_b32_e32 v155, v35
	v_lshl_add_u64 v[160:161], v[92:93], 0, v[0:1]
	v_lshl_add_u64 v[2:3], v[2:3], 0, v[0:1]
	v_pk_add_f32 v[34:35], v[152:153], v[154:155]
	s_waitcnt vmcnt(2)
	v_mov_b32_e32 v152, v224
	v_mov_b32_e32 v153, v225
	v_mov_b32_e32 v154, v226
	v_mov_b32_e32 v155, v227
	v_mov_b32_e32 v156, v228
	v_mov_b32_e32 v157, v229
	v_mov_b32_e32 v158, v230
	v_mov_b32_e32 v159, v231
	v_pk_mul_f32 v[92:93], v[24:25], v[156:157]
	s_nop 0
	v_pk_fma_f32 v[92:93], v[76:77], v[152:153], v[92:93] neg_lo:[0,0,1] neg_hi:[0,0,1]
	v_pk_mul_f32 v[76:77], v[76:77], v[156:157]
	v_mul_f32_e32 v94, v26, v158
	v_pk_fma_f32 v[24:25], v[24:25], v[152:153], v[76:77]
	v_mul_f32_e32 v76, v78, v154
	v_mul_f32_e32 v152, v26, v154
	v_mul_f32_e32 v154, v78, v158
	v_mov_b32_e32 v26, v79
	v_mov_b32_e32 v158, v155
	v_mov_b32_e32 v78, v27
	v_pk_mul_f32 v[156:157], v[26:27], v[158:159]
	v_pk_mul_f32 v[26:27], v[78:79], v[158:159]
	v_mov_b32_e32 v77, v156
	v_mov_b32_e32 v95, v157
	v_mov_b32_e32 v153, v26
	v_mov_b32_e32 v155, v27
	v_pk_add_f32 v[94:95], v[76:77], v[94:95] neg_lo:[0,1] neg_hi:[0,1]
	v_pk_add_f32 v[26:27], v[152:153], v[154:155]
	s_waitcnt vmcnt(0)
	v_mov_b32_e32 v76, v232
	v_mov_b32_e32 v77, v233
	v_mov_b32_e32 v78, v234
	v_mov_b32_e32 v79, v235
	v_mov_b32_e32 v152, v4
	v_mov_b32_e32 v153, v5
	v_mov_b32_e32 v154, v6
	v_mov_b32_e32 v155, v7
	v_pk_mul_f32 v[2:3], v[20:21], v[152:153]
	s_nop 0
	v_pk_fma_f32 v[156:157], v[28:29], v[76:77], v[2:3] neg_lo:[0,0,1] neg_hi:[0,0,1]
	v_pk_mul_f32 v[2:3], v[28:29], v[152:153]
	v_mul_f32_e32 v28, v22, v154
	v_pk_fma_f32 v[20:21], v[20:21], v[76:77], v[2:3]
	v_mul_f32_e32 v2, v30, v78
	v_mul_f32_e32 v76, v22, v78
	v_mul_f32_e32 v78, v30, v154
	v_mov_b32_e32 v22, v31
	v_mov_b32_e32 v154, v79
	v_pk_mul_f32 v[152:153], v[22:23], v[154:155]
	v_mov_b32_e32 v30, v23
	v_mov_b32_e32 v3, v152
	v_mov_b32_e32 v29, v153
	v_pk_add_f32 v[158:159], v[2:3], v[28:29] neg_lo:[0,1] neg_hi:[0,1]
	v_pk_mul_f32 v[2:3], v[30:31], v[154:155]
	v_mov_b64_e32 v[28:29], v[156:157]
	v_mov_b32_e32 v77, v2
	v_mov_b32_e32 v79, v3
	v_pk_add_f32 v[22:23], v[76:77], v[78:79]
	v_mov_b64_e32 v[76:77], v[92:93]
	v_mov_b64_e32 v[78:79], v[94:95]
	v_mov_b64_e32 v[92:93], v[96:97]
	v_mov_b64_e32 v[94:95], v[98:99]
	v_mov_b64_e32 v[96:97], v[100:101]
	v_mov_b64_e32 v[98:99], v[102:103]
	v_mov_b64_e32 v[100:101], v[104:105]
	v_mov_b64_e32 v[102:103], v[106:107]
	v_mov_b64_e32 v[104:105], v[108:109]
	v_mov_b64_e32 v[106:107], v[110:111]
	v_mov_b64_e32 v[108:109], v[112:113]
	v_mov_b64_e32 v[110:111], v[114:115]
	v_mov_b64_e32 v[112:113], v[120:121]
	v_mov_b64_e32 v[114:115], v[122:123]
	v_mov_b64_e32 v[120:121], v[128:129]
	v_mov_b64_e32 v[122:123], v[130:131]
	v_mov_b64_e32 v[128:129], v[148:149]
	v_mov_b64_e32 v[130:131], v[150:151]
	v_mov_b64_e32 v[148:149], v[146:147]
	v_mov_b64_e32 v[146:147], v[144:145]
	v_mov_b64_e32 v[144:145], v[142:143]
	v_mov_b64_e32 v[142:143], v[140:141]
	v_mov_b64_e32 v[140:141], v[138:139]
	v_mov_b64_e32 v[152:153], v[126:127]
	v_mov_b64_e32 v[138:139], v[136:137]
	v_mov_b64_e32 v[136:137], v[134:135]
	v_mov_b64_e32 v[150:151], v[124:125]
	v_mov_b64_e32 v[126:127], v[118:119]
	v_mov_b64_e32 v[30:31], v[158:159]
	v_mov_b64_e32 v[134:135], v[132:133]
	v_mov_b64_e32 v[124:125], v[116:117]
	s_cmp_eq_u32 s42, 1
	s_cselect_b64 s[34:35], -1, 0
	s_cmp_lg_u32 s42, 1
	s_cbranch_scc0 .LBB0_316

; template <int MI, bool SWAP, bool F8 = false>
; __device__ __forceinline__ void gemm_core(const bf16_t* __restrict__ A, int lda, const bf16_t* __restrict__ B, int ldb,
;                                           int K, char* smem, f32x4 (&acc)[MI][4]) {
;     ...
;   for (int kt = 0; kt < nk; ++kt) {
;     __syncthreads();
; #pragma unroll
;     for (int i = 0; i < MI; ++i) *(u32x4*)(smem + woff + i * 4096) = ra[i];
; #pragma unroll
;     for (int i = 0; i < 4; ++i) *(u32x4*)(smem + 32768 + woff + i * 4096) = rb[i];
;     __syncthreads();
;     if (kt + 1 < nk) {
; #pragma unroll
;       for (int i = 0; i < MI; ++i) ra[i] = *(const u32x4*)(ap + (size_t)(32 * i) * lda + (kt + 1) * 64);
; #pragma unroll
;       for (int i = 0; i < 4; ++i) rb[i] = *(const u32x4*)(bp + (size_t)(32 * i) * ldb + (kt + 1) * 64);
;     }
;     if (F8) {
;       const int c0 = (g ^ (li & 7)) << 4, c1 = ((4 + g) ^ (li & 7)) << 4;
;       i32x8 wf8[4];
; #pragma unroll
;       for (int j = 0; j < 4; ++j) {
;         const char* rp = smem + wrow + ((j & 1) * 16 + (j >> 1) * 64) * 128;
;         const u32x4 lo = *(const u32x4*)(rp + c0), hi = *(const u32x4*)(rp + c1);
;         wf8[j] = (i32x8){(int)lo.x, (int)lo.y, (int)lo.z, (int)lo.w, (int)hi.x, (int)hi.y, (int)hi.z, (int)hi.w};
;       }
; #pragma unroll
;       for (int i = 0; i < MI; ++i) {
;         const char* rp = smem + xrow + i * 2048;
;         const u32x4 lo = *(const u32x4*)(rp + c0), hi = *(const u32x4*)(rp + c1);
;         const i32x8 xf8 = {(int)lo.x, (int)lo.y, (int)lo.z, (int)lo.w, (int)hi.x, (int)hi.y, (int)hi.z, (int)hi.w};
; #pragma unroll
;         for (int j = 0; j < 4; ++j)
;           acc[i][j] = __builtin_amdgcn_mfma_scale_f32_16x16x128_f8f6f4(wf8[j], xf8, acc[i][j], 0, 0, 0, 0x77777777, 0, 0x7f7f7f7f);
;       }
;     } else {
; #pragma unroll
;     for (int kk = 0; kk < 2; ++kk) {
;       const int ch = ((kk * 4 + g) ^ (li & 7)) << 4;
;       bf16x8 xf[MI], wf[4];
; #pragma unroll
;       for (int j = 0; j < 4; ++j) wf[j] = *(const bf16x8*)(smem + wrow + ((j & 1) * 16 + (j >> 1) * 64) * 128 + ch);
; #pragma unroll
;       for (int i = 0; i < MI; ++i) xf[i] = *(const bf16x8*)(smem + xrow + i * 2048 + ch);
; #pragma unroll
;       for (int i = 0; i < MI; ++i)
; #pragma unroll
;         for (int j = 0; j < 4; ++j) {
.LBB0_313:
	v_add_u32_e32 v215, v204, v205
	v_add_u32_e32 v213, v203, v205
	s_waitcnt vmcnt(63) expcnt(7) lgkmcnt(15)
	s_barrier
	s_setprio 2
	s_mov_b32 m0, s62
	s_nop 0
	global_load_lds_dwordx4 v252, s[56:57]
	s_add_u32 m0, s62, 0x1000
	s_nop 0
	global_load_lds_dwordx4 v253, s[56:57]
	s_add_u32 s56, s56, 0x20000
	s_addc_u32 s57, s57, 0
	s_add_u32 m0, s62, 0x2000
	s_nop 0
	global_load_lds_dwordx4 v252, s[56:57]
	s_add_u32 m0, s62, 0x3000
	s_nop 0
	global_load_lds_dwordx4 v253, s[56:57]
	s_add_u32 s56, s56, 0x20000
	s_addc_u32 s57, s57, 0
	s_add_u32 m0, s62, 0x4000
	s_nop 0
	global_load_lds_dwordx4 v252, s[56:57]
	s_add_u32 m0, s62, 0x5000
	s_nop 0
	global_load_lds_dwordx4 v253, s[56:57]
	s_add_u32 s56, s56, 0x20000
	s_addc_u32 s57, s57, 0
	s_add_u32 m0, s62, 0x6000
	s_nop 0
	global_load_lds_dwordx4 v252, s[56:57]
	s_add_u32 m0, s62, 0x7000
	s_nop 0
	global_load_lds_dwordx4 v253, s[56:57]
	s_sub_u32 s56, s56, 0x60000
	s_subb_u32 s57, s57, 0
	s_add_u32 m0, s62, 0x8000
	s_nop 0
	global_load_lds_dwordx4 v252, s[58:59]
	s_add_u32 m0, s62, 0x9000
	s_nop 0
	global_load_lds_dwordx4 v253, s[58:59]
	s_add_u32 s58, s58, 0x20000
	s_addc_u32 s59, s59, 0
	s_add_u32 m0, s62, 0xa000
	s_nop 0
	global_load_lds_dwordx4 v252, s[58:59]
	s_add_u32 m0, s62, 0xb000
	s_nop 0
	global_load_lds_dwordx4 v253, s[58:59]
	s_sub_u32 s58, s58, 0x20000
	s_subb_u32 s59, s59, 0
	s_setprio 0
	v_add_u32_e32 v252, 0x80, v252
	v_add_u32_e32 v253, 0x80, v253
	s_waitcnt vmcnt(0)
	s_barrier
	ds_read_b128 v[148:151], v213
	ds_read_b128 v[152:155], v215 offset:32768
	ds_read_b128 v[156:159], v215 offset:34816
	ds_read_b128 v[160:163], v213 offset:2048
	ds_read_b128 v[164:167], v215 offset:40960
	ds_read_b128 v[168:171], v215 offset:43008
	s_waitcnt lgkmcnt(4)
	v_mfma_f32_16x16x32_bf16 v[140:143], v[148:151], v[152:155], v[140:143]
	v_add_u32_e32 v0, v203, v206
	v_add_u32_e32 v207, v204, v206
	s_waitcnt lgkmcnt(3)
	v_mfma_f32_16x16x32_bf16 v[136:139], v[148:151], v[156:159], v[136:139]
	s_waitcnt lgkmcnt(1)
	v_mfma_f32_16x16x32_bf16 v[132:135], v[148:151], v[164:167], v[132:135]
	s_waitcnt lgkmcnt(0)
	v_mfma_f32_16x16x32_bf16 v[128:131], v[148:151], v[168:171], v[128:131]
	v_mfma_f32_16x16x32_bf16 v[124:127], v[160:163], v[152:155], v[124:127]
	v_mfma_f32_16x16x32_bf16 v[120:123], v[160:163], v[156:159], v[120:123]
	v_mfma_f32_16x16x32_bf16 v[116:119], v[160:163], v[164:167], v[116:119]
	v_mfma_f32_16x16x32_bf16 v[112:115], v[160:163], v[168:171], v[112:115]
	ds_read_b128 v[148:151], v213 offset:4096
	ds_read_b128 v[160:163], v213 offset:6144
	s_waitcnt lgkmcnt(1)
	v_mfma_f32_16x16x32_bf16 v[108:111], v[148:151], v[152:155], v[108:111]
	v_mfma_f32_16x16x32_bf16 v[104:107], v[148:151], v[156:159], v[104:107]
	v_mfma_f32_16x16x32_bf16 v[100:103], v[148:151], v[164:167], v[100:103]
	v_mfma_f32_16x16x32_bf16 v[96:99], v[148:151], v[168:171], v[96:99]
	s_waitcnt lgkmcnt(0)
	v_mfma_f32_16x16x32_bf16 v[92:95], v[160:163], v[152:155], v[92:95]
	v_mfma_f32_16x16x32_bf16 v[88:91], v[160:163], v[156:159], v[88:91]
	v_mfma_f32_16x16x32_bf16 v[80:83], v[160:163], v[164:167], v[80:83]
	v_mfma_f32_16x16x32_bf16 v[72:75], v[160:163], v[168:171], v[72:75]
	ds_read_b128 v[148:151], v213 offset:8192
	ds_read_b128 v[160:163], v213 offset:10240
	s_waitcnt lgkmcnt(1)
	v_mfma_f32_16x16x32_bf16 v[64:67], v[148:151], v[152:155], v[64:67]
	v_mfma_f32_16x16x32_bf16 v[60:63], v[148:151], v[156:159], v[60:63]
	v_mfma_f32_16x16x32_bf16 v[52:55], v[148:151], v[164:167], v[52:55]
	v_mfma_f32_16x16x32_bf16 v[48:51], v[148:151], v[168:171], v[48:51]
	s_waitcnt lgkmcnt(0)
	v_mfma_f32_16x16x32_bf16 v[44:47], v[160:163], v[152:155], v[44:47]
	v_mfma_f32_16x16x32_bf16 v[40:43], v[160:163], v[156:159], v[40:43]
	v_mfma_f32_16x16x32_bf16 v[36:39], v[160:163], v[164:167], v[36:39]
	v_mfma_f32_16x16x32_bf16 v[32:35], v[160:163], v[168:171], v[32:35]
	ds_read_b128 v[148:151], v213 offset:12288
	ds_read_b128 v[160:163], v213 offset:14336
	s_waitcnt lgkmcnt(1)
	v_mfma_f32_16x16x32_bf16 v[24:27], v[148:151], v[156:159], v[24:27]
	s_waitcnt lgkmcnt(0)
	v_mfma_f32_16x16x32_bf16 v[56:59], v[160:163], v[156:159], v[56:59]
	v_mfma_f32_16x16x32_bf16 v[68:71], v[160:163], v[152:155], v[68:71]
	v_mfma_f32_16x16x32_bf16 v[20:23], v[160:163], v[164:167], v[20:23]
	v_mfma_f32_16x16x32_bf16 v[144:147], v[160:163], v[168:171], v[144:147]
	v_mfma_f32_16x16x32_bf16 v[28:31], v[148:151], v[152:155], v[28:31]
	v_mfma_f32_16x16x32_bf16 v[84:87], v[148:151], v[164:167], v[84:87]
	v_mfma_f32_16x16x32_bf16 v[76:79], v[148:151], v[168:171], v[76:79]
	ds_read_b128 v[148:151], v0
	ds_read_b128 v[168:171], v207 offset:32768
	ds_read_b128 v[180:183], v207 offset:34816
	ds_read_b128 v[152:155], v0 offset:2048
	ds_read_b128 v[192:195], v207 offset:40960
	ds_read_b128 v[196:199], v207 offset:43008
	s_waitcnt lgkmcnt(4)
	v_mfma_f32_16x16x32_bf16 v[140:143], v[148:151], v[168:171], v[140:143]
	s_waitcnt lgkmcnt(3)
	v_mfma_f32_16x16x32_bf16 v[136:139], v[148:151], v[180:183], v[136:139]
	s_waitcnt lgkmcnt(1)
	v_mfma_f32_16x16x32_bf16 v[132:135], v[148:151], v[192:195], v[132:135]
	s_waitcnt lgkmcnt(0)
	v_mfma_f32_16x16x32_bf16 v[128:131], v[148:151], v[196:199], v[128:131]
	v_mfma_f32_16x16x32_bf16 v[124:127], v[152:155], v[168:171], v[124:127]
	v_mfma_f32_16x16x32_bf16 v[120:123], v[152:155], v[180:183], v[120:123]
	v_mfma_f32_16x16x32_bf16 v[116:119], v[152:155], v[192:195], v[116:119]
	v_mfma_f32_16x16x32_bf16 v[112:115], v[152:155], v[196:199], v[112:115]
	ds_read_b128 v[148:151], v0 offset:4096
	ds_read_b128 v[152:155], v0 offset:6144
	ds_read_b128 v[156:159], v0 offset:12288
	ds_read_b128 v[216:219], v0 offset:14336
	s_waitcnt lgkmcnt(3)
; template <int MI, bool SWAP, bool F8 = false>
; __device__ __forceinline__ void gemm_core(const bf16_t* __restrict__ A, int lda, const bf16_t* __restrict__ B, int ldb,
;                                           int K, char* smem, f32x4 (&acc)[MI][4]) {
;     ...
;   for (int kt = 0; kt < nk; ++kt) {
;     __syncthreads();
; #pragma unroll
;     for (int i = 0; i < MI; ++i) *(u32x4*)(smem + woff + i * 4096) = ra[i];
; #pragma unroll
;     for (int i = 0; i < 4; ++i) *(u32x4*)(smem + 32768 + woff + i * 4096) = rb[i];
;     __syncthreads();
;     if (kt + 1 < nk) {
; #pragma unroll
;       for (int i = 0; i < MI; ++i) ra[i] = *(const u32x4*)(ap + (size_t)(32 * i) * lda + (kt + 1) * 64);
; #pragma unroll
;       for (int i = 0; i < 4; ++i) rb[i] = *(const u32x4*)(bp + (size_t)(32 * i) * ldb + (kt + 1) * 64);
;     }
;     if (F8) {
;       const int c0 = (g ^ (li & 7)) << 4, c1 = ((4 + g) ^ (li & 7)) << 4;
;       i32x8 wf8[4];
; #pragma unroll
;       for (int j = 0; j < 4; ++j) {
;         const char* rp = smem + wrow + ((j & 1) * 16 + (j >> 1) * 64) * 128;
;         const u32x4 lo = *(const u32x4*)(rp + c0), hi = *(const u32x4*)(rp + c1);
;         wf8[j] = (i32x8){(int)lo.x, (int)lo.y, (int)lo.z, (int)lo.w, (int)hi.x, (int)hi.y, (int)hi.z, (int)hi.w};
;       }
; #pragma unroll
;       for (int i = 0; i < MI; ++i) {
;         const char* rp = smem + xrow + i * 2048;
;         const u32x4 lo = *(const u32x4*)(rp + c0), hi = *(const u32x4*)(rp + c1);
;         const i32x8 xf8 = {(int)lo.x, (int)lo.y, (int)lo.z, (int)lo.w, (int)hi.x, (int)hi.y, (int)hi.z, (int)hi.w};
; #pragma unroll
;         for (int j = 0; j < 4; ++j)
;           acc[i][j] = __builtin_amdgcn_mfma_scale_f32_16x16x128_f8f6f4(wf8[j], xf8, acc[i][j], 0, 0, 0, 0x77777777, 0, 0x7f7f7f7f);
;       }
;     } else {
; #pragma unroll
;     for (int kk = 0; kk < 2; ++kk) {
;       const int ch = ((kk * 4 + g) ^ (li & 7)) << 4;
;       bf16x8 xf[MI], wf[4];
; #pragma unroll
;       for (int j = 0; j < 4; ++j) wf[j] = *(const bf16x8*)(smem + wrow + ((j & 1) * 16 + (j >> 1) * 64) * 128 + ch);
; #pragma unroll
;       for (int i = 0; i < MI; ++i) xf[i] = *(const bf16x8*)(smem + xrow + i * 2048 + ch);
; #pragma unroll
;       for (int i = 0; i < MI; ++i)
; #pragma unroll
;         for (int j = 0; j < 4; ++j) {
	v_mfma_f32_16x16x32_bf16 v[108:111], v[148:151], v[168:171], v[108:111]
	v_mfma_f32_16x16x32_bf16 v[104:107], v[148:151], v[180:183], v[104:107]
	v_mfma_f32_16x16x32_bf16 v[100:103], v[148:151], v[192:195], v[100:103]
	v_mfma_f32_16x16x32_bf16 v[96:99], v[148:151], v[196:199], v[96:99]
	ds_read_b128 v[148:151], v0 offset:8192
	s_waitcnt lgkmcnt(3)
	v_mfma_f32_16x16x32_bf16 v[92:95], v[152:155], v[168:171], v[92:95]
	v_mfma_f32_16x16x32_bf16 v[88:91], v[152:155], v[180:183], v[88:91]
	v_mfma_f32_16x16x32_bf16 v[80:83], v[152:155], v[192:195], v[80:83]
	v_mfma_f32_16x16x32_bf16 v[72:75], v[152:155], v[196:199], v[72:75]
	ds_read_b128 v[152:155], v0 offset:10240
	s_waitcnt lgkmcnt(1)
	v_mfma_f32_16x16x32_bf16 v[64:67], v[148:151], v[168:171], v[64:67]
	v_mfma_f32_16x16x32_bf16 v[60:63], v[148:151], v[180:183], v[60:63]
	v_mfma_f32_16x16x32_bf16 v[52:55], v[148:151], v[192:195], v[52:55]
	v_mfma_f32_16x16x32_bf16 v[48:51], v[148:151], v[196:199], v[48:51]
	s_waitcnt lgkmcnt(0)
	v_mfma_f32_16x16x32_bf16 v[44:47], v[152:155], v[168:171], v[44:47]
	v_mfma_f32_16x16x32_bf16 v[40:43], v[152:155], v[180:183], v[40:43]
	v_mfma_f32_16x16x32_bf16 v[36:39], v[152:155], v[192:195], v[36:39]
	v_mfma_f32_16x16x32_bf16 v[32:35], v[152:155], v[196:199], v[32:35]
	v_mfma_f32_16x16x32_bf16 v[28:31], v[156:159], v[168:171], v[28:31]
	v_mfma_f32_16x16x32_bf16 v[24:27], v[156:159], v[180:183], v[24:27]
	v_mfma_f32_16x16x32_bf16 v[84:87], v[156:159], v[192:195], v[84:87]
	v_mfma_f32_16x16x32_bf16 v[76:79], v[156:159], v[196:199], v[76:79]
	v_mfma_f32_16x16x32_bf16 v[68:71], v[216:219], v[168:171], v[68:71]
	v_mfma_f32_16x16x32_bf16 v[56:59], v[216:219], v[180:183], v[56:59]
	v_mfma_f32_16x16x32_bf16 v[20:23], v[216:219], v[192:195], v[20:23]
	v_mfma_f32_16x16x32_bf16 v[144:147], v[216:219], v[196:199], v[144:147]
	s_add_u32 s8, s8, 0x80
	s_addc_u32 s9, s9, 0
	s_cmpk_lg_i32 s8, 0x780
	s_cbranch_scc1 .LBB0_313
	s_barrier
	s_setprio 2
	s_mov_b32 m0, s62
	s_nop 0
	global_load_lds_dwordx4 v252, s[56:57]
	s_add_u32 m0, s62, 0x1000
	s_nop 0
	global_load_lds_dwordx4 v253, s[56:57]
	s_add_u32 s56, s56, 0x20000
	s_addc_u32 s57, s57, 0
	s_add_u32 m0, s62, 0x2000
	s_nop 0
	global_load_lds_dwordx4 v252, s[56:57]
	s_add_u32 m0, s62, 0x3000
	s_nop 0
	global_load_lds_dwordx4 v253, s[56:57]
	s_add_u32 s56, s56, 0x20000
	s_addc_u32 s57, s57, 0
	s_add_u32 m0, s62, 0x4000
	s_nop 0
	global_load_lds_dwordx4 v252, s[56:57]
	s_add_u32 m0, s62, 0x5000
	s_nop 0
	global_load_lds_dwordx4 v253, s[56:57]
	s_add_u32 s56, s56, 0x20000
	s_addc_u32 s57, s57, 0
	s_add_u32 m0, s62, 0x6000
	s_nop 0
	global_load_lds_dwordx4 v252, s[56:57]
	s_add_u32 m0, s62, 0x7000
	s_nop 0
	global_load_lds_dwordx4 v253, s[56:57]
	s_sub_u32 s56, s56, 0x60000
	s_subb_u32 s57, s57, 0
	s_add_u32 m0, s62, 0x8000
	s_nop 0
	global_load_lds_dwordx4 v252, s[58:59]
	s_add_u32 m0, s62, 0x9000
	s_nop 0
	global_load_lds_dwordx4 v253, s[58:59]
	s_add_u32 s58, s58, 0x20000
	s_addc_u32 s59, s59, 0
	s_add_u32 m0, s62, 0xa000
	s_nop 0
	global_load_lds_dwordx4 v252, s[58:59]
	s_add_u32 m0, s62, 0xb000
	s_nop 0
	global_load_lds_dwordx4 v253, s[58:59]
	s_sub_u32 s58, s58, 0x20000
	s_subb_u32 s59, s59, 0
	s_setprio 0
	s_waitcnt vmcnt(0)
	s_barrier
	v_bfe_u32 v12, v208, 4, 1
	v_mul_u32_u24_e32 v12, 24, v12
	v_mov_b32_e32 v13, 0
	ds_read_b128 v[148:151], v215 offset:32768
	ds_read_b128 v[152:155], v215 offset:34816
	ds_read_b128 v[156:159], v215 offset:40960
	ds_read_b128 v[160:163], v215 offset:43008
	ds_read_b128 v[164:167], v213
	ds_read_b128 v[168:171], v213 offset:2048
	ds_read_b128 v[172:175], v213 offset:4096
	ds_read_b128 v[176:179], v213 offset:6144
	ds_read_b128 v[180:183], v213 offset:8192
	ds_read_b128 v[184:187], v213 offset:10240
	ds_read_b128 v[188:191], v213 offset:12288
	ds_read_b128 v[192:195], v213 offset:14336
	s_cmp_eq_u32 s42, 2
	s_mov_b32 s7, 0x6000000
	s_cselect_b32 s7, 0x2000000, s7
	s_waitcnt lgkmcnt(7)
	v_mfma_f32_16x16x32_bf16 v[140:143], v[164:167], v[148:151], v[140:143]
	s_add_u32 s8, s40, s7
	s_addc_u32 s9, s39, 0
	s_ashr_i32 s7, s6, 31
	v_mfma_f32_16x16x32_bf16 v[136:139], v[164:167], v[152:155], v[136:139]
	s_lshl_b64 s[6:7], s[6:7], 20
	s_add_u32 s6, s8, s6
	s_addc_u32 s7, s9, s7
	v_mfma_f32_16x16x32_bf16 v[132:135], v[164:167], v[156:159], v[132:135]
	s_lshl_b32 s8, s41, 1
	s_add_u32 s6, s6, s8
	s_addc_u32 s7, s7, 0
	v_mfma_f32_16x16x32_bf16 v[128:131], v[164:167], v[160:163], v[128:131]
	s_waitcnt lgkmcnt(6)
	v_mfma_f32_16x16x32_bf16 v[124:127], v[168:171], v[148:151], v[124:127]
	v_mfma_f32_16x16x32_bf16 v[120:123], v[168:171], v[152:155], v[120:123]
	v_mfma_f32_16x16x32_bf16 v[116:119], v[168:171], v[156:159], v[116:119]
	v_mfma_f32_16x16x32_bf16 v[112:115], v[168:171], v[160:163], v[112:115]
	s_waitcnt lgkmcnt(5)
	v_mfma_f32_16x16x32_bf16 v[108:111], v[172:175], v[148:151], v[108:111]
	v_mfma_f32_16x16x32_bf16 v[104:107], v[172:175], v[152:155], v[104:107]
	v_mfma_f32_16x16x32_bf16 v[100:103], v[172:175], v[156:159], v[100:103]
	v_mfma_f32_16x16x32_bf16 v[96:99], v[172:175], v[160:163], v[96:99]
	s_waitcnt lgkmcnt(4)
	v_mfma_f32_16x16x32_bf16 v[92:95], v[176:179], v[148:151], v[92:95]
	v_mfma_f32_16x16x32_bf16 v[88:91], v[176:179], v[152:155], v[88:91]
	v_mfma_f32_16x16x32_bf16 v[80:83], v[176:179], v[156:159], v[80:83]
	v_mfma_f32_16x16x32_bf16 v[72:75], v[176:179], v[160:163], v[72:75]
	s_waitcnt lgkmcnt(3)
	v_mfma_f32_16x16x32_bf16 v[64:67], v[180:183], v[148:151], v[64:67]
	v_mfma_f32_16x16x32_bf16 v[60:63], v[180:183], v[152:155], v[60:63]
	v_mfma_f32_16x16x32_bf16 v[52:55], v[180:183], v[156:159], v[52:55]
	v_mfma_f32_16x16x32_bf16 v[48:51], v[180:183], v[160:163], v[48:51]
	s_waitcnt lgkmcnt(2)
; template <int MI, bool SWAP, bool F8 = false>
; __device__ __forceinline__ void gemm_core(const bf16_t* __restrict__ A, int lda, const bf16_t* __restrict__ B, int ldb,
;                                           int K, char* smem, f32x4 (&acc)[MI][4]) {
;     ...
;     for (int kk = 0; kk < 2; ++kk) {
;       const int ch = ((kk * 4 + g) ^ (li & 7)) << 4;
;       bf16x8 xf[MI], wf[4];
; #pragma unroll
;       for (int j = 0; j < 4; ++j) wf[j] = *(const bf16x8*)(smem + wrow + ((j & 1) * 16 + (j >> 1) * 64) * 128 + ch);
; #pragma unroll
;       for (int i = 0; i < MI; ++i) xf[i] = *(const bf16x8*)(smem + xrow + i * 2048 + ch);
; #pragma unroll
;       for (int i = 0; i < MI; ++i)
; #pragma unroll
;         for (int j = 0; j < 4; ++j) {
;           if (SWAP) acc[i][j] = __builtin_amdgcn_mfma_f32_16x16x32_bf16(xf[i], wf[j], acc[i][j], 0, 0, 0);
;           else acc[i][j] = __builtin_amdgcn_mfma_f32_16x16x32_bf16(wf[j], xf[i], acc[i][j], 0, 0, 0);
;         }
; __device__ void even_in_tile(const P& p, int li_even, int tm, int tn, char* smem) {
;     ...
;     bf16_t* dst = R + (seg == 2 ? R_MVT : R_RVT) + (size_t)bh * 128 * 4096;
; #pragma unroll
;     for (int i = 0; i < MI; ++i)
; #pragma unroll
;       for (int j = 0; j < 4; ++j) {
;         u32x2 v;
;         v.x = pk_bf16(acc[i][j][0], acc[i][j][1]);
;         v.y = pk_bf16(acc[i][j][2], acc[i][j][3]);
;         *(u32x2*)(dst + (size_t)NCOLS(j) * 4096 + s0 + MROWS(i)) = v;
;       }
	v_mfma_f32_16x16x32_bf16 v[44:47], v[184:187], v[148:151], v[44:47]
	v_mfma_f32_16x16x32_bf16 v[40:43], v[184:187], v[152:155], v[40:43]
	v_mfma_f32_16x16x32_bf16 v[36:39], v[184:187], v[156:159], v[36:39]
	v_mfma_f32_16x16x32_bf16 v[32:35], v[184:187], v[160:163], v[32:35]
	s_waitcnt lgkmcnt(1)
	v_mfma_f32_16x16x32_bf16 v[28:31], v[188:191], v[148:151], v[28:31]
	v_mfma_f32_16x16x32_bf16 v[24:27], v[188:191], v[152:155], v[24:27]
	v_mfma_f32_16x16x32_bf16 v[164:167], v[188:191], v[156:159], v[84:87]
	v_mfma_f32_16x16x32_bf16 v[168:171], v[188:191], v[160:163], v[76:79]
	s_waitcnt lgkmcnt(0)
	v_mfma_f32_16x16x32_bf16 v[148:151], v[192:195], v[148:151], v[68:71]
	v_mfma_f32_16x16x32_bf16 v[152:155], v[192:195], v[152:155], v[56:59]
	v_mfma_f32_16x16x32_bf16 v[20:23], v[192:195], v[156:159], v[20:23]
	v_mfma_f32_16x16x32_bf16 v[144:147], v[192:195], v[160:163], v[144:147]
	ds_read_b128 v[156:159], v207 offset:32768
	ds_read_b128 v[160:163], v207 offset:34816
	ds_read_b128 v[172:175], v207 offset:40960
	ds_read_b128 v[176:179], v207 offset:43008
	ds_read_b128 v[56:59], v0
	ds_read_b128 v[68:71], v0 offset:2048
	ds_read_b128 v[76:79], v0 offset:4096
	ds_read_b128 v[84:87], v0 offset:6144
	ds_read_b128 v[180:183], v0 offset:8192
	ds_read_b128 v[184:187], v0 offset:10240
	ds_read_b128 v[188:191], v0 offset:12288
	ds_read_b128 v[192:195], v0 offset:14336
	v_mov_b32_e32 v0, v208
	s_waitcnt lgkmcnt(7)
	v_mfma_f32_16x16x32_bf16 v[140:143], v[56:59], v[156:159], v[140:143]
	v_and_b32_e32 v2, 15, v0
	v_lshrrev_b32_e32 v3, 1, v0
	v_mfma_f32_16x16x32_bf16 v[196:199], v[56:59], v[160:163], v[136:139]
	s_nop 2
	v_and_or_b32 v136, v3, 32, v2
	v_and_b32_e32 v2, 0xffffff80, v0
	v_lshrrev_b32_e32 v0, 2, v0
	v_and_or_b32 v2, v0, 12, v2
	v_ashrrev_i32_e32 v3, 31, v2
	v_lshl_add_u64 v[2:3], v[2:3], 1, s[6:7]
	v_lshlrev_b32_e32 v0, 13, v136
	v_mfma_f32_16x16x32_bf16 v[200:203], v[56:59], v[172:175], v[132:135]
	v_cvt_pk_bf16_f32 v138, v140, v141
	v_cvt_pk_bf16_f32 v139, v142, v143
	v_lshl_add_u64 v[136:137], v[2:3], 0, v[0:1]
	v_mfma_f32_16x16x32_bf16 v[132:135], v[56:59], v[176:179], v[128:131]
	global_store_dwordx2 v[136:137], v[138:139], off
	v_or_b32_e32 v138, 0x20000, v0
	v_mov_b32_e32 v139, v1
	s_waitcnt lgkmcnt(6)
	v_mfma_f32_16x16x32_bf16 v[128:131], v[68:71], v[156:159], v[124:127]
	v_cvt_pk_bf16_f32 v140, v196, v197
	v_cvt_pk_bf16_f32 v141, v198, v199
	v_lshl_add_u64 v[142:143], v[2:3], 0, v[138:139]
	v_mfma_f32_16x16x32_bf16 v[124:127], v[68:71], v[160:163], v[120:123]
	global_store_dwordx2 v[142:143], v[140:141], off
	v_or_b32_e32 v140, 0x80000, v0
	v_or_b32_e32 v0, 0xa0000, v0
	v_mfma_f32_16x16x32_bf16 v[120:123], v[68:71], v[172:175], v[116:119]
	v_cvt_pk_bf16_f32 v132, v132, v133
	v_cvt_pk_bf16_f32 v133, v134, v135
	v_lshl_add_u64 v[134:135], v[2:3], 0, v[0:1]
	v_mfma_f32_16x16x32_bf16 v[116:119], v[68:71], v[176:179], v[112:115]
	global_store_dwordx2 v[134:135], v[132:133], off
	v_lshl_add_u64 v[132:133], v[2:3], 0, 32
	s_mov_b64 s[6:7], 0x60
	s_waitcnt lgkmcnt(5)
	v_mfma_f32_16x16x32_bf16 v[112:115], v[76:79], v[156:159], v[108:111]
	v_mov_b32_e32 v141, v1
	s_nop 1
	v_cvt_pk_bf16_f32 v116, v116, v117
	v_cvt_pk_bf16_f32 v117, v118, v119
	v_mfma_f32_16x16x32_bf16 v[108:111], v[76:79], v[160:163], v[104:107]
	v_lshl_add_u64 v[118:119], v[132:133], 0, v[0:1]
	global_store_dwordx2 v[118:119], v[116:117], off
	v_lshl_add_u64 v[116:117], v[2:3], 0, 64
	v_mfma_f32_16x16x32_bf16 v[104:107], v[76:79], v[172:175], v[100:103]
	v_cvt_pk_bf16_f32 v142, v200, v201
	v_cvt_pk_bf16_f32 v143, v202, v203
	v_cvt_pk_bf16_f32 v128, v128, v129
	v_mfma_f32_16x16x32_bf16 v[100:103], v[76:79], v[176:179], v[96:99]
	v_cvt_pk_bf16_f32 v129, v130, v131
	v_cvt_pk_bf16_f32 v124, v124, v125
	v_cvt_pk_bf16_f32 v125, v126, v127
	s_waitcnt lgkmcnt(4)
	v_mfma_f32_16x16x32_bf16 v[96:99], v[84:87], v[156:159], v[92:95]
	v_lshl_add_u64 v[126:127], v[132:133], 0, v[138:139]
	s_nop 1
	v_cvt_pk_bf16_f32 v100, v100, v101
	v_cvt_pk_bf16_f32 v101, v102, v103
	v_mfma_f32_16x16x32_bf16 v[92:95], v[84:87], v[160:163], v[88:91]
	v_lshl_add_u64 v[102:103], v[116:117], 0, v[0:1]
	global_store_dwordx2 v[102:103], v[100:101], off
	v_lshl_add_u64 v[100:101], v[2:3], 0, s[6:7]
	v_mfma_f32_16x16x32_bf16 v[88:91], v[84:87], v[172:175], v[80:83]
	s_mov_b64 s[6:7], 0x80
	v_cvt_pk_bf16_f32 v120, v120, v121
	v_cvt_pk_bf16_f32 v121, v122, v123
	v_mfma_f32_16x16x32_bf16 v[84:87], v[84:87], v[176:179], v[72:75]
	v_lshl_add_u64 v[122:123], v[132:133], 0, v[140:141]
	v_cvt_pk_bf16_f32 v112, v112, v113
	v_cvt_pk_bf16_f32 v113, v114, v115
	s_waitcnt lgkmcnt(3)
	v_mfma_f32_16x16x32_bf16 v[68:71], v[180:183], v[176:179], v[48:51]
	v_cvt_pk_bf16_f32 v108, v108, v109
	s_nop 1
	v_cvt_pk_bf16_f32 v84, v84, v85
	v_cvt_pk_bf16_f32 v85, v86, v87
	v_mfma_f32_16x16x32_bf16 v[72:75], v[180:183], v[172:175], v[52:55]
	v_lshl_add_u64 v[86:87], v[100:101], 0, v[0:1]
	global_store_dwordx2 v[86:87], v[84:85], off
	v_lshl_add_u64 v[84:85], v[2:3], 0, s[6:7]
	s_waitcnt lgkmcnt(2)
; __device__ void even_in_tile(const P& p, int li_even, int tm, int tn, char* smem) {
;     ...
;     for (int i = 0; i < MI; ++i)
; #pragma unroll
;       for (int j = 0; j < 4; ++j) {
;         u32x2 v;
;         v.x = pk_bf16(acc[i][j][0], acc[i][j][1]);
;         v.y = pk_bf16(acc[i][j][2], acc[i][j][3]);
;         *(u32x2*)(dst + (size_t)NCOLS(j) * 4096 + s0 + MROWS(i)) = v;
;       }
	v_mfma_f32_16x16x32_bf16 v[52:55], v[184:187], v[176:179], v[32:35]
	v_cvt_pk_bf16_f32 v68, v68, v69
	v_cvt_pk_bf16_f32 v69, v70, v71
	v_lshl_add_u64 v[70:71], v[84:85], 0, v[0:1]
	s_mov_b64 s[6:7], 0xa0
	v_mfma_f32_16x16x32_bf16 v[80:83], v[180:183], v[156:159], v[64:67]
	global_store_dwordx2 v[70:71], v[68:69], off
	v_lshl_add_u64 v[68:69], v[2:3], 0, s[6:7]
	s_nop 0
	v_cvt_pk_bf16_f32 v52, v52, v53
	v_mfma_f32_16x16x32_bf16 v[76:79], v[180:183], v[160:163], v[60:63]
	v_cvt_pk_bf16_f32 v53, v54, v55
	v_lshl_add_u64 v[54:55], v[68:69], 0, v[0:1]
	s_mov_b64 s[6:7], 0xc0
	v_mfma_f32_16x16x32_bf16 v[64:67], v[184:187], v[156:159], v[44:47]
	global_store_dwordx2 v[54:55], v[52:53], off
	v_lshl_add_u64 v[52:53], v[2:3], 0, s[6:7]
	s_mov_b64 s[6:7], 0xe0
	v_mfma_f32_16x16x32_bf16 v[60:63], v[184:187], v[160:163], v[40:43]
	v_cvt_pk_bf16_f32 v109, v110, v111
	v_lshl_add_u64 v[110:111], v[116:117], 0, v[138:139]
	v_cvt_pk_bf16_f32 v104, v104, v105
	v_mfma_f32_16x16x32_bf16 v[56:59], v[184:187], v[172:175], v[36:39]
	v_cvt_pk_bf16_f32 v105, v106, v107
	v_lshl_add_u64 v[106:107], v[116:117], 0, v[140:141]
	v_cvt_pk_bf16_f32 v96, v96, v97
	s_waitcnt lgkmcnt(1)
	v_mfma_f32_16x16x32_bf16 v[48:51], v[188:191], v[156:159], v[28:31]
	v_cvt_pk_bf16_f32 v97, v98, v99
	v_cvt_pk_bf16_f32 v92, v92, v93
	v_cvt_pk_bf16_f32 v93, v94, v95
	v_mfma_f32_16x16x32_bf16 v[44:47], v[188:191], v[160:163], v[24:27]
	v_lshl_add_u64 v[94:95], v[100:101], 0, v[138:139]
	v_cvt_pk_bf16_f32 v88, v88, v89
	v_cvt_pk_bf16_f32 v89, v90, v91
	v_mfma_f32_16x16x32_bf16 v[40:43], v[188:191], v[172:175], v[164:167]
	v_lshl_add_u64 v[90:91], v[100:101], 0, v[140:141]
	v_cvt_pk_bf16_f32 v80, v80, v81
	v_cvt_pk_bf16_f32 v81, v82, v83
	v_mfma_f32_16x16x32_bf16 v[36:39], v[188:191], v[176:179], v[168:171]
	v_cvt_pk_bf16_f32 v76, v76, v77
	v_cvt_pk_bf16_f32 v77, v78, v79
	v_lshl_add_u64 v[78:79], v[84:85], 0, v[138:139]
	s_waitcnt lgkmcnt(0)
	v_mfma_f32_16x16x32_bf16 v[32:35], v[192:195], v[156:159], v[148:151]
	v_cvt_pk_bf16_f32 v72, v72, v73
	v_cvt_pk_bf16_f32 v73, v74, v75
	v_lshl_add_u64 v[74:75], v[84:85], 0, v[140:141]
	v_mfma_f32_16x16x32_bf16 v[28:31], v[192:195], v[160:163], v[152:155]
	v_cvt_pk_bf16_f32 v64, v64, v65
	v_cvt_pk_bf16_f32 v65, v66, v67
	v_cvt_pk_bf16_f32 v60, v60, v61
	v_mfma_f32_16x16x32_bf16 v[24:27], v[192:195], v[172:175], v[20:23]
	v_cvt_pk_bf16_f32 v61, v62, v63
	v_lshl_add_u64 v[62:63], v[68:69], 0, v[138:139]
	v_cvt_pk_bf16_f32 v56, v56, v57
	v_mfma_f32_16x16x32_bf16 v[20:23], v[192:195], v[176:179], v[144:147]
	v_cvt_pk_bf16_f32 v57, v58, v59
	v_lshl_add_u64 v[58:59], v[68:69], 0, v[140:141]
	v_cvt_pk_bf16_f32 v48, v48, v49
	v_lshl_add_u64 v[144:145], v[2:3], 0, v[140:141]
	v_lshl_add_u64 v[2:3], v[2:3], 0, s[6:7]
	v_cvt_pk_bf16_f32 v49, v50, v51
	v_cvt_pk_bf16_f32 v44, v44, v45
	v_cvt_pk_bf16_f32 v45, v46, v47
	v_lshl_add_u64 v[46:47], v[52:53], 0, v[138:139]
	v_cvt_pk_bf16_f32 v40, v40, v41
	v_cvt_pk_bf16_f32 v41, v42, v43
	v_lshl_add_u64 v[42:43], v[52:53], 0, v[140:141]
	v_cvt_pk_bf16_f32 v36, v36, v37
	v_cvt_pk_bf16_f32 v37, v38, v39
	v_lshl_add_u64 v[38:39], v[52:53], 0, v[0:1]
	v_cvt_pk_bf16_f32 v32, v32, v33
	v_cvt_pk_bf16_f32 v33, v34, v35
	v_cvt_pk_bf16_f32 v28, v28, v29
	v_cvt_pk_bf16_f32 v29, v30, v31
	v_lshl_add_u64 v[30:31], v[2:3], 0, v[138:139]
	v_cvt_pk_bf16_f32 v24, v24, v25
	v_cvt_pk_bf16_f32 v25, v26, v27
	v_lshl_add_u64 v[26:27], v[2:3], 0, v[140:141]
	v_cvt_pk_bf16_f32 v20, v20, v21
	v_cvt_pk_bf16_f32 v21, v22, v23
	v_lshl_add_u64 v[2:3], v[2:3], 0, v[0:1]
	global_store_dwordx2 v[144:145], v[142:143], off
	global_store_dwordx2 v[136:137], v[128:129], off offset:32
	global_store_dwordx2 v[126:127], v[124:125], off
	global_store_dwordx2 v[122:123], v[120:121], off
	global_store_dwordx2 v[136:137], v[112:113], off offset:64
	global_store_dwordx2 v[110:111], v[108:109], off
	global_store_dwordx2 v[106:107], v[104:105], off
	global_store_dwordx2 v[136:137], v[96:97], off offset:96
	global_store_dwordx2 v[94:95], v[92:93], off
	global_store_dwordx2 v[90:91], v[88:89], off
	global_store_dwordx2 v[136:137], v[80:81], off offset:128
	global_store_dwordx2 v[78:79], v[76:77], off
	global_store_dwordx2 v[74:75], v[72:73], off
	global_store_dwordx2 v[136:137], v[64:65], off offset:160
	global_store_dwordx2 v[62:63], v[60:61], off
	global_store_dwordx2 v[58:59], v[56:57], off
	global_store_dwordx2 v[136:137], v[48:49], off offset:192
	global_store_dwordx2 v[46:47], v[44:45], off
	global_store_dwordx2 v[42:43], v[40:41], off
	global_store_dwordx2 v[38:39], v[36:37], off
	global_store_dwordx2 v[136:137], v[32:33], off offset:224
	global_store_dwordx2 v[30:31], v[28:29], off
	global_store_dwordx2 v[26:27], v[24:25], off
	global_store_dwordx2 v[2:3], v[20:21], off
	s_branch .LBB0_294

; template <int MI, bool SWAP, bool F8 = false>
; __device__ __forceinline__ void gemm_core(const bf16_t* __restrict__ A, int lda, const bf16_t* __restrict__ B, int ldb,
;                                           int K, char* smem, f32x4 (&acc)[MI][4]) {
;     ...
;     for (int kk = 0; kk < 2; ++kk) {
;       const int ch = ((kk * 4 + g) ^ (li & 7)) << 4;
;       bf16x8 xf[MI], wf[4];
; #pragma unroll
;       for (int j = 0; j < 4; ++j) wf[j] = *(const bf16x8*)(smem + wrow + ((j & 1) * 16 + (j >> 1) * 64) * 128 + ch);
; #pragma unroll
;       for (int i = 0; i < MI; ++i) xf[i] = *(const bf16x8*)(smem + xrow + i * 2048 + ch);
; #pragma unroll
;       for (int i = 0; i < MI; ++i)
; #pragma unroll
;         for (int j = 0; j < 4; ++j) {
;           if (SWAP) acc[i][j] = __builtin_amdgcn_mfma_f32_16x16x32_bf16(xf[i], wf[j], acc[i][j], 0, 0, 0);
;           else acc[i][j] = __builtin_amdgcn_mfma_f32_16x16x32_bf16(wf[j], xf[i], acc[i][j], 0, 0, 0);
;         }
.Lcch819_ret:
	s_add_u32 s63, s63, 1
	s_barrier
	v_add_u32_e32 v213, v202, v204
	ds_read_b128 v[148:151], v215 offset:32768
	ds_read_b128 v[152:155], v215 offset:34816
	ds_read_b128 v[156:159], v213
	ds_read_b128 v[160:163], v213 offset:2048
	ds_read_b128 v[164:167], v215 offset:40960
	ds_read_b128 v[168:171], v215 offset:43008
	s_waitcnt lgkmcnt(3)
	v_mfma_f32_16x16x32_bf16 v[140:143], v[148:151], v[156:159], v[140:143]
	v_add_u32_e32 v207, v203, v205
	v_add_u32_e32 v206, v202, v205
	v_mfma_f32_16x16x32_bf16 v[136:139], v[152:155], v[156:159], v[136:139]
	s_waitcnt lgkmcnt(1)
	v_mfma_f32_16x16x32_bf16 v[132:135], v[164:167], v[156:159], v[132:135]
	s_waitcnt lgkmcnt(0)
	v_mfma_f32_16x16x32_bf16 v[124:127], v[168:171], v[156:159], v[124:127]
	v_mfma_f32_16x16x32_bf16 v[108:111], v[148:151], v[160:163], v[108:111]
	v_mfma_f32_16x16x32_bf16 v[104:107], v[152:155], v[160:163], v[104:107]
	v_mfma_f32_16x16x32_bf16 v[96:99], v[164:167], v[160:163], v[96:99]
	v_mfma_f32_16x16x32_bf16 v[92:95], v[168:171], v[160:163], v[92:95]
	ds_read_b128 v[156:159], v213 offset:4096
	ds_read_b128 v[160:163], v213 offset:6144
	s_waitcnt lgkmcnt(1)
	v_mfma_f32_16x16x32_bf16 v[88:91], v[148:151], v[156:159], v[88:91]
	v_mfma_f32_16x16x32_bf16 v[84:87], v[152:155], v[156:159], v[84:87]
	v_mfma_f32_16x16x32_bf16 v[80:83], v[164:167], v[156:159], v[80:83]
	v_mfma_f32_16x16x32_bf16 v[60:63], v[168:171], v[156:159], v[60:63]
	s_waitcnt lgkmcnt(0)
	v_mfma_f32_16x16x32_bf16 v[56:59], v[148:151], v[160:163], v[56:59]
	v_mfma_f32_16x16x32_bf16 v[52:55], v[152:155], v[160:163], v[52:55]
	v_mfma_f32_16x16x32_bf16 v[48:51], v[164:167], v[160:163], v[48:51]
	v_mfma_f32_16x16x32_bf16 v[44:47], v[168:171], v[160:163], v[44:47]
	ds_read_b128 v[156:159], v213 offset:8192
	ds_read_b128 v[160:163], v213 offset:10240
	s_waitcnt lgkmcnt(1)
	v_mfma_f32_16x16x32_bf16 v[40:43], v[148:151], v[156:159], v[40:43]
	v_mfma_f32_16x16x32_bf16 v[36:39], v[152:155], v[156:159], v[36:39]
	v_mfma_f32_16x16x32_bf16 v[32:35], v[164:167], v[156:159], v[32:35]
	v_mfma_f32_16x16x32_bf16 v[28:31], v[168:171], v[156:159], v[28:31]
	s_waitcnt lgkmcnt(0)
	v_mfma_f32_16x16x32_bf16 v[24:27], v[148:151], v[160:163], v[24:27]
	v_mfma_f32_16x16x32_bf16 v[20:23], v[152:155], v[160:163], v[20:23]
	v_mfma_f32_16x16x32_bf16 v[68:71], v[164:167], v[160:163], v[68:71]
	v_mfma_f32_16x16x32_bf16 v[64:67], v[168:171], v[160:163], v[64:67]
	ds_read_b128 v[156:159], v213 offset:12288
	ds_read_b128 v[160:163], v213 offset:14336
	ds_read_b128 v[172:175], v207 offset:32768
	ds_read_b128 v[180:183], v207 offset:34816
	s_waitcnt lgkmcnt(3)
	v_mfma_f32_16x16x32_bf16 v[72:75], v[148:151], v[156:159], v[72:75]
	v_mfma_f32_16x16x32_bf16 v[76:79], v[152:155], v[156:159], v[76:79]
	v_mfma_f32_16x16x32_bf16 v[128:131], v[164:167], v[156:159], v[128:131]
	v_mfma_f32_16x16x32_bf16 v[120:123], v[168:171], v[156:159], v[120:123]
	s_waitcnt lgkmcnt(2)
	v_mfma_f32_16x16x32_bf16 v[116:119], v[148:151], v[160:163], v[116:119]
	v_mfma_f32_16x16x32_bf16 v[112:115], v[152:155], v[160:163], v[112:115]
	ds_read_b128 v[148:151], v206
	ds_read_b128 v[152:155], v206 offset:2048
	ds_read_b128 v[192:195], v207 offset:40960
	ds_read_b128 v[196:199], v207 offset:43008
	v_mfma_f32_16x16x32_bf16 v[100:103], v[164:167], v[160:163], v[100:103]
	v_mfma_f32_16x16x32_bf16 v[144:147], v[168:171], v[160:163], v[144:147]
	s_waitcnt lgkmcnt(3)
	v_mfma_f32_16x16x32_bf16 v[140:143], v[172:175], v[148:151], v[140:143]
	v_mfma_f32_16x16x32_bf16 v[136:139], v[180:183], v[148:151], v[136:139]
	s_waitcnt lgkmcnt(1)
	v_mfma_f32_16x16x32_bf16 v[132:135], v[192:195], v[148:151], v[132:135]
	s_waitcnt lgkmcnt(0)
	v_mfma_f32_16x16x32_bf16 v[124:127], v[196:199], v[148:151], v[124:127]
	v_mfma_f32_16x16x32_bf16 v[108:111], v[172:175], v[152:155], v[108:111]
	v_mfma_f32_16x16x32_bf16 v[104:107], v[180:183], v[152:155], v[104:107]
	v_mfma_f32_16x16x32_bf16 v[96:99], v[192:195], v[152:155], v[96:99]
	v_mfma_f32_16x16x32_bf16 v[92:95], v[196:199], v[152:155], v[92:95]
	ds_read_b128 v[148:151], v206 offset:4096
	ds_read_b128 v[152:155], v206 offset:6144
	s_waitcnt lgkmcnt(1)
	v_mfma_f32_16x16x32_bf16 v[88:91], v[172:175], v[148:151], v[88:91]
	ds_read_b128 v[156:159], v206 offset:12288
	ds_read_b128 v[216:219], v206 offset:14336
	v_mfma_f32_16x16x32_bf16 v[84:87], v[180:183], v[148:151], v[84:87]
	v_mfma_f32_16x16x32_bf16 v[80:83], v[192:195], v[148:151], v[80:83]
	v_mfma_f32_16x16x32_bf16 v[60:63], v[196:199], v[148:151], v[60:63]
	ds_read_b128 v[148:151], v206 offset:8192
	s_waitcnt lgkmcnt(3)
	v_mfma_f32_16x16x32_bf16 v[56:59], v[172:175], v[152:155], v[56:59]
	v_mfma_f32_16x16x32_bf16 v[52:55], v[180:183], v[152:155], v[52:55]
	v_mfma_f32_16x16x32_bf16 v[48:51], v[192:195], v[152:155], v[48:51]
	v_mfma_f32_16x16x32_bf16 v[44:47], v[196:199], v[152:155], v[44:47]
	ds_read_b128 v[152:155], v206 offset:10240
	s_waitcnt lgkmcnt(1)
	v_mfma_f32_16x16x32_bf16 v[40:43], v[172:175], v[148:151], v[40:43]
	v_mfma_f32_16x16x32_bf16 v[36:39], v[180:183], v[148:151], v[36:39]
	v_mfma_f32_16x16x32_bf16 v[32:35], v[192:195], v[148:151], v[32:35]
	v_mfma_f32_16x16x32_bf16 v[28:31], v[196:199], v[148:151], v[28:31]
	s_waitcnt lgkmcnt(0)
	v_mfma_f32_16x16x32_bf16 v[24:27], v[172:175], v[152:155], v[24:27]
	v_mfma_f32_16x16x32_bf16 v[20:23], v[180:183], v[152:155], v[20:23]
	v_mfma_f32_16x16x32_bf16 v[68:71], v[192:195], v[152:155], v[68:71]
	v_mfma_f32_16x16x32_bf16 v[64:67], v[196:199], v[152:155], v[64:67]
	v_mfma_f32_16x16x32_bf16 v[72:75], v[172:175], v[156:159], v[72:75]
	v_mfma_f32_16x16x32_bf16 v[76:79], v[180:183], v[156:159], v[76:79]
	v_mfma_f32_16x16x32_bf16 v[128:131], v[192:195], v[156:159], v[128:131]
	v_mfma_f32_16x16x32_bf16 v[120:123], v[196:199], v[156:159], v[120:123]
	v_mfma_f32_16x16x32_bf16 v[116:119], v[172:175], v[216:219], v[116:119]
	v_mfma_f32_16x16x32_bf16 v[112:115], v[180:183], v[216:219], v[112:115]
	v_mfma_f32_16x16x32_bf16 v[100:103], v[192:195], v[216:219], v[100:103]
	v_mfma_f32_16x16x32_bf16 v[144:147], v[196:199], v[216:219], v[144:147]
	s_add_u32 s6, s6, 0x80
	s_addc_u32 s7, s7, 0
	s_cmpk_lg_i32 s6, 0x780
	s_cbranch_scc1 .LBB0_819
; template <int MI, bool SWAP, bool F8 = false>
; __device__ __forceinline__ void gemm_core(const bf16_t* __restrict__ A, int lda, const bf16_t* __restrict__ B, int ldb,
;                                           int K, char* smem, f32x4 (&acc)[MI][4]) {
;     ...
;   for (int kt = 0; kt < nk; ++kt) {
;     __syncthreads();
; #pragma unroll
;     for (int i = 0; i < MI; ++i) *(u32x4*)(smem + woff + i * 4096) = ra[i];
; #pragma unroll
;     for (int i = 0; i < 4; ++i) *(u32x4*)(smem + 32768 + woff + i * 4096) = rb[i];
;     __syncthreads();
;     if (kt + 1 < nk) {
; #pragma unroll
;       for (int i = 0; i < MI; ++i) ra[i] = *(const u32x4*)(ap + (size_t)(32 * i) * lda + (kt + 1) * 64);
; #pragma unroll
;       for (int i = 0; i < 4; ++i) rb[i] = *(const u32x4*)(bp + (size_t)(32 * i) * ldb + (kt + 1) * 64);
;     }
;     if (F8) {
;       const int c0 = (g ^ (li & 7)) << 4, c1 = ((4 + g) ^ (li & 7)) << 4;
;       i32x8 wf8[4];
; #pragma unroll
;       for (int j = 0; j < 4; ++j) {
;         const char* rp = smem + wrow + ((j & 1) * 16 + (j >> 1) * 64) * 128;
;         const u32x4 lo = *(const u32x4*)(rp + c0), hi = *(const u32x4*)(rp + c1);
;         wf8[j] = (i32x8){(int)lo.x, (int)lo.y, (int)lo.z, (int)lo.w, (int)hi.x, (int)hi.y, (int)hi.z, (int)hi.w};
;       }
; #pragma unroll
;       for (int i = 0; i < MI; ++i) {
;         const char* rp = smem + xrow + i * 2048;
;         const u32x4 lo = *(const u32x4*)(rp + c0), hi = *(const u32x4*)(rp + c1);
;         const i32x8 xf8 = {(int)lo.x, (int)lo.y, (int)lo.z, (int)lo.w, (int)hi.x, (int)hi.y, (int)hi.z, (int)hi.w};
; #pragma unroll
;         for (int j = 0; j < 4; ++j)
;           acc[i][j] = __builtin_amdgcn_mfma_scale_f32_16x16x128_f8f6f4(wf8[j], xf8, acc[i][j], 0, 0, 0, 0x77777777, 0, 0x7f7f7f7f);
;       }
;     } else {
; #pragma unroll
;     for (int kk = 0; kk < 2; ++kk) {
;       const int ch = ((kk * 4 + g) ^ (li & 7)) << 4;
;       bf16x8 xf[MI], wf[4];
; #pragma unroll
;       for (int j = 0; j < 4; ++j) wf[j] = *(const bf16x8*)(smem + wrow + ((j & 1) * 16 + (j >> 1) * 64) * 128 + ch);
; #pragma unroll
;       for (int i = 0; i < MI; ++i) xf[i] = *(const bf16x8*)(smem + xrow + i * 2048 + ch);
; #pragma unroll
;       for (int i = 0; i < MI; ++i)
; #pragma unroll
;         for (int j = 0; j < 4; ++j) {
	s_barrier
	s_setprio 2
	s_mov_b32 m0, s62
	s_nop 0
	global_load_lds_dwordx4 v252, s[56:57]
	s_add_u32 m0, s62, 0x1000
	s_nop 0
	global_load_lds_dwordx4 v253, s[56:57]
	s_add_u32 s56, s56, 0x20000
	s_addc_u32 s57, s57, 0
	s_add_u32 m0, s62, 0x2000
	s_nop 0
	global_load_lds_dwordx4 v252, s[56:57]
	s_add_u32 m0, s62, 0x3000
	s_nop 0
	global_load_lds_dwordx4 v253, s[56:57]
	s_add_u32 s56, s56, 0x20000
	s_addc_u32 s57, s57, 0
	s_add_u32 m0, s62, 0x4000
	s_nop 0
	global_load_lds_dwordx4 v252, s[56:57]
	s_add_u32 m0, s62, 0x5000
	s_nop 0
	global_load_lds_dwordx4 v253, s[56:57]
	s_add_u32 s56, s56, 0x20000
	s_addc_u32 s57, s57, 0
	s_add_u32 m0, s62, 0x6000
	s_nop 0
	global_load_lds_dwordx4 v252, s[56:57]
	s_add_u32 m0, s62, 0x7000
	s_nop 0
	global_load_lds_dwordx4 v253, s[56:57]
	s_sub_u32 s56, s56, 0x60000
	s_subb_u32 s57, s57, 0
	s_add_u32 m0, s62, 0x8000
	s_nop 0
	global_load_lds_dwordx4 v252, s[58:59]
	s_add_u32 m0, s62, 0x9000
	s_nop 0
	global_load_lds_dwordx4 v253, s[58:59]
	s_add_u32 s58, s58, 0x20000
	s_addc_u32 s59, s59, 0
	s_add_u32 m0, s62, 0xa000
	s_nop 0
	global_load_lds_dwordx4 v252, s[58:59]
	s_add_u32 m0, s62, 0xb000
	s_nop 0
	global_load_lds_dwordx4 v253, s[58:59]
	s_sub_u32 s58, s58, 0x20000
	s_subb_u32 s59, s59, 0
	s_setprio 0
	s_waitcnt vmcnt(0)
	s_barrier
	ds_read_b128 v[148:151], v215 offset:32768
	ds_read_b128 v[152:155], v215 offset:34816
	ds_read_b128 v[156:159], v215 offset:40960
	ds_read_b128 v[160:163], v215 offset:43008
	ds_read_b128 v[164:167], v213
	ds_read_b128 v[168:171], v213 offset:2048
	ds_read_b128 v[172:175], v213 offset:4096
	ds_read_b128 v[176:179], v213 offset:6144
	ds_read_b128 v[180:183], v213 offset:8192
	ds_read_b128 v[184:187], v213 offset:10240
	ds_read_b128 v[188:191], v213 offset:12288
	ds_read_b128 v[192:195], v213 offset:14336
	s_waitcnt lgkmcnt(7)
	v_mfma_f32_16x16x32_bf16 v[132:135], v[156:159], v[164:167], v[132:135]
	s_lshl_b64 s[0:1], s[0:1], 2
	s_add_u32 s0, s16, s0
	s_addc_u32 s1, s17, s1
	v_mfma_f32_16x16x32_bf16 v[140:143], v[148:151], v[164:167], v[140:143]
	s_lshl_b32 s6, s22, 2
	s_add_u32 s0, s0, s6
	s_addc_u32 s1, s1, 0
	v_mfma_f32_16x16x32_bf16 v[136:139], v[152:155], v[164:167], v[136:139]
	s_add_i32 s21, s21, s78
	s_add_i32 s20, s20, s71
	s_add_i32 s19, s19, s76
	v_mfma_f32_16x16x32_bf16 v[124:127], v[160:163], v[164:167], v[124:127]
	s_cmpk_gt_i32 s21, 0x1ff
	s_waitcnt lgkmcnt(6)
	v_mfma_f32_16x16x32_bf16 v[108:111], v[148:151], v[168:171], v[108:111]
	v_mfma_f32_16x16x32_bf16 v[104:107], v[152:155], v[168:171], v[104:107]
	v_mfma_f32_16x16x32_bf16 v[96:99], v[156:159], v[168:171], v[96:99]
	v_mfma_f32_16x16x32_bf16 v[92:95], v[160:163], v[168:171], v[92:95]
	s_waitcnt lgkmcnt(5)
	v_mfma_f32_16x16x32_bf16 v[88:91], v[148:151], v[172:175], v[88:91]
	v_mfma_f32_16x16x32_bf16 v[84:87], v[152:155], v[172:175], v[84:87]
	v_mfma_f32_16x16x32_bf16 v[80:83], v[156:159], v[172:175], v[80:83]
	v_mfma_f32_16x16x32_bf16 v[60:63], v[160:163], v[172:175], v[60:63]
	s_waitcnt lgkmcnt(4)
	v_mfma_f32_16x16x32_bf16 v[56:59], v[148:151], v[176:179], v[56:59]
	v_mfma_f32_16x16x32_bf16 v[52:55], v[152:155], v[176:179], v[52:55]
	v_mfma_f32_16x16x32_bf16 v[48:51], v[156:159], v[176:179], v[48:51]
	v_mfma_f32_16x16x32_bf16 v[44:47], v[160:163], v[176:179], v[44:47]
	s_waitcnt lgkmcnt(3)
	v_mfma_f32_16x16x32_bf16 v[40:43], v[148:151], v[180:183], v[40:43]
	v_mfma_f32_16x16x32_bf16 v[36:39], v[152:155], v[180:183], v[36:39]
	v_mfma_f32_16x16x32_bf16 v[32:35], v[156:159], v[180:183], v[32:35]
	v_mfma_f32_16x16x32_bf16 v[28:31], v[160:163], v[180:183], v[28:31]
	s_waitcnt lgkmcnt(2)
	v_mfma_f32_16x16x32_bf16 v[24:27], v[148:151], v[184:187], v[24:27]
	v_mfma_f32_16x16x32_bf16 v[20:23], v[152:155], v[184:187], v[20:23]
	v_mfma_f32_16x16x32_bf16 v[164:167], v[156:159], v[184:187], v[68:71]
	v_mfma_f32_16x16x32_bf16 v[168:171], v[160:163], v[184:187], v[64:67]
	s_waitcnt lgkmcnt(1)
	v_mfma_f32_16x16x32_bf16 v[172:175], v[148:151], v[188:191], v[72:75]
	v_mfma_f32_16x16x32_bf16 v[176:179], v[152:155], v[188:191], v[76:79]
	v_mfma_f32_16x16x32_bf16 v[180:183], v[156:159], v[188:191], v[128:131]
	v_mfma_f32_16x16x32_bf16 v[184:187], v[160:163], v[188:191], v[120:123]
	s_waitcnt lgkmcnt(0)
	v_mfma_f32_16x16x32_bf16 v[148:151], v[148:151], v[192:195], v[116:119]
	v_mfma_f32_16x16x32_bf16 v[152:155], v[152:155], v[192:195], v[112:115]
	v_mfma_f32_16x16x32_bf16 v[156:159], v[156:159], v[192:195], v[100:103]
	v_mfma_f32_16x16x32_bf16 v[144:147], v[160:163], v[192:195], v[144:147]
	ds_read_b128 v[160:163], v207 offset:32768
	ds_read_b128 v[188:191], v207 offset:34816
	ds_read_b128 v[192:195], v207 offset:40960
	ds_read_b128 v[196:199], v207 offset:43008
	ds_read_b128 v[64:67], v206
	ds_read_b128 v[68:71], v206 offset:2048
	ds_read_b128 v[72:75], v206 offset:4096
	ds_read_b128 v[76:79], v206 offset:6144
	ds_read_b128 v[200:203], v206 offset:8192
	ds_read_b128 v[216:219], v206 offset:10240
	ds_read_b128 v[220:223], v206 offset:12288
	ds_read_b128 v[204:207], v206 offset:14336
	s_waitcnt lgkmcnt(7)
; template <bool ACCUM, int MI>
; __device__ void gemm_tile_f32(const bf16_t* A, int lda, const bf16_t* B, int ldb, int K, float* C, int ldc, char* smem) {
;     ...
; #pragma unroll
;   for (int i = 0; i < MI; ++i)
; #pragma unroll
;     for (int j = 0; j < 4; ++j) {
;       f32x4* cp = (f32x4*)(C + (size_t)MROW(i) * ldc + NCOL(j));
;       f32x4 v = acc[i][j];
;       if (ACCUM) v += *cp;
;       *cp = v;
;     }
	v_mfma_f32_16x16x32_bf16 v[224:227], v[192:195], v[64:67], v[132:135]
	v_mfma_f32_16x16x32_bf16 v[228:231], v[196:199], v[64:67], v[124:127]
	s_waitcnt lgkmcnt(6)
	v_mfma_f32_16x16x32_bf16 v[128:131], v[160:163], v[68:71], v[108:111]
	v_mfma_f32_16x16x32_bf16 v[124:127], v[188:191], v[68:71], v[104:107]
	s_waitcnt lgkmcnt(5)
	v_mfma_f32_16x16x32_bf16 v[112:115], v[160:163], v[72:75], v[88:91]
	v_mfma_f32_16x16x32_bf16 v[108:111], v[188:191], v[72:75], v[84:87]
	v_mfma_f32_16x16x32_bf16 v[104:107], v[192:195], v[72:75], v[80:83]
	v_mfma_f32_16x16x32_bf16 v[100:103], v[196:199], v[72:75], v[60:63]
	s_waitcnt lgkmcnt(3)
	v_mfma_f32_16x16x32_bf16 v[72:75], v[192:195], v[200:203], v[32:35]
	s_waitcnt lgkmcnt(0)
	v_mfma_f32_16x16x32_bf16 v[32:35], v[160:163], v[204:207], v[148:151]
	v_mfma_f32_16x16x32_bf16 v[60:63], v[188:191], v[216:219], v[20:23]
	v_mfma_f32_16x16x32_bf16 v[20:23], v[196:199], v[204:207], v[144:147]
	v_mfma_f32_16x16x32_bf16 v[140:143], v[160:163], v[64:67], v[140:143]
	v_mfma_f32_16x16x32_bf16 v[136:139], v[188:191], v[64:67], v[136:139]
	v_mfma_f32_16x16x32_bf16 v[120:123], v[192:195], v[68:71], v[96:99]
	v_mfma_f32_16x16x32_bf16 v[116:119], v[196:199], v[68:71], v[92:95]
	v_mfma_f32_16x16x32_bf16 v[96:99], v[160:163], v[76:79], v[56:59]
	v_mfma_f32_16x16x32_bf16 v[92:95], v[188:191], v[76:79], v[52:55]
	v_mfma_f32_16x16x32_bf16 v[88:91], v[192:195], v[76:79], v[48:51]
	v_mfma_f32_16x16x32_bf16 v[84:87], v[196:199], v[76:79], v[44:47]
	v_mfma_f32_16x16x32_bf16 v[80:83], v[160:163], v[200:203], v[40:43]
	v_mfma_f32_16x16x32_bf16 v[76:79], v[188:191], v[200:203], v[36:39]
	v_mfma_f32_16x16x32_bf16 v[68:71], v[196:199], v[200:203], v[28:31]
	v_mfma_f32_16x16x32_bf16 v[64:67], v[160:163], v[216:219], v[24:27]
	v_mfma_f32_16x16x32_bf16 v[56:59], v[192:195], v[216:219], v[164:167]
	v_mfma_f32_16x16x32_bf16 v[52:55], v[196:199], v[216:219], v[168:171]
	v_mfma_f32_16x16x32_bf16 v[48:51], v[160:163], v[220:223], v[172:175]
	v_mfma_f32_16x16x32_bf16 v[44:47], v[188:191], v[220:223], v[176:179]
	v_mfma_f32_16x16x32_bf16 v[40:43], v[192:195], v[220:223], v[180:183]
	v_mfma_f32_16x16x32_bf16 v[36:39], v[196:199], v[220:223], v[184:187]
	v_mfma_f32_16x16x32_bf16 v[28:31], v[188:191], v[204:207], v[152:155]
	v_mfma_f32_16x16x32_bf16 v[24:27], v[192:195], v[204:207], v[156:159]
	s_nop 7
	s_nop 7
	s_nop 7
	global_store_dwordx4 v237, v[140:143], s[98:99]
	global_store_dwordx4 v237, v[136:139], s[98:99] offset:64
	global_store_dwordx4 v237, v[224:227], s[98:99] offset:256
	global_store_dwordx4 v237, v[228:231], s[98:99] offset:320
	v_add_u32_e32 v237, 0x10000, v237
	global_store_dwordx4 v237, v[128:131], s[98:99]
	global_store_dwordx4 v237, v[124:127], s[98:99] offset:64
	global_store_dwordx4 v237, v[120:123], s[98:99] offset:256
	global_store_dwordx4 v237, v[116:119], s[98:99] offset:320
	v_add_u32_e32 v237, 0x10000, v237
	global_store_dwordx4 v237, v[112:115], s[98:99]
	global_store_dwordx4 v237, v[108:111], s[98:99] offset:64
	global_store_dwordx4 v237, v[104:107], s[98:99] offset:256
	global_store_dwordx4 v237, v[100:103], s[98:99] offset:320
	v_add_u32_e32 v237, 0x10000, v237
	global_store_dwordx4 v237, v[96:99], s[98:99]
	global_store_dwordx4 v237, v[92:95], s[98:99] offset:64
	global_store_dwordx4 v237, v[88:91], s[98:99] offset:256
	global_store_dwordx4 v237, v[84:87], s[98:99] offset:320
	v_add_u32_e32 v237, 0x10000, v237
	global_store_dwordx4 v237, v[80:83], s[98:99]
	global_store_dwordx4 v237, v[76:79], s[98:99] offset:64
	global_store_dwordx4 v237, v[72:75], s[98:99] offset:256
	global_store_dwordx4 v237, v[68:71], s[98:99] offset:320
	v_add_u32_e32 v237, 0x10000, v237
	global_store_dwordx4 v237, v[64:67], s[98:99]
	global_store_dwordx4 v237, v[60:63], s[98:99] offset:64
	global_store_dwordx4 v237, v[56:59], s[98:99] offset:256
	global_store_dwordx4 v237, v[52:55], s[98:99] offset:320
	v_add_u32_e32 v237, 0x10000, v237
	global_store_dwordx4 v237, v[48:51], s[98:99]
	global_store_dwordx4 v237, v[44:47], s[98:99] offset:64
	global_store_dwordx4 v237, v[40:43], s[98:99] offset:256
	global_store_dwordx4 v237, v[36:39], s[98:99] offset:320
	v_add_u32_e32 v237, 0x10000, v237
	global_store_dwordx4 v237, v[32:35], s[98:99]
	global_store_dwordx4 v237, v[28:31], s[98:99] offset:64
	global_store_dwordx4 v237, v[24:27], s[98:99] offset:256
	global_store_dwordx4 v237, v[20:23], s[98:99] offset:320
	s_cbranch_scc0 .LBB0_818

; template <int MI, bool SWAP, bool F8 = false>
; __device__ __forceinline__ void gemm_core(const bf16_t* __restrict__ A, int lda, const bf16_t* __restrict__ B, int ldb,
;                                           int K, char* smem, f32x4 (&acc)[MI][4]) {
;     ...
;   for (int kt = 0; kt < nk; ++kt) {
;     __syncthreads();
; #pragma unroll
;     for (int i = 0; i < MI; ++i) *(u32x4*)(smem + woff + i * 4096) = ra[i];
; #pragma unroll
;     for (int i = 0; i < 4; ++i) *(u32x4*)(smem + 32768 + woff + i * 4096) = rb[i];
;     __syncthreads();
;     if (kt + 1 < nk) {
; #pragma unroll
;       for (int i = 0; i < MI; ++i) ra[i] = *(const u32x4*)(ap + (size_t)(32 * i) * lda + (kt + 1) * 64);
; #pragma unroll
;       for (int i = 0; i < 4; ++i) rb[i] = *(const u32x4*)(bp + (size_t)(32 * i) * ldb + (kt + 1) * 64);
;     }
;     if (F8) {
;       const int c0 = (g ^ (li & 7)) << 4, c1 = ((4 + g) ^ (li & 7)) << 4;
;       i32x8 wf8[4];
; #pragma unroll
;       for (int j = 0; j < 4; ++j) {
;         const char* rp = smem + wrow + ((j & 1) * 16 + (j >> 1) * 64) * 128;
;         const u32x4 lo = *(const u32x4*)(rp + c0), hi = *(const u32x4*)(rp + c1);
;         wf8[j] = (i32x8){(int)lo.x, (int)lo.y, (int)lo.z, (int)lo.w, (int)hi.x, (int)hi.y, (int)hi.z, (int)hi.w};
;       }
; #pragma unroll
;       for (int i = 0; i < MI; ++i) {
;         const char* rp = smem + xrow + i * 2048;
;         const u32x4 lo = *(const u32x4*)(rp + c0), hi = *(const u32x4*)(rp + c1);
;         const i32x8 xf8 = {(int)lo.x, (int)lo.y, (int)lo.z, (int)lo.w, (int)hi.x, (int)hi.y, (int)hi.z, (int)hi.w};
; #pragma unroll
;         for (int j = 0; j < 4; ++j)
;           acc[i][j] = __builtin_amdgcn_mfma_scale_f32_16x16x128_f8f6f4(wf8[j], xf8, acc[i][j], 0, 0, 0, 0x77777777, 0, 0x7f7f7f7f);
;       }
.LBB0_944:
	v_add_u32_e32 v222, v215, v218
	v_add_u32_e32 v223, v215, v219
	s_barrier
	s_setprio 2
	s_mov_b32 m0, s62
	s_nop 0
	global_load_lds_dwordx4 v252, s[56:57]
	s_add_u32 m0, s62, 0x1000
	s_nop 0
	global_load_lds_dwordx4 v253, s[56:57]
	s_add_u32 s56, s56, 0x10000
	s_addc_u32 s57, s57, 0
	s_add_u32 m0, s62, 0x2000
	s_nop 0
	global_load_lds_dwordx4 v252, s[56:57]
	s_add_u32 m0, s62, 0x3000
	s_nop 0
	global_load_lds_dwordx4 v253, s[56:57]
	s_add_u32 s56, s56, 0x10000
	s_addc_u32 s57, s57, 0
	s_add_u32 m0, s62, 0x4000
	s_nop 0
	global_load_lds_dwordx4 v252, s[56:57]
	s_add_u32 m0, s62, 0x5000
	s_nop 0
	global_load_lds_dwordx4 v253, s[56:57]
	s_add_u32 s56, s56, 0x10000
	s_addc_u32 s57, s57, 0
	s_add_u32 m0, s62, 0x6000
	s_nop 0
	global_load_lds_dwordx4 v252, s[56:57]
	s_add_u32 m0, s62, 0x7000
	s_nop 0
	global_load_lds_dwordx4 v253, s[56:57]
	s_sub_u32 s56, s56, 0x30000
	s_subb_u32 s57, s57, 0
	s_add_u32 m0, s62, 0x8000
	s_nop 0
	global_load_lds_dwordx4 v252, s[58:59]
	s_add_u32 m0, s62, 0x9000
	s_nop 0
	global_load_lds_dwordx4 v253, s[58:59]
	s_add_u32 s58, s58, 0x10000
	s_addc_u32 s59, s59, 0
	s_add_u32 m0, s62, 0xa000
	s_nop 0
	global_load_lds_dwordx4 v252, s[58:59]
	s_add_u32 m0, s62, 0xb000
	s_nop 0
	global_load_lds_dwordx4 v253, s[58:59]
	s_sub_u32 s58, s58, 0x10000
	s_subb_u32 s59, s59, 0
	s_setprio 0
	v_add_u32_e32 v252, 0x80, v252
	v_add_u32_e32 v253, 0x80, v253
	s_waitcnt vmcnt(0)
	s_barrier
	v_add_u32_e32 v221, v213, v218
	v_add_u32_e32 v220, v213, v219
	ds_read_b128 v[44:47], v222 offset:32768
	ds_read_b128 v[48:51], v223 offset:32768
	ds_read_b128 v[180:183], v221
	ds_read_b128 v[184:187], v220
	ds_read_b128 v[20:23], v222 offset:34816
	ds_read_b128 v[24:27], v223 offset:34816
	ds_read_b128 v[188:191], v221 offset:2048
	ds_read_b128 v[192:195], v220 offset:2048
	ds_read_b128 v[32:35], v223 offset:40960
	ds_read_b128 v[28:31], v222 offset:40960
	ds_read_b128 v[36:39], v222 offset:43008
	ds_read_b128 v[40:43], v223 offset:43008
	s_waitcnt lgkmcnt(8)
	v_mfma_scale_f32_16x16x128_f8f6f4 v[176:179], v[44:51], v[180:187], v[176:179], v239, v238 op_sel_hi:[0,0,0]
	s_waitcnt lgkmcnt(6)
	v_mfma_scale_f32_16x16x128_f8f6f4 v[172:175], v[20:27], v[180:187], v[172:175], v239, v238 op_sel_hi:[0,0,0]
	s_waitcnt lgkmcnt(2)
	v_mfma_scale_f32_16x16x128_f8f6f4 v[168:171], v[28:35], v[180:187], v[168:171], v239, v238 op_sel_hi:[0,0,0]
	s_waitcnt lgkmcnt(0)
	v_mfma_scale_f32_16x16x128_f8f6f4 v[164:167], v[36:43], v[180:187], v[164:167], v239, v238 op_sel_hi:[0,0,0]
	v_mfma_scale_f32_16x16x128_f8f6f4 v[160:163], v[44:51], v[188:195], v[160:163], v239, v238 op_sel_hi:[0,0,0]
	v_mfma_scale_f32_16x16x128_f8f6f4 v[156:159], v[20:27], v[188:195], v[156:159], v239, v238 op_sel_hi:[0,0,0]
	v_mfma_scale_f32_16x16x128_f8f6f4 v[152:155], v[28:35], v[188:195], v[152:155], v239, v238 op_sel_hi:[0,0,0]
	v_mfma_scale_f32_16x16x128_f8f6f4 v[148:151], v[36:43], v[188:195], v[148:151], v239, v238 op_sel_hi:[0,0,0]
	ds_read_b128 v[184:187], v220 offset:4096
	ds_read_b128 v[180:183], v221 offset:4096
	ds_read_b128 v[188:191], v221 offset:6144
	ds_read_b128 v[192:195], v220 offset:6144
	s_waitcnt lgkmcnt(2)
	v_mfma_scale_f32_16x16x128_f8f6f4 v[144:147], v[44:51], v[180:187], v[144:147], v239, v238 op_sel_hi:[0,0,0]
	v_mfma_scale_f32_16x16x128_f8f6f4 v[140:143], v[20:27], v[180:187], v[140:143], v239, v238 op_sel_hi:[0,0,0]
	v_mfma_scale_f32_16x16x128_f8f6f4 v[136:139], v[28:35], v[180:187], v[136:139], v239, v238 op_sel_hi:[0,0,0]
	v_mfma_scale_f32_16x16x128_f8f6f4 v[132:135], v[36:43], v[180:187], v[132:135], v239, v238 op_sel_hi:[0,0,0]
	s_waitcnt lgkmcnt(0)
	v_mfma_scale_f32_16x16x128_f8f6f4 v[128:131], v[44:51], v[188:195], v[128:131], v239, v238 op_sel_hi:[0,0,0]
	v_mfma_scale_f32_16x16x128_f8f6f4 v[124:127], v[20:27], v[188:195], v[124:127], v239, v238 op_sel_hi:[0,0,0]
	v_mfma_scale_f32_16x16x128_f8f6f4 v[120:123], v[28:35], v[188:195], v[120:123], v239, v238 op_sel_hi:[0,0,0]
	v_mfma_scale_f32_16x16x128_f8f6f4 v[116:119], v[36:43], v[188:195], v[116:119], v239, v238 op_sel_hi:[0,0,0]
	ds_read_b128 v[184:187], v220 offset:8192
	ds_read_b128 v[180:183], v221 offset:8192
	ds_read_b128 v[188:191], v221 offset:10240
	ds_read_b128 v[192:195], v220 offset:10240
	s_waitcnt lgkmcnt(0)
	v_mfma_scale_f32_16x16x128_f8f6f4 v[96:99], v[44:51], v[188:195], v[96:99], v239, v238 op_sel_hi:[0,0,0]
	v_mfma_scale_f32_16x16x128_f8f6f4 v[92:95], v[20:27], v[188:195], v[92:95], v239, v238 op_sel_hi:[0,0,0]
	v_mfma_scale_f32_16x16x128_f8f6f4 v[88:91], v[28:35], v[188:195], v[88:91], v239, v238 op_sel_hi:[0,0,0]
	v_mfma_scale_f32_16x16x128_f8f6f4 v[84:87], v[36:43], v[188:195], v[84:87], v239, v238 op_sel_hi:[0,0,0]
	v_mfma_scale_f32_16x16x128_f8f6f4 v[112:115], v[44:51], v[180:187], v[112:115], v239, v238 op_sel_hi:[0,0,0]
	v_mfma_scale_f32_16x16x128_f8f6f4 v[108:111], v[20:27], v[180:187], v[108:111], v239, v238 op_sel_hi:[0,0,0]
	v_mfma_scale_f32_16x16x128_f8f6f4 v[104:107], v[28:35], v[180:187], v[104:107], v239, v238 op_sel_hi:[0,0,0]
	v_mfma_scale_f32_16x16x128_f8f6f4 v[100:103], v[36:43], v[180:187], v[100:103], v239, v238 op_sel_hi:[0,0,0]
	ds_read_b128 v[180:183], v221 offset:12288
	ds_read_b128 v[184:187], v220 offset:12288
	ds_read_b128 v[224:227], v221 offset:14336
	ds_read_b128 v[228:231], v220 offset:14336
	s_waitcnt lgkmcnt(2)
	v_mfma_scale_f32_16x16x128_f8f6f4 v[80:83], v[44:51], v[180:187], v[80:83], v239, v238 op_sel_hi:[0,0,0]
	v_mfma_scale_f32_16x16x128_f8f6f4 v[76:79], v[20:27], v[180:187], v[76:79], v239, v238 op_sel_hi:[0,0,0]
	v_mfma_scale_f32_16x16x128_f8f6f4 v[72:75], v[28:35], v[180:187], v[72:75], v239, v238 op_sel_hi:[0,0,0]
	v_mfma_scale_f32_16x16x128_f8f6f4 v[68:71], v[36:43], v[180:187], v[68:71], v239, v238 op_sel_hi:[0,0,0]
	s_waitcnt lgkmcnt(0)
	v_mfma_scale_f32_16x16x128_f8f6f4 v[64:67], v[44:51], v[224:231], v[64:67], v239, v238 op_sel_hi:[0,0,0]
	v_mfma_scale_f32_16x16x128_f8f6f4 v[60:63], v[20:27], v[224:231], v[60:63], v239, v238 op_sel_hi:[0,0,0]
	v_mfma_scale_f32_16x16x128_f8f6f4 v[56:59], v[28:35], v[224:231], v[56:59], v239, v238 op_sel_hi:[0,0,0]
	v_mfma_scale_f32_16x16x128_f8f6f4 v[52:55], v[36:43], v[224:231], v[52:55], v239, v238 op_sel_hi:[0,0,0]
	s_add_u32 s8, s8, 0x80
	s_addc_u32 s9, s9, 0
	s_cmpk_lg_i32 s8, 0x380
	s_cbranch_scc1 .LBB0_944
; template <int MI, bool SWAP, bool F8 = false>
; __device__ __forceinline__ void gemm_core(const bf16_t* __restrict__ A, int lda, const bf16_t* __restrict__ B, int ldb,
;                                           int K, char* smem, f32x4 (&acc)[MI][4]) {
;     ...
;   for (int kt = 0; kt < nk; ++kt) {
;     __syncthreads();
; #pragma unroll
;     for (int i = 0; i < MI; ++i) *(u32x4*)(smem + woff + i * 4096) = ra[i];
; #pragma unroll
;     for (int i = 0; i < 4; ++i) *(u32x4*)(smem + 32768 + woff + i * 4096) = rb[i];
;     __syncthreads();
;     if (kt + 1 < nk) {
; #pragma unroll
;       for (int i = 0; i < MI; ++i) ra[i] = *(const u32x4*)(ap + (size_t)(32 * i) * lda + (kt + 1) * 64);
; #pragma unroll
;       for (int i = 0; i < 4; ++i) rb[i] = *(const u32x4*)(bp + (size_t)(32 * i) * ldb + (kt + 1) * 64);
;     }
;     if (F8) {
;       const int c0 = (g ^ (li & 7)) << 4, c1 = ((4 + g) ^ (li & 7)) << 4;
;       i32x8 wf8[4];
; #pragma unroll
;       for (int j = 0; j < 4; ++j) {
;         const char* rp = smem + wrow + ((j & 1) * 16 + (j >> 1) * 64) * 128;
;         const u32x4 lo = *(const u32x4*)(rp + c0), hi = *(const u32x4*)(rp + c1);
;         wf8[j] = (i32x8){(int)lo.x, (int)lo.y, (int)lo.z, (int)lo.w, (int)hi.x, (int)hi.y, (int)hi.z, (int)hi.w};
;       }
; #pragma unroll
;       for (int i = 0; i < MI; ++i) {
;         const char* rp = smem + xrow + i * 2048;
;         const u32x4 lo = *(const u32x4*)(rp + c0), hi = *(const u32x4*)(rp + c1);
;         const i32x8 xf8 = {(int)lo.x, (int)lo.y, (int)lo.z, (int)lo.w, (int)hi.x, (int)hi.y, (int)hi.z, (int)hi.w};
; #pragma unroll
;         for (int j = 0; j < 4; ++j)
;           acc[i][j] = __builtin_amdgcn_mfma_scale_f32_16x16x128_f8f6f4(wf8[j], xf8, acc[i][j], 0, 0, 0, 0x77777777, 0, 0x7f7f7f7f);
;       }
	s_barrier
	s_setprio 2
	s_mov_b32 m0, s62
	s_nop 0
	global_load_lds_dwordx4 v252, s[56:57]
	s_add_u32 m0, s62, 0x1000
	s_nop 0
	global_load_lds_dwordx4 v253, s[56:57]
	s_add_u32 s56, s56, 0x10000
	s_addc_u32 s57, s57, 0
	s_add_u32 m0, s62, 0x2000
	s_nop 0
	global_load_lds_dwordx4 v252, s[56:57]
	s_add_u32 m0, s62, 0x3000
	s_nop 0
	global_load_lds_dwordx4 v253, s[56:57]
	s_add_u32 s56, s56, 0x10000
	s_addc_u32 s57, s57, 0
	s_add_u32 m0, s62, 0x4000
	s_nop 0
	global_load_lds_dwordx4 v252, s[56:57]
	s_add_u32 m0, s62, 0x5000
	s_nop 0
	global_load_lds_dwordx4 v253, s[56:57]
	s_add_u32 s56, s56, 0x10000
	s_addc_u32 s57, s57, 0
	s_add_u32 m0, s62, 0x6000
	s_nop 0
	global_load_lds_dwordx4 v252, s[56:57]
	s_add_u32 m0, s62, 0x7000
	s_nop 0
	global_load_lds_dwordx4 v253, s[56:57]
	s_sub_u32 s56, s56, 0x30000
	s_subb_u32 s57, s57, 0
	s_add_u32 m0, s62, 0x8000
	s_nop 0
	global_load_lds_dwordx4 v252, s[58:59]
	s_add_u32 m0, s62, 0x9000
	s_nop 0
	global_load_lds_dwordx4 v253, s[58:59]
	s_add_u32 s58, s58, 0x10000
	s_addc_u32 s59, s59, 0
	s_add_u32 m0, s62, 0xa000
	s_nop 0
	global_load_lds_dwordx4 v252, s[58:59]
	s_add_u32 m0, s62, 0xb000
	s_nop 0
	global_load_lds_dwordx4 v253, s[58:59]
	s_sub_u32 s58, s58, 0x10000
	s_subb_u32 s59, s59, 0
	s_setprio 0
	s_waitcnt vmcnt(0)
	s_barrier
	v_bfe_u32 v12, v208, 4, 1
	v_mul_u32_u24_e32 v12, 24, v12
	v_mov_b32_e32 v13, 0
	ds_read_b128 v[20:23], v222 offset:32768
	ds_read_b128 v[24:27], v223 offset:32768
	ds_read_b128 v[28:31], v222 offset:34816
	ds_read_b128 v[32:35], v223 offset:34816
	ds_read_b128 v[36:39], v222 offset:40960
	ds_read_b128 v[40:43], v223 offset:40960
	ds_read_b128 v[44:47], v222 offset:43008
	ds_read_b128 v[48:51], v223 offset:43008
	ds_read_b128 v[180:183], v221
	ds_read_b128 v[184:187], v220
	s_waitcnt lgkmcnt(0)
	v_mfma_scale_f32_16x16x128_f8f6f4 v[176:179], v[20:27], v[180:187], v[176:179], v239, v238 op_sel_hi:[0,0,0]
	s_lshl_b64 s[6:7], s[6:7], 20
	s_add_u32 s6, s42, s6
	s_addc_u32 s7, s43, s7
	s_lshl_b32 s8, s19, 1
	s_add_u32 s6, s6, s8
	s_addc_u32 s7, s7, 0
	s_add_i32 s18, s18, s78
	v_mfma_scale_f32_16x16x128_f8f6f4 v[172:175], v[28:35], v[180:187], v[172:175], v239, v238 op_sel_hi:[0,0,0]
	s_add_i32 s15, s15, s71
	s_add_i32 s14, s14, s76
	s_cmpk_gt_i32 s18, 0x3ff
	v_mfma_scale_f32_16x16x128_f8f6f4 v[168:171], v[36:43], v[180:187], v[168:171], v239, v238 op_sel_hi:[0,0,0]
	v_mfma_scale_f32_16x16x128_f8f6f4 v[164:167], v[44:51], v[180:187], v[164:167], v239, v238 op_sel_hi:[0,0,0]
	ds_read_b128 v[180:183], v221 offset:2048
	ds_read_b128 v[184:187], v220 offset:2048
	s_waitcnt lgkmcnt(0)
	v_mfma_scale_f32_16x16x128_f8f6f4 v[160:163], v[20:27], v[180:187], v[160:163], v239, v238 op_sel_hi:[0,0,0]
	v_mfma_scale_f32_16x16x128_f8f6f4 v[156:159], v[28:35], v[180:187], v[156:159], v239, v238 op_sel_hi:[0,0,0]
	v_mfma_scale_f32_16x16x128_f8f6f4 v[152:155], v[36:43], v[180:187], v[152:155], v239, v238 op_sel_hi:[0,0,0]
	v_mfma_scale_f32_16x16x128_f8f6f4 v[148:151], v[44:51], v[180:187], v[148:151], v239, v238 op_sel_hi:[0,0,0]
	ds_read_b128 v[180:183], v221 offset:4096
	ds_read_b128 v[184:187], v220 offset:4096
	s_waitcnt lgkmcnt(0)
	v_mfma_scale_f32_16x16x128_f8f6f4 v[144:147], v[20:27], v[180:187], v[144:147], v239, v238 op_sel_hi:[0,0,0]
	v_mfma_scale_f32_16x16x128_f8f6f4 v[140:143], v[28:35], v[180:187], v[140:143], v239, v238 op_sel_hi:[0,0,0]
	v_mfma_scale_f32_16x16x128_f8f6f4 v[136:139], v[36:43], v[180:187], v[136:139], v239, v238 op_sel_hi:[0,0,0]
	v_mfma_scale_f32_16x16x128_f8f6f4 v[132:135], v[44:51], v[180:187], v[132:135], v239, v238 op_sel_hi:[0,0,0]
	ds_read_b128 v[180:183], v221 offset:6144
	ds_read_b128 v[184:187], v220 offset:6144
	s_waitcnt lgkmcnt(0)
	v_mfma_scale_f32_16x16x128_f8f6f4 v[128:131], v[20:27], v[180:187], v[128:131], v239, v238 op_sel_hi:[0,0,0]
	v_mfma_scale_f32_16x16x128_f8f6f4 v[124:127], v[28:35], v[180:187], v[124:127], v239, v238 op_sel_hi:[0,0,0]
	v_mfma_scale_f32_16x16x128_f8f6f4 v[120:123], v[36:43], v[180:187], v[120:123], v239, v238 op_sel_hi:[0,0,0]
	v_mfma_scale_f32_16x16x128_f8f6f4 v[116:119], v[44:51], v[180:187], v[116:119], v239, v238 op_sel_hi:[0,0,0]
	ds_read_b128 v[180:183], v221 offset:8192
	ds_read_b128 v[184:187], v220 offset:8192
	s_waitcnt lgkmcnt(0)
	v_mfma_scale_f32_16x16x128_f8f6f4 v[112:115], v[20:27], v[180:187], v[112:115], v239, v238 op_sel_hi:[0,0,0]
	v_mfma_scale_f32_16x16x128_f8f6f4 v[108:111], v[28:35], v[180:187], v[108:111], v239, v238 op_sel_hi:[0,0,0]
	v_mfma_scale_f32_16x16x128_f8f6f4 v[104:107], v[36:43], v[180:187], v[104:107], v239, v238 op_sel_hi:[0,0,0]
	v_mfma_scale_f32_16x16x128_f8f6f4 v[100:103], v[44:51], v[180:187], v[100:103], v239, v238 op_sel_hi:[0,0,0]
	ds_read_b128 v[180:183], v221 offset:10240
	ds_read_b128 v[184:187], v220 offset:10240
	s_waitcnt lgkmcnt(0)
	v_mfma_scale_f32_16x16x128_f8f6f4 v[96:99], v[20:27], v[180:187], v[96:99], v239, v238 op_sel_hi:[0,0,0]
	v_mfma_scale_f32_16x16x128_f8f6f4 v[92:95], v[28:35], v[180:187], v[92:95], v239, v238 op_sel_hi:[0,0,0]
	v_mfma_scale_f32_16x16x128_f8f6f4 v[88:91], v[36:43], v[180:187], v[88:91], v239, v238 op_sel_hi:[0,0,0]
	v_mfma_scale_f32_16x16x128_f8f6f4 v[84:87], v[44:51], v[180:187], v[84:87], v239, v238 op_sel_hi:[0,0,0]
	ds_read_b128 v[180:183], v221 offset:12288
	ds_read_b128 v[184:187], v220 offset:12288
	s_waitcnt lgkmcnt(0)
	v_mfma_scale_f32_16x16x128_f8f6f4 v[80:83], v[20:27], v[180:187], v[80:83], v239, v238 op_sel_hi:[0,0,0]
	v_mfma_scale_f32_16x16x128_f8f6f4 v[76:79], v[28:35], v[180:187], v[76:79], v239, v238 op_sel_hi:[0,0,0]
	v_mfma_scale_f32_16x16x128_f8f6f4 v[72:75], v[36:43], v[180:187], v[72:75], v239, v238 op_sel_hi:[0,0,0]
	v_mfma_scale_f32_16x16x128_f8f6f4 v[68:71], v[44:51], v[180:187], v[68:71], v239, v238 op_sel_hi:[0,0,0]
	ds_read_b128 v[180:183], v221 offset:14336
	ds_read_b128 v[184:187], v220 offset:14336
	s_waitcnt lgkmcnt(0)
; template <int MI, bool F8 = false>
; __device__ void gemm_tile_bf16(const bf16_t* A, int lda, const bf16_t* B, int ldb, int K, bf16_t* C, int ldc, char* smem) {
;     ...
; #pragma unroll
;   for (int i = 0; i < MI; ++i)
; #pragma unroll
;     for (int j = 0; j < 4; ++j) {
;       u32x2 v;
;       v.x = pk_bf16(acc[i][j][0], acc[i][j][1]);
;       v.y = pk_bf16(acc[i][j][2], acc[i][j][3]);
;       *(u32x2*)(C + (size_t)MROW(i) * ldc + NCOL(j)) = v;
;     }
	v_mfma_scale_f32_16x16x128_f8f6f4 v[64:67], v[20:27], v[180:187], v[64:67], v239, v238 op_sel_hi:[0,0,0]
	v_mfma_scale_f32_16x16x128_f8f6f4 v[24:27], v[36:43], v[180:187], v[56:59], v239, v238 op_sel_hi:[0,0,0]
	v_mov_b32_e32 v36, v208
	s_nop 0
	v_lshrrev_b32_e32 v0, 1, v36
	v_and_b32_e32 v2, 0xffffff8f, v36
	v_and_b32_e32 v0, 32, v0
	v_lshrrev_b32_e32 v3, 2, v36
	v_and_or_b32 v0, v3, 12, v0
	v_ashrrev_i32_e32 v3, 31, v2
	v_mfma_scale_f32_16x16x128_f8f6f4 v[28:31], v[28:35], v[180:187], v[60:63], v239, v238 op_sel_hi:[0,0,0]
	v_lshlrev_b64 v[32:33], 12, v[2:3]
	v_lshl_add_u64 v[32:33], s[6:7], 0, v[32:33]
	v_lshlrev_b32_e32 v0, 1, v0
	v_cvt_pk_bf16_f32 v4, v176, v177
	v_cvt_pk_bf16_f32 v5, v178, v179
	v_lshl_add_u64 v[32:33], v[32:33], 0, v[0:1]
	v_cvt_pk_bf16_f32 v6, v172, v173
	v_cvt_pk_bf16_f32 v7, v174, v175
	s_nop 1
	v_permlane16_swap_b32_e32 v4, v6
	v_permlane16_swap_b32_e32 v5, v7
	v_lshl_add_u64 v[14:15], v[32:33], 0, v[12:13]
	global_store_dwordx4 v[14:15], v[4:7], off
	v_cvt_pk_bf16_f32 v8, v168, v169
	v_cvt_pk_bf16_f32 v9, v170, v171
	v_cvt_pk_bf16_f32 v10, v164, v165
	v_cvt_pk_bf16_f32 v11, v166, v167
	s_nop 1
	v_permlane16_swap_b32_e32 v8, v10
	v_permlane16_swap_b32_e32 v9, v11
	v_lshl_add_u64 v[14:15], v[32:33], 0, v[12:13]
	global_store_dwordx4 v[14:15], v[8:11], off offset:128
	v_or_b32_e32 v32, 16, v2
	v_ashrrev_i32_e32 v33, 31, v32
	v_lshlrev_b64 v[32:33], 12, v[32:33]
	v_lshl_add_u64 v[32:33], s[6:7], 0, v[32:33]
	v_cvt_pk_bf16_f32 v4, v160, v161
	v_cvt_pk_bf16_f32 v5, v162, v163
	v_lshl_add_u64 v[32:33], v[32:33], 0, v[0:1]
	v_cvt_pk_bf16_f32 v6, v156, v157
	v_cvt_pk_bf16_f32 v7, v158, v159
	s_nop 1
	v_permlane16_swap_b32_e32 v4, v6
	v_permlane16_swap_b32_e32 v5, v7
	v_lshl_add_u64 v[14:15], v[32:33], 0, v[12:13]
	global_store_dwordx4 v[14:15], v[4:7], off
	v_cvt_pk_bf16_f32 v8, v152, v153
	v_cvt_pk_bf16_f32 v9, v154, v155
	v_cvt_pk_bf16_f32 v10, v148, v149
	v_cvt_pk_bf16_f32 v11, v150, v151
	s_nop 1
	v_permlane16_swap_b32_e32 v8, v10
	v_permlane16_swap_b32_e32 v9, v11
	v_lshl_add_u64 v[14:15], v[32:33], 0, v[12:13]
	global_store_dwordx4 v[14:15], v[8:11], off offset:128
	v_or_b32_e32 v32, 32, v2
	v_ashrrev_i32_e32 v33, 31, v32
	v_lshlrev_b64 v[32:33], 12, v[32:33]
	v_lshl_add_u64 v[32:33], s[6:7], 0, v[32:33]
	v_cvt_pk_bf16_f32 v4, v144, v145
	v_cvt_pk_bf16_f32 v5, v146, v147
	v_lshl_add_u64 v[32:33], v[32:33], 0, v[0:1]
	v_cvt_pk_bf16_f32 v6, v140, v141
	v_cvt_pk_bf16_f32 v7, v142, v143
	s_nop 1
	v_permlane16_swap_b32_e32 v4, v6
	v_permlane16_swap_b32_e32 v5, v7
	v_lshl_add_u64 v[14:15], v[32:33], 0, v[12:13]
	global_store_dwordx4 v[14:15], v[4:7], off
	v_cvt_pk_bf16_f32 v8, v136, v137
	v_cvt_pk_bf16_f32 v9, v138, v139
	v_cvt_pk_bf16_f32 v10, v132, v133
	v_cvt_pk_bf16_f32 v11, v134, v135
	s_nop 1
	v_permlane16_swap_b32_e32 v8, v10
	v_permlane16_swap_b32_e32 v9, v11
	v_lshl_add_u64 v[14:15], v[32:33], 0, v[12:13]
	global_store_dwordx4 v[14:15], v[8:11], off offset:128
	v_or_b32_e32 v32, 48, v2
	v_ashrrev_i32_e32 v33, 31, v32
	v_lshlrev_b64 v[32:33], 12, v[32:33]
	v_lshl_add_u64 v[32:33], s[6:7], 0, v[32:33]
	v_cvt_pk_bf16_f32 v4, v128, v129
	v_cvt_pk_bf16_f32 v5, v130, v131
	v_lshl_add_u64 v[32:33], v[32:33], 0, v[0:1]
	v_cvt_pk_bf16_f32 v6, v124, v125
	v_cvt_pk_bf16_f32 v7, v126, v127
	s_nop 1
	v_permlane16_swap_b32_e32 v4, v6
	v_permlane16_swap_b32_e32 v5, v7
	v_lshl_add_u64 v[14:15], v[32:33], 0, v[12:13]
	global_store_dwordx4 v[14:15], v[4:7], off
	v_cvt_pk_bf16_f32 v8, v120, v121
	v_cvt_pk_bf16_f32 v9, v122, v123
	v_cvt_pk_bf16_f32 v10, v116, v117
	v_cvt_pk_bf16_f32 v11, v118, v119
	s_nop 1
	v_permlane16_swap_b32_e32 v8, v10
; template <int MI, bool F8 = false>
; __device__ void gemm_tile_bf16(const bf16_t* A, int lda, const bf16_t* B, int ldb, int K, bf16_t* C, int ldc, char* smem) {
;     ...
; #pragma unroll
;   for (int i = 0; i < MI; ++i)
; #pragma unroll
;     for (int j = 0; j < 4; ++j) {
;       u32x2 v;
;       v.x = pk_bf16(acc[i][j][0], acc[i][j][1]);
;       v.y = pk_bf16(acc[i][j][2], acc[i][j][3]);
;       *(u32x2*)(C + (size_t)MROW(i) * ldc + NCOL(j)) = v;
;     }
	v_permlane16_swap_b32_e32 v9, v11
	v_lshl_add_u64 v[14:15], v[32:33], 0, v[12:13]
	global_store_dwordx4 v[14:15], v[8:11], off offset:128
	v_or_b32_e32 v32, 64, v2
	v_ashrrev_i32_e32 v33, 31, v32
	v_lshlrev_b64 v[32:33], 12, v[32:33]
	v_lshl_add_u64 v[32:33], s[6:7], 0, v[32:33]
	v_cvt_pk_bf16_f32 v4, v112, v113
	v_cvt_pk_bf16_f32 v5, v114, v115
	v_lshl_add_u64 v[32:33], v[32:33], 0, v[0:1]
	v_cvt_pk_bf16_f32 v6, v108, v109
	v_cvt_pk_bf16_f32 v7, v110, v111
	s_nop 1
	v_permlane16_swap_b32_e32 v4, v6
	v_permlane16_swap_b32_e32 v5, v7
	v_lshl_add_u64 v[14:15], v[32:33], 0, v[12:13]
	global_store_dwordx4 v[14:15], v[4:7], off
	v_cvt_pk_bf16_f32 v8, v104, v105
	v_cvt_pk_bf16_f32 v9, v106, v107
	v_cvt_pk_bf16_f32 v10, v100, v101
	v_cvt_pk_bf16_f32 v11, v102, v103
	s_nop 1
	v_permlane16_swap_b32_e32 v8, v10
	v_permlane16_swap_b32_e32 v9, v11
	v_lshl_add_u64 v[14:15], v[32:33], 0, v[12:13]
	global_store_dwordx4 v[14:15], v[8:11], off offset:128
	v_or_b32_e32 v32, 0x50, v2
	v_ashrrev_i32_e32 v33, 31, v32
	v_lshlrev_b64 v[32:33], 12, v[32:33]
	v_lshl_add_u64 v[32:33], s[6:7], 0, v[32:33]
	v_cvt_pk_bf16_f32 v4, v96, v97
	v_cvt_pk_bf16_f32 v5, v98, v99
	v_lshl_add_u64 v[32:33], v[32:33], 0, v[0:1]
	v_or_b32_e32 v2, 0x60, v2
	v_cvt_pk_bf16_f32 v6, v92, v93
	v_cvt_pk_bf16_f32 v7, v94, v95
	v_ashrrev_i32_e32 v3, 31, v2
	s_nop 1
	v_permlane16_swap_b32_e32 v4, v6
	v_permlane16_swap_b32_e32 v5, v7
	v_lshl_add_u64 v[14:15], v[32:33], 0, v[12:13]
	global_store_dwordx4 v[14:15], v[4:7], off
	v_cvt_pk_bf16_f32 v8, v88, v89
	v_cvt_pk_bf16_f32 v9, v90, v91
	v_lshlrev_b64 v[2:3], 12, v[2:3]
	v_cvt_pk_bf16_f32 v10, v84, v85
	v_cvt_pk_bf16_f32 v11, v86, v87
	v_lshl_add_u64 v[2:3], s[6:7], 0, v[2:3]
	v_mfma_scale_f32_16x16x128_f8f6f4 v[20:23], v[44:51], v[180:187], v[52:55], v239, v238 op_sel_hi:[0,0,0]
	s_nop 1
	v_permlane16_swap_b32_e32 v8, v10
	v_permlane16_swap_b32_e32 v9, v11
	v_lshl_add_u64 v[14:15], v[32:33], 0, v[12:13]
	global_store_dwordx4 v[14:15], v[8:11], off offset:128
	v_cvt_pk_bf16_f32 v4, v80, v81
	v_cvt_pk_bf16_f32 v5, v82, v83
	v_lshl_add_u64 v[2:3], v[2:3], 0, v[0:1]
	v_cvt_pk_bf16_f32 v6, v76, v77
	v_cvt_pk_bf16_f32 v7, v78, v79
	s_nop 1
	v_permlane16_swap_b32_e32 v4, v6
	v_permlane16_swap_b32_e32 v5, v7
	v_lshl_add_u64 v[14:15], v[2:3], 0, v[12:13]
	global_store_dwordx4 v[14:15], v[4:7], off
	v_cvt_pk_bf16_f32 v8, v72, v73
	v_cvt_pk_bf16_f32 v9, v74, v75
	v_cvt_pk_bf16_f32 v10, v68, v69
	v_cvt_pk_bf16_f32 v11, v70, v71
	s_nop 1
	v_permlane16_swap_b32_e32 v8, v10
	v_permlane16_swap_b32_e32 v9, v11
	v_lshl_add_u64 v[14:15], v[2:3], 0, v[12:13]
	global_store_dwordx4 v[14:15], v[8:11], off offset:128
	v_or_b32_e32 v2, 0x70, v36
	v_ashrrev_i32_e32 v3, 31, v2
	v_lshlrev_b64 v[2:3], 12, v[2:3]
	v_lshl_add_u64 v[2:3], s[6:7], 0, v[2:3]
	v_cvt_pk_bf16_f32 v32, v64, v65
	v_cvt_pk_bf16_f32 v33, v66, v67
	v_lshl_add_u64 v[2:3], v[2:3], 0, v[0:1]
	v_cvt_pk_bf16_f32 v28, v28, v29
	v_cvt_pk_bf16_f32 v29, v30, v31
	v_cvt_pk_bf16_f32 v24, v24, v25
	v_cvt_pk_bf16_f32 v25, v26, v27
	v_cvt_pk_bf16_f32 v20, v20, v21
	v_cvt_pk_bf16_f32 v21, v22, v23
	v_mov_b64_e32 v[4:5], v[32:33]
	v_mov_b64_e32 v[6:7], v[28:29]
	s_nop 1
	v_permlane16_swap_b32_e32 v4, v6
	v_permlane16_swap_b32_e32 v5, v7
	v_lshl_add_u64 v[14:15], v[2:3], 0, v[12:13]
	global_store_dwordx4 v[14:15], v[4:7], off
	v_mov_b64_e32 v[8:9], v[24:25]
	v_mov_b64_e32 v[10:11], v[20:21]
	s_nop 1
	v_permlane16_swap_b32_e32 v8, v10
	v_permlane16_swap_b32_e32 v9, v11
	v_lshl_add_u64 v[14:15], v[2:3], 0, v[12:13]
	global_store_dwordx4 v[14:15], v[8:11], off offset:128
	s_cbranch_scc0 .LBB0_943
